# M-phase: branch GEMM and gate GEMM chained as one 24-tile DMA stream over the 3-stage LDS ring (no prologue stall between them)
# speedup vs baseline: 1.0210x; 1.0001x over previous
; DI f32x16 mfma(bf16x8 a, bf16x8 b, f32x16 c) { return __builtin_amdgcn_mfma_f32_32x32x16_bf16(a, b, c, 0, 0, 0); }
;     ...
;   __syncthreads();
;   DMA_ISSUE(0, 0)
;   asm volatile("s_waitcnt vmcnt(0)" ::: "memory");
;   __builtin_amdgcn_s_barrier();
;   for (int kt = 0; kt < nk; ++kt) {
;     const char* cur = lds + (kt & 1) * DBUF;
;     if (kt + 1 < nk) DMA_ISSUE((kt + 1) & 1, kt + 1)
; #pragma unroll(NTB == 1 ? 2 : 4)
;     for (int s = 0; s < 4; ++s) {
;       const int ro = ((2 * s + hh) ^ xr) * 16;
;       bf16x8 bfr[NTB];
; #pragma unroll
;       for (int tb = 0; tb < NTB; ++tb) bfr[tb] = *(const bf16x8*)(cur + bbase + tb * 32 * DROW + ro);
; #pragma unroll
;       for (int fb = 0; fb < NFB; ++fb) {
;         const bf16x8 afr = *(const bf16x8*)(cur + abase + fb * 32 * DROW + ro);
; #pragma unroll
;         for (int tb = 0; tb < NTB; ++tb) acc[tb * NFB + fb] = mfma(afr, bfr[tb], acc[tb * NFB + fb]);
;       }
;     }
;     asm volatile("s_waitcnt vmcnt(0) lgkmcnt(0)" ::: "memory");
;     __builtin_amdgcn_s_barrier();
; __global__ void __launch_bounds__(512) mega(Params p) {
;     ...
;         for (int n = 0; n < 3; ++n) {
;           f32x16 acc[4]; zero4(acc);
;           const size_t ooff = (n == 0) ? R_OA : (n == 1 ? R_OB : R_OC);
;           gemm_main<4, 1>((const u16*)(ws + OFF_WBR) + ((size_t)n * 1024 + ft * 256) * 512, 512, (const u16*)(ws + ooff) + (size_t)tt * 128 * 512, 512, 8, acc, lds);
.LBB0_25:
	s_cmp_eq_u32 s8, 1
	s_mov_b32 s0, 0x19db1000
	s_cselect_b32 s33, s0, 0x1bdb1000
	s_cmp_eq_u32 s8, 0
	s_cselect_b64 s[0:1], -1, 0
	s_and_b64 s[34:35], s[0:1], exec
	s_cselect_b32 s33, 0x6db1000, s33
	s_lshl_b32 s34, s8, 10
	s_add_u32 s34, s34, s54
	s_addc_u32 s35, 0, s55
	s_lshl_b64 s[66:67], s[34:35], 10
	v_mov_b32_e32 v8, v145
	s_add_u32 s66, s36, s66
	s_addc_u32 s67, s37, s67
	v_ashrrev_i32_e32 v2, 3, v8
	v_lshrrev_b32_e32 v0, 4, v8
	v_xor_b32_e32 v0, v0, v8
	v_ashrrev_i32_e32 v3, 31, v2
	s_add_u32 s68, s9, s33
	v_lshlrev_b64 v[4:5], 10, v[2:3]
	v_lshlrev_b32_e32 v0, 4, v0
	v_lshl_add_u32 v15, v8, 4, 0
	s_addc_u32 s69, s59, 0
	v_lshl_add_u64 v[2:3], s[66:67], 0, v[4:5]
	v_and_b32_e32 v0, 0x70, v0
	v_readfirstlane_b32 s33, v15
	v_add_u32_e32 v16, 0x2000, v15
	v_lshl_add_u64 v[2:3], v[2:3], 0, v[0:1]
	v_lshl_add_u64 v[4:5], s[68:69], 0, v[4:5]
	s_waitcnt vmcnt(0) lgkmcnt(0)
	s_barrier
	v_lshl_add_u64 v[4:5], v[4:5], 0, v[0:1]
	s_mov_b64 s[68:69], 0x10000
	v_lshl_add_u64 v[6:7], v[2:3], 0, s[68:69]
	v_lshl_add_u64 v[12:13], v[4:5], 0, s[68:69]
	v_lshl_add_u64 v[8:9], v[6:7], 0, s[68:69]
	v_lshl_add_u64 v[10:11], v[8:9], 0, s[68:69]
	s_add_u32 m0, s33, 0x0
	s_nop 0
	global_load_lds_dwordx4 v[2:3], off
	s_add_u32 m0, s33, 0x2000
	s_nop 0
	global_load_lds_dwordx4 v[6:7], off
	s_add_u32 m0, s33, 0x4000
	s_nop 0
	global_load_lds_dwordx4 v[8:9], off
	s_add_u32 m0, s33, 0x6000
	s_nop 0
	global_load_lds_dwordx4 v[10:11], off
	s_add_u32 m0, s33, 0x8000
	s_nop 0
	global_load_lds_dwordx4 v[4:5], off
	s_add_u32 m0, s33, 0xa000
	s_nop 0
	global_load_lds_dwordx4 v[12:13], off
	s_add_u32 m0, s33, 0xc000
	v_lshl_add_u64 v[2:3], v[2:3], 0, s[84:85]
	global_load_lds_dwordx4 v[2:3], off
	s_add_u32 m0, s33, 0xe000
	v_lshl_add_u64 v[6:7], v[6:7], 0, s[84:85]
	global_load_lds_dwordx4 v[6:7], off
	s_add_u32 m0, s33, 0x10000
	v_lshl_add_u64 v[8:9], v[8:9], 0, s[84:85]
	global_load_lds_dwordx4 v[8:9], off
	s_add_u32 m0, s33, 0x12000
	v_lshl_add_u64 v[10:11], v[10:11], 0, s[84:85]
	global_load_lds_dwordx4 v[10:11], off
	s_add_u32 m0, s33, 0x14000
	v_lshl_add_u64 v[4:5], v[4:5], 0, s[84:85]
	global_load_lds_dwordx4 v[4:5], off
	s_add_u32 m0, s33, 0x16000
	v_lshl_add_u64 v[12:13], v[12:13], 0, s[84:85]
	global_load_lds_dwordx4 v[12:13], off
	v_and_b32_e32 v238, 31, v145
	v_lshrrev_b32_e32 v239, 8, v145
	v_bfe_u32 v240, v145, 6, 2
	v_lshl_add_u32 v239, v239, 7, v238
	v_lshl_add_u32 v240, v240, 5, v238
	v_lshlrev_b32_e32 v239, 7, v239
	v_lshlrev_b32_e32 v240, 7, v240
	v_bfe_u32 v241, v145, 5, 1
	v_bfe_u32 v242, v145, 1, 3
	v_or_b32_e32 v243, 0, v241
	v_xor_b32_e32 v243, v243, v242
	v_lshlrev_b32_e32 v243, 4, v243
	v_add_u32_e32 v14, v239, v243
	v_add_u32_e32 v186, v240, v243
	v_or_b32_e32 v243, 2, v241
	v_xor_b32_e32 v243, v243, v242
	v_lshlrev_b32_e32 v243, 4, v243
	v_add_u32_e32 v15, v239, v243
	v_add_u32_e32 v189, v240, v243
	v_or_b32_e32 v243, 4, v241
	v_xor_b32_e32 v243, v243, v242
	v_lshlrev_b32_e32 v243, 4, v243
	v_add_u32_e32 v0, v239, v243
	v_add_u32_e32 v233, v240, v243
	v_or_b32_e32 v243, 6, v241
	v_xor_b32_e32 v243, v243, v242
	v_lshlrev_b32_e32 v243, 4, v243
	v_add_u32_e32 v184, v239, v243
	v_add_u32_e32 v234, v240, v243
	s_waitcnt vmcnt(6)
	s_barrier
	ds_read_b128 v[180:183], v186 offset:32768
	ds_read_b128 v[238:241], v14
	ds_read_b128 v[242:245], v14 offset:4096
	ds_read_b128 v[246:249], v14 offset:8192
	ds_read_b128 v[250:253], v14 offset:12288
	s_add_u32 m0, s33, 0x18000
	v_lshl_add_u64 v[2:3], v[2:3], 0, s[84:85]
	global_load_lds_dwordx4 v[2:3], off
	s_add_u32 m0, s33, 0x1a000
	v_lshl_add_u64 v[6:7], v[6:7], 0, s[84:85]
	global_load_lds_dwordx4 v[6:7], off
	s_add_u32 m0, s33, 0x1c000
	v_lshl_add_u64 v[8:9], v[8:9], 0, s[84:85]
	global_load_lds_dwordx4 v[8:9], off
	s_add_u32 m0, s33, 0x1e000
	v_lshl_add_u64 v[10:11], v[10:11], 0, s[84:85]
	global_load_lds_dwordx4 v[10:11], off
	s_add_u32 m0, s33, 0x20000
	v_lshl_add_u64 v[4:5], v[4:5], 0, s[84:85]
	global_load_lds_dwordx4 v[4:5], off
	s_add_u32 m0, s33, 0x22000
	v_lshl_add_u64 v[12:13], v[12:13], 0, s[84:85]
	global_load_lds_dwordx4 v[12:13], off
	ds_read_b128 v[190:193], v189 offset:32768
	s_waitcnt lgkmcnt(4)
	v_mfma_f32_32x32x16_bf16 v[112:127], v[238:241], v[180:183], 0
	ds_read_b128 v[238:241], v15
	s_waitcnt lgkmcnt(4)
	v_mfma_f32_32x32x16_bf16 v[96:111], v[242:245], v[180:183], 0
	ds_read_b128 v[242:245], v15 offset:4096
	s_waitcnt lgkmcnt(4)
	v_mfma_f32_32x32x16_bf16 v[80:95], v[246:249], v[180:183], 0
	ds_read_b128 v[246:249], v15 offset:8192
	s_waitcnt lgkmcnt(4)
	v_mfma_f32_32x32x16_bf16 v[64:79], v[250:253], v[180:183], 0
	ds_read_b128 v[250:253], v15 offset:12288
	ds_read_b128 v[180:183], v233 offset:32768
	s_waitcnt lgkmcnt(4)
	v_mfma_f32_32x32x16_bf16 v[112:127], v[238:241], v[190:193], v[112:127]
	ds_read_b128 v[238:241], v0
	s_waitcnt lgkmcnt(4)
	v_mfma_f32_32x32x16_bf16 v[96:111], v[242:245], v[190:193], v[96:111]
	ds_read_b128 v[242:245], v0 offset:4096
	s_waitcnt lgkmcnt(4)
	v_mfma_f32_32x32x16_bf16 v[80:95], v[246:249], v[190:193], v[80:95]
	ds_read_b128 v[246:249], v0 offset:8192
	s_waitcnt lgkmcnt(4)
	v_mfma_f32_32x32x16_bf16 v[64:79], v[250:253], v[190:193], v[64:79]
	ds_read_b128 v[250:253], v0 offset:12288
	ds_read_b128 v[190:193], v234 offset:32768
	s_waitcnt lgkmcnt(4)
	v_mfma_f32_32x32x16_bf16 v[112:127], v[238:241], v[180:183], v[112:127]
	ds_read_b128 v[238:241], v184
	s_waitcnt lgkmcnt(4)
	v_mfma_f32_32x32x16_bf16 v[96:111], v[242:245], v[180:183], v[96:111]
	ds_read_b128 v[242:245], v184 offset:4096
	s_waitcnt lgkmcnt(4)
	v_mfma_f32_32x32x16_bf16 v[80:95], v[246:249], v[180:183], v[80:95]
	ds_read_b128 v[246:249], v184 offset:8192
	s_waitcnt lgkmcnt(4)
	v_mfma_f32_32x32x16_bf16 v[64:79], v[250:253], v[180:183], v[64:79]
	ds_read_b128 v[250:253], v184 offset:12288
	s_waitcnt lgkmcnt(3)
	v_mfma_f32_32x32x16_bf16 v[112:127], v[238:241], v[190:193], v[112:127]
	s_waitcnt lgkmcnt(2)
	v_mfma_f32_32x32x16_bf16 v[96:111], v[242:245], v[190:193], v[96:111]
	s_waitcnt lgkmcnt(1)
	v_mfma_f32_32x32x16_bf16 v[80:95], v[246:249], v[190:193], v[80:95]
	s_waitcnt lgkmcnt(0)
	v_mfma_f32_32x32x16_bf16 v[64:79], v[250:253], v[190:193], v[64:79]
	s_waitcnt vmcnt(6)
	s_barrier
; DI f32x16 mfma(bf16x8 a, bf16x8 b, f32x16 c) { return __builtin_amdgcn_mfma_f32_32x32x16_bf16(a, b, c, 0, 0, 0); }
;     ...
;   __syncthreads();
;   DMA_ISSUE(0, 0)
;   asm volatile("s_waitcnt vmcnt(0)" ::: "memory");
;   __builtin_amdgcn_s_barrier();
;   for (int kt = 0; kt < nk; ++kt) {
;     const char* cur = lds + (kt & 1) * DBUF;
;     if (kt + 1 < nk) DMA_ISSUE((kt + 1) & 1, kt + 1)
; #pragma unroll(NTB == 1 ? 2 : 4)
;     for (int s = 0; s < 4; ++s) {
;       const int ro = ((2 * s + hh) ^ xr) * 16;
;       bf16x8 bfr[NTB];
; #pragma unroll
;       for (int tb = 0; tb < NTB; ++tb) bfr[tb] = *(const bf16x8*)(cur + bbase + tb * 32 * DROW + ro);
; #pragma unroll
;       for (int fb = 0; fb < NFB; ++fb) {
;         const bf16x8 afr = *(const bf16x8*)(cur + abase + fb * 32 * DROW + ro);
; #pragma unroll
;         for (int tb = 0; tb < NTB; ++tb) acc[tb * NFB + fb] = mfma(afr, bfr[tb], acc[tb * NFB + fb]);
;       }
;     }
;     asm volatile("s_waitcnt vmcnt(0) lgkmcnt(0)" ::: "memory");
;     __builtin_amdgcn_s_barrier();
	v_add_u32_e32 v195, 0xc000, v186
	ds_read_b128 v[180:183], v195 offset:32768
	v_add_u32_e32 v194, 0xc000, v14
	ds_read_b128 v[238:241], v194
	ds_read_b128 v[242:245], v194 offset:4096
	ds_read_b128 v[246:249], v194 offset:8192
	ds_read_b128 v[250:253], v194 offset:12288
	s_add_u32 m0, s33, 0x0
	v_lshl_add_u64 v[2:3], v[2:3], 0, s[84:85]
	global_load_lds_dwordx4 v[2:3], off
	s_add_u32 m0, s33, 0x2000
	v_lshl_add_u64 v[6:7], v[6:7], 0, s[84:85]
	global_load_lds_dwordx4 v[6:7], off
	s_add_u32 m0, s33, 0x4000
	v_lshl_add_u64 v[8:9], v[8:9], 0, s[84:85]
	global_load_lds_dwordx4 v[8:9], off
	s_add_u32 m0, s33, 0x6000
	v_lshl_add_u64 v[10:11], v[10:11], 0, s[84:85]
	global_load_lds_dwordx4 v[10:11], off
	s_add_u32 m0, s33, 0x8000
	v_lshl_add_u64 v[4:5], v[4:5], 0, s[84:85]
	global_load_lds_dwordx4 v[4:5], off
	s_add_u32 m0, s33, 0xa000
	v_lshl_add_u64 v[12:13], v[12:13], 0, s[84:85]
	global_load_lds_dwordx4 v[12:13], off
	v_add_u32_e32 v195, 0xc000, v189
	ds_read_b128 v[190:193], v195 offset:32768
	v_add_u32_e32 v194, 0xc000, v15
	s_waitcnt lgkmcnt(4)
	v_mfma_f32_32x32x16_bf16 v[112:127], v[238:241], v[180:183], v[112:127]
	ds_read_b128 v[238:241], v194
	s_waitcnt lgkmcnt(4)
	v_mfma_f32_32x32x16_bf16 v[96:111], v[242:245], v[180:183], v[96:111]
	ds_read_b128 v[242:245], v194 offset:4096
	s_waitcnt lgkmcnt(4)
	v_mfma_f32_32x32x16_bf16 v[80:95], v[246:249], v[180:183], v[80:95]
	ds_read_b128 v[246:249], v194 offset:8192
	s_waitcnt lgkmcnt(4)
	v_mfma_f32_32x32x16_bf16 v[64:79], v[250:253], v[180:183], v[64:79]
	ds_read_b128 v[250:253], v194 offset:12288
	v_add_u32_e32 v195, 0xc000, v233
	ds_read_b128 v[180:183], v195 offset:32768
	v_add_u32_e32 v194, 0xc000, v0
	s_waitcnt lgkmcnt(4)
	v_mfma_f32_32x32x16_bf16 v[112:127], v[238:241], v[190:193], v[112:127]
	ds_read_b128 v[238:241], v194
	s_waitcnt lgkmcnt(4)
	v_mfma_f32_32x32x16_bf16 v[96:111], v[242:245], v[190:193], v[96:111]
	ds_read_b128 v[242:245], v194 offset:4096
	s_waitcnt lgkmcnt(4)
	v_mfma_f32_32x32x16_bf16 v[80:95], v[246:249], v[190:193], v[80:95]
	ds_read_b128 v[246:249], v194 offset:8192
	s_waitcnt lgkmcnt(4)
	v_mfma_f32_32x32x16_bf16 v[64:79], v[250:253], v[190:193], v[64:79]
	ds_read_b128 v[250:253], v194 offset:12288
	v_add_u32_e32 v195, 0xc000, v234
	ds_read_b128 v[190:193], v195 offset:32768
	v_add_u32_e32 v194, 0xc000, v184
	s_waitcnt lgkmcnt(4)
	v_mfma_f32_32x32x16_bf16 v[112:127], v[238:241], v[180:183], v[112:127]
	ds_read_b128 v[238:241], v194
	s_waitcnt lgkmcnt(4)
	v_mfma_f32_32x32x16_bf16 v[96:111], v[242:245], v[180:183], v[96:111]
	ds_read_b128 v[242:245], v194 offset:4096
	s_waitcnt lgkmcnt(4)
	v_mfma_f32_32x32x16_bf16 v[80:95], v[246:249], v[180:183], v[80:95]
	ds_read_b128 v[246:249], v194 offset:8192
	s_waitcnt lgkmcnt(4)
	v_mfma_f32_32x32x16_bf16 v[64:79], v[250:253], v[180:183], v[64:79]
	ds_read_b128 v[250:253], v194 offset:12288
	s_waitcnt lgkmcnt(3)
	v_mfma_f32_32x32x16_bf16 v[112:127], v[238:241], v[190:193], v[112:127]
	s_waitcnt lgkmcnt(2)
	v_mfma_f32_32x32x16_bf16 v[96:111], v[242:245], v[190:193], v[96:111]
	s_waitcnt lgkmcnt(1)
	v_mfma_f32_32x32x16_bf16 v[80:95], v[246:249], v[190:193], v[80:95]
	s_waitcnt lgkmcnt(0)
	v_mfma_f32_32x32x16_bf16 v[64:79], v[250:253], v[190:193], v[64:79]
	s_waitcnt vmcnt(6)
	s_barrier
	v_add_u32_e32 v195, 0x18000, v186
	ds_read_b128 v[180:183], v195 offset:32768
	v_add_u32_e32 v194, 0x18000, v14
	ds_read_b128 v[238:241], v194
	ds_read_b128 v[242:245], v194 offset:4096
	ds_read_b128 v[246:249], v194 offset:8192
	ds_read_b128 v[250:253], v194 offset:12288
	s_add_u32 m0, s33, 0xc000
	v_lshl_add_u64 v[2:3], v[2:3], 0, s[84:85]
	global_load_lds_dwordx4 v[2:3], off
	s_add_u32 m0, s33, 0xe000
	v_lshl_add_u64 v[6:7], v[6:7], 0, s[84:85]
	global_load_lds_dwordx4 v[6:7], off
	s_add_u32 m0, s33, 0x10000
	v_lshl_add_u64 v[8:9], v[8:9], 0, s[84:85]
	global_load_lds_dwordx4 v[8:9], off
	s_add_u32 m0, s33, 0x12000
	v_lshl_add_u64 v[10:11], v[10:11], 0, s[84:85]
	global_load_lds_dwordx4 v[10:11], off
	s_add_u32 m0, s33, 0x14000
	v_lshl_add_u64 v[4:5], v[4:5], 0, s[84:85]
	global_load_lds_dwordx4 v[4:5], off
	s_add_u32 m0, s33, 0x16000
	v_lshl_add_u64 v[12:13], v[12:13], 0, s[84:85]
	global_load_lds_dwordx4 v[12:13], off
	v_add_u32_e32 v195, 0x18000, v189
	ds_read_b128 v[190:193], v195 offset:32768
	v_add_u32_e32 v194, 0x18000, v15
	s_waitcnt lgkmcnt(4)
	v_mfma_f32_32x32x16_bf16 v[112:127], v[238:241], v[180:183], v[112:127]
	ds_read_b128 v[238:241], v194
	s_waitcnt lgkmcnt(4)
	v_mfma_f32_32x32x16_bf16 v[96:111], v[242:245], v[180:183], v[96:111]
	ds_read_b128 v[242:245], v194 offset:4096
	s_waitcnt lgkmcnt(4)
	v_mfma_f32_32x32x16_bf16 v[80:95], v[246:249], v[180:183], v[80:95]
	ds_read_b128 v[246:249], v194 offset:8192
	s_waitcnt lgkmcnt(4)
	v_mfma_f32_32x32x16_bf16 v[64:79], v[250:253], v[180:183], v[64:79]
	ds_read_b128 v[250:253], v194 offset:12288
	v_add_u32_e32 v195, 0x18000, v233
	ds_read_b128 v[180:183], v195 offset:32768
	v_add_u32_e32 v194, 0x18000, v0
	s_waitcnt lgkmcnt(4)
	v_mfma_f32_32x32x16_bf16 v[112:127], v[238:241], v[190:193], v[112:127]
	ds_read_b128 v[238:241], v194
	s_waitcnt lgkmcnt(4)
	v_mfma_f32_32x32x16_bf16 v[96:111], v[242:245], v[190:193], v[96:111]
	ds_read_b128 v[242:245], v194 offset:4096
	s_waitcnt lgkmcnt(4)
	v_mfma_f32_32x32x16_bf16 v[80:95], v[246:249], v[190:193], v[80:95]
	ds_read_b128 v[246:249], v194 offset:8192
	s_waitcnt lgkmcnt(4)
	v_mfma_f32_32x32x16_bf16 v[64:79], v[250:253], v[190:193], v[64:79]
	ds_read_b128 v[250:253], v194 offset:12288
	v_add_u32_e32 v195, 0x18000, v234
	ds_read_b128 v[190:193], v195 offset:32768
	v_add_u32_e32 v194, 0x18000, v184
	s_waitcnt lgkmcnt(4)
	v_mfma_f32_32x32x16_bf16 v[112:127], v[238:241], v[180:183], v[112:127]
	ds_read_b128 v[238:241], v194
	s_waitcnt lgkmcnt(4)
	v_mfma_f32_32x32x16_bf16 v[96:111], v[242:245], v[180:183], v[96:111]
	ds_read_b128 v[242:245], v194 offset:4096
	s_waitcnt lgkmcnt(4)
	v_mfma_f32_32x32x16_bf16 v[80:95], v[246:249], v[180:183], v[80:95]
	ds_read_b128 v[246:249], v194 offset:8192
	s_waitcnt lgkmcnt(4)
	v_mfma_f32_32x32x16_bf16 v[64:79], v[250:253], v[180:183], v[64:79]
	ds_read_b128 v[250:253], v194 offset:12288
	s_waitcnt lgkmcnt(3)
	v_mfma_f32_32x32x16_bf16 v[112:127], v[238:241], v[190:193], v[112:127]
	s_waitcnt lgkmcnt(2)
	v_mfma_f32_32x32x16_bf16 v[96:111], v[242:245], v[190:193], v[96:111]
	s_waitcnt lgkmcnt(1)
	v_mfma_f32_32x32x16_bf16 v[80:95], v[246:249], v[190:193], v[80:95]
	s_waitcnt lgkmcnt(0)
	v_mfma_f32_32x32x16_bf16 v[64:79], v[250:253], v[190:193], v[64:79]
	s_waitcnt vmcnt(6)
	s_barrier
; DI f32x16 mfma(bf16x8 a, bf16x8 b, f32x16 c) { return __builtin_amdgcn_mfma_f32_32x32x16_bf16(a, b, c, 0, 0, 0); }
;     ...
;   __syncthreads();
;   DMA_ISSUE(0, 0)
;   asm volatile("s_waitcnt vmcnt(0)" ::: "memory");
;   __builtin_amdgcn_s_barrier();
;   for (int kt = 0; kt < nk; ++kt) {
;     const char* cur = lds + (kt & 1) * DBUF;
;     if (kt + 1 < nk) DMA_ISSUE((kt + 1) & 1, kt + 1)
; #pragma unroll(NTB == 1 ? 2 : 4)
;     for (int s = 0; s < 4; ++s) {
;       const int ro = ((2 * s + hh) ^ xr) * 16;
;       bf16x8 bfr[NTB];
; #pragma unroll
;       for (int tb = 0; tb < NTB; ++tb) bfr[tb] = *(const bf16x8*)(cur + bbase + tb * 32 * DROW + ro);
; #pragma unroll
;       for (int fb = 0; fb < NFB; ++fb) {
;         const bf16x8 afr = *(const bf16x8*)(cur + abase + fb * 32 * DROW + ro);
; #pragma unroll
;         for (int tb = 0; tb < NTB; ++tb) acc[tb * NFB + fb] = mfma(afr, bfr[tb], acc[tb * NFB + fb]);
;       }
;     }
;     asm volatile("s_waitcnt vmcnt(0) lgkmcnt(0)" ::: "memory");
;     __builtin_amdgcn_s_barrier();
	ds_read_b128 v[180:183], v186 offset:32768
	ds_read_b128 v[238:241], v14
	ds_read_b128 v[242:245], v14 offset:4096
	ds_read_b128 v[246:249], v14 offset:8192
	ds_read_b128 v[250:253], v14 offset:12288
	s_add_u32 m0, s33, 0x18000
	v_lshl_add_u64 v[2:3], v[2:3], 0, s[84:85]
	global_load_lds_dwordx4 v[2:3], off
	s_add_u32 m0, s33, 0x1a000
	v_lshl_add_u64 v[6:7], v[6:7], 0, s[84:85]
	global_load_lds_dwordx4 v[6:7], off
	s_add_u32 m0, s33, 0x1c000
	v_lshl_add_u64 v[8:9], v[8:9], 0, s[84:85]
	global_load_lds_dwordx4 v[8:9], off
	s_add_u32 m0, s33, 0x1e000
	v_lshl_add_u64 v[10:11], v[10:11], 0, s[84:85]
	global_load_lds_dwordx4 v[10:11], off
	s_add_u32 m0, s33, 0x20000
	v_lshl_add_u64 v[4:5], v[4:5], 0, s[84:85]
	global_load_lds_dwordx4 v[4:5], off
	s_add_u32 m0, s33, 0x22000
	v_lshl_add_u64 v[12:13], v[12:13], 0, s[84:85]
	global_load_lds_dwordx4 v[12:13], off
	ds_read_b128 v[190:193], v189 offset:32768
	s_waitcnt lgkmcnt(4)
	v_mfma_f32_32x32x16_bf16 v[112:127], v[238:241], v[180:183], v[112:127]
	ds_read_b128 v[238:241], v15
	s_waitcnt lgkmcnt(4)
	v_mfma_f32_32x32x16_bf16 v[96:111], v[242:245], v[180:183], v[96:111]
	ds_read_b128 v[242:245], v15 offset:4096
	s_waitcnt lgkmcnt(4)
	v_mfma_f32_32x32x16_bf16 v[80:95], v[246:249], v[180:183], v[80:95]
	ds_read_b128 v[246:249], v15 offset:8192
	s_waitcnt lgkmcnt(4)
	v_mfma_f32_32x32x16_bf16 v[64:79], v[250:253], v[180:183], v[64:79]
	ds_read_b128 v[250:253], v15 offset:12288
	ds_read_b128 v[180:183], v233 offset:32768
	s_waitcnt lgkmcnt(4)
	v_mfma_f32_32x32x16_bf16 v[112:127], v[238:241], v[190:193], v[112:127]
	ds_read_b128 v[238:241], v0
	s_waitcnt lgkmcnt(4)
	v_mfma_f32_32x32x16_bf16 v[96:111], v[242:245], v[190:193], v[96:111]
	ds_read_b128 v[242:245], v0 offset:4096
	s_waitcnt lgkmcnt(4)
	v_mfma_f32_32x32x16_bf16 v[80:95], v[246:249], v[190:193], v[80:95]
	ds_read_b128 v[246:249], v0 offset:8192
	s_waitcnt lgkmcnt(4)
	v_mfma_f32_32x32x16_bf16 v[64:79], v[250:253], v[190:193], v[64:79]
	ds_read_b128 v[250:253], v0 offset:12288
	ds_read_b128 v[190:193], v234 offset:32768
	s_waitcnt lgkmcnt(4)
	v_mfma_f32_32x32x16_bf16 v[112:127], v[238:241], v[180:183], v[112:127]
	ds_read_b128 v[238:241], v184
	s_waitcnt lgkmcnt(4)
	v_mfma_f32_32x32x16_bf16 v[96:111], v[242:245], v[180:183], v[96:111]
	ds_read_b128 v[242:245], v184 offset:4096
	s_waitcnt lgkmcnt(4)
	v_mfma_f32_32x32x16_bf16 v[80:95], v[246:249], v[180:183], v[80:95]
	ds_read_b128 v[246:249], v184 offset:8192
	s_waitcnt lgkmcnt(4)
	v_mfma_f32_32x32x16_bf16 v[64:79], v[250:253], v[180:183], v[64:79]
	ds_read_b128 v[250:253], v184 offset:12288
	s_waitcnt lgkmcnt(3)
	v_mfma_f32_32x32x16_bf16 v[112:127], v[238:241], v[190:193], v[112:127]
	s_waitcnt lgkmcnt(2)
	v_mfma_f32_32x32x16_bf16 v[96:111], v[242:245], v[190:193], v[96:111]
	s_waitcnt lgkmcnt(1)
	v_mfma_f32_32x32x16_bf16 v[80:95], v[246:249], v[190:193], v[80:95]
	s_waitcnt lgkmcnt(0)
	v_mfma_f32_32x32x16_bf16 v[64:79], v[250:253], v[190:193], v[64:79]
	s_waitcnt vmcnt(6)
	s_barrier
	v_add_u32_e32 v195, 0xc000, v186
	ds_read_b128 v[180:183], v195 offset:32768
	v_add_u32_e32 v194, 0xc000, v14
	ds_read_b128 v[238:241], v194
	ds_read_b128 v[242:245], v194 offset:4096
	ds_read_b128 v[246:249], v194 offset:8192
	ds_read_b128 v[250:253], v194 offset:12288
	s_add_u32 m0, s33, 0x0
	v_lshl_add_u64 v[2:3], v[2:3], 0, s[84:85]
	global_load_lds_dwordx4 v[2:3], off
	s_add_u32 m0, s33, 0x2000
	v_lshl_add_u64 v[6:7], v[6:7], 0, s[84:85]
	global_load_lds_dwordx4 v[6:7], off
	s_add_u32 m0, s33, 0x4000
	v_lshl_add_u64 v[8:9], v[8:9], 0, s[84:85]
	global_load_lds_dwordx4 v[8:9], off
	s_add_u32 m0, s33, 0x6000
	v_lshl_add_u64 v[10:11], v[10:11], 0, s[84:85]
	global_load_lds_dwordx4 v[10:11], off
	s_add_u32 m0, s33, 0x8000
	v_lshl_add_u64 v[4:5], v[4:5], 0, s[84:85]
	global_load_lds_dwordx4 v[4:5], off
	s_add_u32 m0, s33, 0xa000
	v_lshl_add_u64 v[12:13], v[12:13], 0, s[84:85]
	global_load_lds_dwordx4 v[12:13], off
	v_add_u32_e32 v195, 0xc000, v189
	ds_read_b128 v[190:193], v195 offset:32768
	v_add_u32_e32 v194, 0xc000, v15
	s_waitcnt lgkmcnt(4)
	v_mfma_f32_32x32x16_bf16 v[112:127], v[238:241], v[180:183], v[112:127]
	ds_read_b128 v[238:241], v194
	s_waitcnt lgkmcnt(4)
	v_mfma_f32_32x32x16_bf16 v[96:111], v[242:245], v[180:183], v[96:111]
	ds_read_b128 v[242:245], v194 offset:4096
	s_waitcnt lgkmcnt(4)
	v_mfma_f32_32x32x16_bf16 v[80:95], v[246:249], v[180:183], v[80:95]
	ds_read_b128 v[246:249], v194 offset:8192
	s_waitcnt lgkmcnt(4)
	v_mfma_f32_32x32x16_bf16 v[64:79], v[250:253], v[180:183], v[64:79]
	ds_read_b128 v[250:253], v194 offset:12288
	v_add_u32_e32 v195, 0xc000, v233
	ds_read_b128 v[180:183], v195 offset:32768
	v_add_u32_e32 v194, 0xc000, v0
	s_waitcnt lgkmcnt(4)
	v_mfma_f32_32x32x16_bf16 v[112:127], v[238:241], v[190:193], v[112:127]
	ds_read_b128 v[238:241], v194
	s_waitcnt lgkmcnt(4)
	v_mfma_f32_32x32x16_bf16 v[96:111], v[242:245], v[190:193], v[96:111]
	ds_read_b128 v[242:245], v194 offset:4096
	s_waitcnt lgkmcnt(4)
	v_mfma_f32_32x32x16_bf16 v[80:95], v[246:249], v[190:193], v[80:95]
	ds_read_b128 v[246:249], v194 offset:8192
	s_waitcnt lgkmcnt(4)
	v_mfma_f32_32x32x16_bf16 v[64:79], v[250:253], v[190:193], v[64:79]
	ds_read_b128 v[250:253], v194 offset:12288
	v_add_u32_e32 v195, 0xc000, v234
	ds_read_b128 v[190:193], v195 offset:32768
	v_add_u32_e32 v194, 0xc000, v184
	s_waitcnt lgkmcnt(4)
	v_mfma_f32_32x32x16_bf16 v[112:127], v[238:241], v[180:183], v[112:127]
	ds_read_b128 v[238:241], v194
	s_waitcnt lgkmcnt(4)
	v_mfma_f32_32x32x16_bf16 v[96:111], v[242:245], v[180:183], v[96:111]
	ds_read_b128 v[242:245], v194 offset:4096
	s_waitcnt lgkmcnt(4)
	v_mfma_f32_32x32x16_bf16 v[80:95], v[246:249], v[180:183], v[80:95]
	ds_read_b128 v[246:249], v194 offset:8192
	s_waitcnt lgkmcnt(4)
	v_mfma_f32_32x32x16_bf16 v[64:79], v[250:253], v[180:183], v[64:79]
	ds_read_b128 v[250:253], v194 offset:12288
	s_waitcnt lgkmcnt(3)
	v_mfma_f32_32x32x16_bf16 v[112:127], v[238:241], v[190:193], v[112:127]
	s_waitcnt lgkmcnt(2)
	v_mfma_f32_32x32x16_bf16 v[96:111], v[242:245], v[190:193], v[96:111]
	s_waitcnt lgkmcnt(1)
	v_mfma_f32_32x32x16_bf16 v[80:95], v[246:249], v[190:193], v[80:95]
	s_waitcnt lgkmcnt(0)
	v_mfma_f32_32x32x16_bf16 v[64:79], v[250:253], v[190:193], v[64:79]
	s_waitcnt vmcnt(6)
	s_barrier
; DI unsigned pack2(float a, float b) { f2_t v = {a, b}; bf2_t r = __builtin_convertvector(v, bf2_t); return __builtin_bit_cast(unsigned, r); }
;     ...
;   __syncthreads();
;   DMA_ISSUE(0, 0)
;   asm volatile("s_waitcnt vmcnt(0)" ::: "memory");
;   __builtin_amdgcn_s_barrier();
;   for (int kt = 0; kt < nk; ++kt) {
;     const char* cur = lds + (kt & 1) * DBUF;
;     if (kt + 1 < nk) DMA_ISSUE((kt + 1) & 1, kt + 1)
; __global__ void __launch_bounds__(512) mega(Params p) {
;     ...
;         for (int n = 0; n < 3; ++n) {
;           f32x16 acc[4]; zero4(acc);
;           const size_t ooff = (n == 0) ? R_OA : (n == 1 ? R_OB : R_OC);
;           gemm_main<4, 1>((const u16*)(ws + OFF_WBR) + ((size_t)n * 1024 + ft * 256) * 512, 512, (const u16*)(ws + ooff) + (size_t)tt * 128 * 512, 512, 8, acc, lds);
;           unsigned bp[4][8];
; #pragma unroll
;           for (int fb = 0; fb < 4; ++fb)
; #pragma unroll
;             for (int i = 0; i < 8; ++i) bp[fb][i] = pack2(acc[fb][2 * i], acc[fb][2 * i + 1]);
;           zero4(acc);
;           gemm_main<4, 1>((const u16*)(ws + OFF_WG) + ((size_t)n * 1024 + ft * 256) * 1024, 1024, (const u16*)(ws + OFF_H) + (size_t)tt * 128 * 1024, 1024, 16, acc, lds);
	v_add_u32_e32 v195, 0x18000, v186
	ds_read_b128 v[180:183], v195 offset:32768
	v_add_u32_e32 v194, 0x18000, v14
	ds_read_b128 v[238:241], v194
	ds_read_b128 v[242:245], v194 offset:4096
	ds_read_b128 v[246:249], v194 offset:8192
	ds_read_b128 v[250:253], v194 offset:12288
	s_add_u32 m0, s33, 0xc000
	v_lshl_add_u64 v[2:3], v[2:3], 0, s[84:85]
	global_load_lds_dwordx4 v[2:3], off
	s_add_u32 m0, s33, 0xe000
	v_lshl_add_u64 v[6:7], v[6:7], 0, s[84:85]
	global_load_lds_dwordx4 v[6:7], off
	s_add_u32 m0, s33, 0x10000
	v_lshl_add_u64 v[8:9], v[8:9], 0, s[84:85]
	global_load_lds_dwordx4 v[8:9], off
	s_add_u32 m0, s33, 0x12000
	v_lshl_add_u64 v[10:11], v[10:11], 0, s[84:85]
	global_load_lds_dwordx4 v[10:11], off
	s_add_u32 m0, s33, 0x14000
	v_lshl_add_u64 v[4:5], v[4:5], 0, s[84:85]
	global_load_lds_dwordx4 v[4:5], off
	s_add_u32 m0, s33, 0x16000
	v_lshl_add_u64 v[12:13], v[12:13], 0, s[84:85]
	global_load_lds_dwordx4 v[12:13], off
	v_add_u32_e32 v195, 0x18000, v189
	ds_read_b128 v[190:193], v195 offset:32768
	v_add_u32_e32 v194, 0x18000, v15
	s_waitcnt lgkmcnt(4)
	v_mfma_f32_32x32x16_bf16 v[112:127], v[238:241], v[180:183], v[112:127]
	ds_read_b128 v[238:241], v194
	s_waitcnt lgkmcnt(4)
	v_mfma_f32_32x32x16_bf16 v[96:111], v[242:245], v[180:183], v[96:111]
	ds_read_b128 v[242:245], v194 offset:4096
	s_waitcnt lgkmcnt(4)
	v_mfma_f32_32x32x16_bf16 v[80:95], v[246:249], v[180:183], v[80:95]
	ds_read_b128 v[246:249], v194 offset:8192
	s_waitcnt lgkmcnt(4)
	v_mfma_f32_32x32x16_bf16 v[64:79], v[250:253], v[180:183], v[64:79]
	ds_read_b128 v[250:253], v194 offset:12288
	v_add_u32_e32 v195, 0x18000, v233
	ds_read_b128 v[180:183], v195 offset:32768
	v_add_u32_e32 v194, 0x18000, v0
	s_waitcnt lgkmcnt(4)
	v_mfma_f32_32x32x16_bf16 v[112:127], v[238:241], v[190:193], v[112:127]
	ds_read_b128 v[238:241], v194
	s_waitcnt lgkmcnt(4)
	v_mfma_f32_32x32x16_bf16 v[96:111], v[242:245], v[190:193], v[96:111]
	ds_read_b128 v[242:245], v194 offset:4096
	s_waitcnt lgkmcnt(4)
	v_mfma_f32_32x32x16_bf16 v[80:95], v[246:249], v[190:193], v[80:95]
	ds_read_b128 v[246:249], v194 offset:8192
	s_waitcnt lgkmcnt(4)
	v_mfma_f32_32x32x16_bf16 v[64:79], v[250:253], v[190:193], v[64:79]
	ds_read_b128 v[250:253], v194 offset:12288
	v_add_u32_e32 v195, 0x18000, v234
	ds_read_b128 v[190:193], v195 offset:32768
	v_add_u32_e32 v194, 0x18000, v184
	s_waitcnt lgkmcnt(4)
	v_mfma_f32_32x32x16_bf16 v[112:127], v[238:241], v[180:183], v[112:127]
	ds_read_b128 v[238:241], v194
	s_waitcnt lgkmcnt(4)
	v_mfma_f32_32x32x16_bf16 v[96:111], v[242:245], v[180:183], v[96:111]
	ds_read_b128 v[242:245], v194 offset:4096
	s_waitcnt lgkmcnt(4)
	v_mfma_f32_32x32x16_bf16 v[80:95], v[246:249], v[180:183], v[80:95]
	ds_read_b128 v[246:249], v194 offset:8192
	s_waitcnt lgkmcnt(4)
	v_mfma_f32_32x32x16_bf16 v[64:79], v[250:253], v[180:183], v[64:79]
	ds_read_b128 v[250:253], v194 offset:12288
	s_waitcnt lgkmcnt(3)
	v_mfma_f32_32x32x16_bf16 v[112:127], v[238:241], v[190:193], v[112:127]
	s_waitcnt lgkmcnt(2)
	v_mfma_f32_32x32x16_bf16 v[96:111], v[242:245], v[190:193], v[96:111]
	s_waitcnt lgkmcnt(1)
	v_mfma_f32_32x32x16_bf16 v[80:95], v[246:249], v[190:193], v[80:95]
	s_waitcnt lgkmcnt(0)
	v_mfma_f32_32x32x16_bf16 v[64:79], v[250:253], v[190:193], v[64:79]
	s_waitcnt vmcnt(6)
	s_barrier
	ds_read_b128 v[180:183], v186 offset:32768
	ds_read_b128 v[238:241], v14
	ds_read_b128 v[242:245], v14 offset:4096
	ds_read_b128 v[246:249], v14 offset:8192
	ds_read_b128 v[250:253], v14 offset:12288
	s_lshl_b64 s[34:35], s[34:35], 11
	s_add_u32 s34, s38, s34
	s_addc_u32 s35, s39, s35
	v_ashrrev_i32_e32 v18, 3, v145
	v_lshrrev_b32_e32 v16, 4, v145
	v_xor_b32_e32 v16, v16, v145
	v_ashrrev_i32_e32 v19, 31, v18
	v_lshlrev_b64 v[18:19], 11, v[18:19]
	v_lshlrev_b32_e32 v16, 4, v16
	v_and_b32_e32 v16, 0x70, v16
	v_mov_b32_e32 v17, 0
	v_lshl_add_u64 v[2:3], s[34:35], 0, v[18:19]
	v_lshl_add_u64 v[4:5], s[64:65], 0, v[18:19]
	v_lshl_add_u64 v[2:3], v[2:3], 0, v[16:17]
	v_lshl_add_u64 v[4:5], v[4:5], 0, v[16:17]
	s_mov_b64 s[68:69], 0x20000
	v_lshl_add_u64 v[6:7], v[2:3], 0, s[68:69]
	v_lshl_add_u64 v[12:13], v[4:5], 0, s[68:69]
	v_lshl_add_u64 v[8:9], v[6:7], 0, s[68:69]
	v_lshl_add_u64 v[10:11], v[8:9], 0, s[68:69]
	s_add_u32 m0, s33, 0x18000
	s_nop 0
	global_load_lds_dwordx4 v[2:3], off
	s_add_u32 m0, s33, 0x1a000
	s_nop 0
	global_load_lds_dwordx4 v[6:7], off
	s_add_u32 m0, s33, 0x1c000
	s_nop 0
	global_load_lds_dwordx4 v[8:9], off
	s_add_u32 m0, s33, 0x1e000
	s_nop 0
	global_load_lds_dwordx4 v[10:11], off
	s_add_u32 m0, s33, 0x20000
	s_nop 0
	global_load_lds_dwordx4 v[4:5], off
	s_add_u32 m0, s33, 0x22000
	s_nop 0
	global_load_lds_dwordx4 v[12:13], off
	ds_read_b128 v[190:193], v189 offset:32768
	s_waitcnt lgkmcnt(4)
	v_mfma_f32_32x32x16_bf16 v[112:127], v[238:241], v[180:183], v[112:127]
	ds_read_b128 v[238:241], v15
	s_waitcnt lgkmcnt(4)
	v_mfma_f32_32x32x16_bf16 v[96:111], v[242:245], v[180:183], v[96:111]
	ds_read_b128 v[242:245], v15 offset:4096
	s_waitcnt lgkmcnt(4)
	v_mfma_f32_32x32x16_bf16 v[80:95], v[246:249], v[180:183], v[80:95]
	ds_read_b128 v[246:249], v15 offset:8192
	s_waitcnt lgkmcnt(4)
	v_mfma_f32_32x32x16_bf16 v[64:79], v[250:253], v[180:183], v[64:79]
	ds_read_b128 v[250:253], v15 offset:12288
	ds_read_b128 v[180:183], v233 offset:32768
	s_waitcnt lgkmcnt(4)
	v_mfma_f32_32x32x16_bf16 v[112:127], v[238:241], v[190:193], v[112:127]
	ds_read_b128 v[238:241], v0
	s_waitcnt lgkmcnt(4)
	v_mfma_f32_32x32x16_bf16 v[96:111], v[242:245], v[190:193], v[96:111]
	ds_read_b128 v[242:245], v0 offset:4096
	s_waitcnt lgkmcnt(4)
	v_mfma_f32_32x32x16_bf16 v[80:95], v[246:249], v[190:193], v[80:95]
	ds_read_b128 v[246:249], v0 offset:8192
	s_waitcnt lgkmcnt(4)
	v_mfma_f32_32x32x16_bf16 v[64:79], v[250:253], v[190:193], v[64:79]
	ds_read_b128 v[250:253], v0 offset:12288
	ds_read_b128 v[190:193], v234 offset:32768
	s_waitcnt lgkmcnt(4)
	v_mfma_f32_32x32x16_bf16 v[112:127], v[238:241], v[180:183], v[112:127]
	ds_read_b128 v[238:241], v184
	s_waitcnt lgkmcnt(4)
	v_mfma_f32_32x32x16_bf16 v[96:111], v[242:245], v[180:183], v[96:111]
	ds_read_b128 v[242:245], v184 offset:4096
	s_waitcnt lgkmcnt(4)
	v_mfma_f32_32x32x16_bf16 v[80:95], v[246:249], v[180:183], v[80:95]
	ds_read_b128 v[246:249], v184 offset:8192
	s_waitcnt lgkmcnt(4)
	v_mfma_f32_32x32x16_bf16 v[64:79], v[250:253], v[180:183], v[64:79]
	ds_read_b128 v[250:253], v184 offset:12288
	s_waitcnt lgkmcnt(3)
	v_mfma_f32_32x32x16_bf16 v[112:127], v[238:241], v[190:193], v[112:127]
	s_waitcnt lgkmcnt(2)
	v_mfma_f32_32x32x16_bf16 v[96:111], v[242:245], v[190:193], v[96:111]
	s_waitcnt lgkmcnt(1)
	v_mfma_f32_32x32x16_bf16 v[80:95], v[246:249], v[190:193], v[80:95]
	s_waitcnt lgkmcnt(0)
	v_mfma_f32_32x32x16_bf16 v[64:79], v[250:253], v[190:193], v[64:79]
	s_waitcnt vmcnt(6)
	s_barrier
; DI unsigned pack2(float a, float b) { f2_t v = {a, b}; bf2_t r = __builtin_convertvector(v, bf2_t); return __builtin_bit_cast(unsigned, r); }
; DI f32x16 mfma(bf16x8 a, bf16x8 b, f32x16 c) { return __builtin_amdgcn_mfma_f32_32x32x16_bf16(a, b, c, 0, 0, 0); }
;     ...
;   __syncthreads();
;   DMA_ISSUE(0, 0)
;   asm volatile("s_waitcnt vmcnt(0)" ::: "memory");
;   __builtin_amdgcn_s_barrier();
;   for (int kt = 0; kt < nk; ++kt) {
;     const char* cur = lds + (kt & 1) * DBUF;
;     if (kt + 1 < nk) DMA_ISSUE((kt + 1) & 1, kt + 1)
; #pragma unroll(NTB == 1 ? 2 : 4)
;     for (int s = 0; s < 4; ++s) {
;       const int ro = ((2 * s + hh) ^ xr) * 16;
;       bf16x8 bfr[NTB];
; #pragma unroll
;       for (int tb = 0; tb < NTB; ++tb) bfr[tb] = *(const bf16x8*)(cur + bbase + tb * 32 * DROW + ro);
; #pragma unroll
;       for (int fb = 0; fb < NFB; ++fb) {
;         const bf16x8 afr = *(const bf16x8*)(cur + abase + fb * 32 * DROW + ro);
; #pragma unroll
;         for (int tb = 0; tb < NTB; ++tb) acc[tb * NFB + fb] = mfma(afr, bfr[tb], acc[tb * NFB + fb]);
;       }
;     }
;     asm volatile("s_waitcnt vmcnt(0) lgkmcnt(0)" ::: "memory");
;     __builtin_amdgcn_s_barrier();
; __global__ void __launch_bounds__(512) mega(Params p) {
;     ...
;           gemm_main<4, 1>((const u16*)(ws + OFF_WBR) + ((size_t)n * 1024 + ft * 256) * 512, 512, (const u16*)(ws + ooff) + (size_t)tt * 128 * 512, 512, 8, acc, lds);
;           unsigned bp[4][8];
; #pragma unroll
;           for (int fb = 0; fb < 4; ++fb)
; #pragma unroll
;             for (int i = 0; i < 8; ++i) bp[fb][i] = pack2(acc[fb][2 * i], acc[fb][2 * i + 1]);
;           zero4(acc);
;           gemm_main<4, 1>((const u16*)(ws + OFF_WG) + ((size_t)n * 1024 + ft * 256) * 1024, 1024, (const u16*)(ws + OFF_H) + (size_t)tt * 128 * 1024, 1024, 16, acc, lds);
	v_add_u32_e32 v195, 0xc000, v186
	ds_read_b128 v[180:183], v195 offset:32768
	v_add_u32_e32 v194, 0xc000, v14
	ds_read_b128 v[238:241], v194
	ds_read_b128 v[242:245], v194 offset:4096
	ds_read_b128 v[246:249], v194 offset:8192
	ds_read_b128 v[250:253], v194 offset:12288
	s_add_u32 m0, s33, 0x0
	v_lshl_add_u64 v[2:3], v[2:3], 0, s[84:85]
	global_load_lds_dwordx4 v[2:3], off
	s_add_u32 m0, s33, 0x2000
	v_lshl_add_u64 v[6:7], v[6:7], 0, s[84:85]
	global_load_lds_dwordx4 v[6:7], off
	s_add_u32 m0, s33, 0x4000
	v_lshl_add_u64 v[8:9], v[8:9], 0, s[84:85]
	global_load_lds_dwordx4 v[8:9], off
	s_add_u32 m0, s33, 0x6000
	v_lshl_add_u64 v[10:11], v[10:11], 0, s[84:85]
	global_load_lds_dwordx4 v[10:11], off
	s_add_u32 m0, s33, 0x8000
	v_lshl_add_u64 v[4:5], v[4:5], 0, s[84:85]
	global_load_lds_dwordx4 v[4:5], off
	s_add_u32 m0, s33, 0xa000
	v_lshl_add_u64 v[12:13], v[12:13], 0, s[84:85]
	global_load_lds_dwordx4 v[12:13], off
	v_add_u32_e32 v195, 0xc000, v189
	ds_read_b128 v[190:193], v195 offset:32768
	v_add_u32_e32 v194, 0xc000, v15
	s_waitcnt lgkmcnt(4)
	v_mfma_f32_32x32x16_bf16 v[112:127], v[238:241], v[180:183], v[112:127]
	ds_read_b128 v[238:241], v194
	s_waitcnt lgkmcnt(4)
	v_mfma_f32_32x32x16_bf16 v[96:111], v[242:245], v[180:183], v[96:111]
	ds_read_b128 v[242:245], v194 offset:4096
	s_waitcnt lgkmcnt(4)
	v_mfma_f32_32x32x16_bf16 v[80:95], v[246:249], v[180:183], v[80:95]
	ds_read_b128 v[246:249], v194 offset:8192
	s_waitcnt lgkmcnt(4)
	v_mfma_f32_32x32x16_bf16 v[64:79], v[250:253], v[180:183], v[64:79]
	ds_read_b128 v[250:253], v194 offset:12288
	v_add_u32_e32 v195, 0xc000, v233
	ds_read_b128 v[180:183], v195 offset:32768
	v_add_u32_e32 v194, 0xc000, v0
	s_waitcnt lgkmcnt(4)
	v_mfma_f32_32x32x16_bf16 v[112:127], v[238:241], v[190:193], v[112:127]
	ds_read_b128 v[238:241], v194
	s_waitcnt lgkmcnt(4)
	v_mfma_f32_32x32x16_bf16 v[96:111], v[242:245], v[190:193], v[96:111]
	ds_read_b128 v[242:245], v194 offset:4096
	s_waitcnt lgkmcnt(4)
	v_mfma_f32_32x32x16_bf16 v[80:95], v[246:249], v[190:193], v[80:95]
	ds_read_b128 v[246:249], v194 offset:8192
	s_waitcnt lgkmcnt(4)
	v_mfma_f32_32x32x16_bf16 v[64:79], v[250:253], v[190:193], v[64:79]
	ds_read_b128 v[250:253], v194 offset:12288
	v_add_u32_e32 v195, 0xc000, v234
	ds_read_b128 v[190:193], v195 offset:32768
	v_add_u32_e32 v194, 0xc000, v184
	s_waitcnt lgkmcnt(4)
	v_mfma_f32_32x32x16_bf16 v[112:127], v[238:241], v[180:183], v[112:127]
	ds_read_b128 v[238:241], v194
	s_waitcnt lgkmcnt(4)
	v_mfma_f32_32x32x16_bf16 v[96:111], v[242:245], v[180:183], v[96:111]
	ds_read_b128 v[242:245], v194 offset:4096
	s_waitcnt lgkmcnt(4)
	v_mfma_f32_32x32x16_bf16 v[80:95], v[246:249], v[180:183], v[80:95]
	ds_read_b128 v[246:249], v194 offset:8192
	s_waitcnt lgkmcnt(4)
	v_mfma_f32_32x32x16_bf16 v[64:79], v[250:253], v[180:183], v[64:79]
	ds_read_b128 v[250:253], v194 offset:12288
	s_waitcnt lgkmcnt(3)
	v_mfma_f32_32x32x16_bf16 v[112:127], v[238:241], v[190:193], v[112:127]
	s_waitcnt lgkmcnt(2)
	v_mfma_f32_32x32x16_bf16 v[96:111], v[242:245], v[190:193], v[96:111]
	s_waitcnt lgkmcnt(1)
	v_mfma_f32_32x32x16_bf16 v[80:95], v[246:249], v[190:193], v[80:95]
	s_waitcnt lgkmcnt(0)
	v_mfma_f32_32x32x16_bf16 v[64:79], v[250:253], v[190:193], v[64:79]
	s_waitcnt vmcnt(6)
	s_barrier
	v_add_u32_e32 v195, 0x18000, v186
	ds_read_b128 v[180:183], v195 offset:32768
	v_add_u32_e32 v194, 0x18000, v14
	ds_read_b128 v[238:241], v194
	ds_read_b128 v[242:245], v194 offset:4096
	ds_read_b128 v[246:249], v194 offset:8192
	ds_read_b128 v[250:253], v194 offset:12288
	s_add_u32 m0, s33, 0xc000
	v_lshl_add_u64 v[2:3], v[2:3], 0, s[84:85]
	global_load_lds_dwordx4 v[2:3], off
	s_add_u32 m0, s33, 0xe000
	v_lshl_add_u64 v[6:7], v[6:7], 0, s[84:85]
	global_load_lds_dwordx4 v[6:7], off
	s_add_u32 m0, s33, 0x10000
	v_lshl_add_u64 v[8:9], v[8:9], 0, s[84:85]
	global_load_lds_dwordx4 v[8:9], off
	s_add_u32 m0, s33, 0x12000
	v_lshl_add_u64 v[10:11], v[10:11], 0, s[84:85]
	global_load_lds_dwordx4 v[10:11], off
	s_add_u32 m0, s33, 0x14000
	v_lshl_add_u64 v[4:5], v[4:5], 0, s[84:85]
	global_load_lds_dwordx4 v[4:5], off
	s_add_u32 m0, s33, 0x16000
	v_lshl_add_u64 v[12:13], v[12:13], 0, s[84:85]
	global_load_lds_dwordx4 v[12:13], off
	v_add_u32_e32 v195, 0x18000, v189
	ds_read_b128 v[190:193], v195 offset:32768
	v_add_u32_e32 v194, 0x18000, v15
	s_waitcnt lgkmcnt(4)
	v_mfma_f32_32x32x16_bf16 v[128:143], v[238:241], v[180:183], 0
	ds_read_b128 v[238:241], v194
	s_waitcnt lgkmcnt(4)
	v_mfma_f32_32x32x16_bf16 v[48:63], v[242:245], v[180:183], 0
	ds_read_b128 v[242:245], v194 offset:4096
	s_waitcnt lgkmcnt(4)
	v_mfma_f32_32x32x16_bf16 v[32:47], v[246:249], v[180:183], 0
	ds_read_b128 v[246:249], v194 offset:8192
	s_waitcnt lgkmcnt(4)
	v_mfma_f32_32x32x16_bf16 v[16:31], v[250:253], v[180:183], 0
	ds_read_b128 v[250:253], v194 offset:12288
	v_add_u32_e32 v195, 0x18000, v233
	ds_read_b128 v[180:183], v195 offset:32768
	v_add_u32_e32 v194, 0x18000, v0
	s_waitcnt lgkmcnt(4)
	v_mfma_f32_32x32x16_bf16 v[128:143], v[238:241], v[190:193], v[128:143]
	ds_read_b128 v[238:241], v194
	s_waitcnt lgkmcnt(4)
	v_mfma_f32_32x32x16_bf16 v[48:63], v[242:245], v[190:193], v[48:63]
	ds_read_b128 v[242:245], v194 offset:4096
	s_waitcnt lgkmcnt(4)
	v_mfma_f32_32x32x16_bf16 v[32:47], v[246:249], v[190:193], v[32:47]
	ds_read_b128 v[246:249], v194 offset:8192
	s_waitcnt lgkmcnt(4)
	v_mfma_f32_32x32x16_bf16 v[16:31], v[250:253], v[190:193], v[16:31]
	ds_read_b128 v[250:253], v194 offset:12288
	v_add_u32_e32 v195, 0x18000, v234
	ds_read_b128 v[190:193], v195 offset:32768
	v_add_u32_e32 v194, 0x18000, v184
	s_waitcnt lgkmcnt(4)
	v_mfma_f32_32x32x16_bf16 v[128:143], v[238:241], v[180:183], v[128:143]
	ds_read_b128 v[238:241], v194
	s_waitcnt lgkmcnt(4)
	v_mfma_f32_32x32x16_bf16 v[48:63], v[242:245], v[180:183], v[48:63]
	ds_read_b128 v[242:245], v194 offset:4096
	s_waitcnt lgkmcnt(4)
	v_mfma_f32_32x32x16_bf16 v[32:47], v[246:249], v[180:183], v[32:47]
	ds_read_b128 v[246:249], v194 offset:8192
	s_waitcnt lgkmcnt(4)
	v_mfma_f32_32x32x16_bf16 v[16:31], v[250:253], v[180:183], v[16:31]
	ds_read_b128 v[250:253], v194 offset:12288
	s_waitcnt lgkmcnt(3)
	v_mfma_f32_32x32x16_bf16 v[128:143], v[238:241], v[190:193], v[128:143]
	s_waitcnt lgkmcnt(2)
	v_mfma_f32_32x32x16_bf16 v[48:63], v[242:245], v[190:193], v[48:63]
	s_waitcnt lgkmcnt(1)
	v_mfma_f32_32x32x16_bf16 v[32:47], v[246:249], v[190:193], v[32:47]
	s_waitcnt lgkmcnt(0)
	v_mfma_f32_32x32x16_bf16 v[16:31], v[250:253], v[190:193], v[16:31]
	s_waitcnt vmcnt(6)
	s_barrier
; DI f32x16 mfma(bf16x8 a, bf16x8 b, f32x16 c) { return __builtin_amdgcn_mfma_f32_32x32x16_bf16(a, b, c, 0, 0, 0); }
;     ...
;   __syncthreads();
;   DMA_ISSUE(0, 0)
;   asm volatile("s_waitcnt vmcnt(0)" ::: "memory");
;   __builtin_amdgcn_s_barrier();
;   for (int kt = 0; kt < nk; ++kt) {
;     const char* cur = lds + (kt & 1) * DBUF;
;     if (kt + 1 < nk) DMA_ISSUE((kt + 1) & 1, kt + 1)
; #pragma unroll(NTB == 1 ? 2 : 4)
;     for (int s = 0; s < 4; ++s) {
;       const int ro = ((2 * s + hh) ^ xr) * 16;
;       bf16x8 bfr[NTB];
; #pragma unroll
;       for (int tb = 0; tb < NTB; ++tb) bfr[tb] = *(const bf16x8*)(cur + bbase + tb * 32 * DROW + ro);
; #pragma unroll
;       for (int fb = 0; fb < NFB; ++fb) {
;         const bf16x8 afr = *(const bf16x8*)(cur + abase + fb * 32 * DROW + ro);
; #pragma unroll
;         for (int tb = 0; tb < NTB; ++tb) acc[tb * NFB + fb] = mfma(afr, bfr[tb], acc[tb * NFB + fb]);
;       }
;     }
;     asm volatile("s_waitcnt vmcnt(0) lgkmcnt(0)" ::: "memory");
;     __builtin_amdgcn_s_barrier();
	ds_read_b128 v[180:183], v186 offset:32768
	ds_read_b128 v[238:241], v14
	ds_read_b128 v[242:245], v14 offset:4096
	ds_read_b128 v[246:249], v14 offset:8192
	ds_read_b128 v[250:253], v14 offset:12288
	s_add_u32 m0, s33, 0x18000
	v_lshl_add_u64 v[2:3], v[2:3], 0, s[84:85]
	global_load_lds_dwordx4 v[2:3], off
	s_add_u32 m0, s33, 0x1a000
	v_lshl_add_u64 v[6:7], v[6:7], 0, s[84:85]
	global_load_lds_dwordx4 v[6:7], off
	s_add_u32 m0, s33, 0x1c000
	v_lshl_add_u64 v[8:9], v[8:9], 0, s[84:85]
	global_load_lds_dwordx4 v[8:9], off
	s_add_u32 m0, s33, 0x1e000
	v_lshl_add_u64 v[10:11], v[10:11], 0, s[84:85]
	global_load_lds_dwordx4 v[10:11], off
	s_add_u32 m0, s33, 0x20000
	v_lshl_add_u64 v[4:5], v[4:5], 0, s[84:85]
	global_load_lds_dwordx4 v[4:5], off
	s_add_u32 m0, s33, 0x22000
	v_lshl_add_u64 v[12:13], v[12:13], 0, s[84:85]
	global_load_lds_dwordx4 v[12:13], off
	ds_read_b128 v[190:193], v189 offset:32768
	s_waitcnt lgkmcnt(4)
	v_mfma_f32_32x32x16_bf16 v[128:143], v[238:241], v[180:183], v[128:143]
	ds_read_b128 v[238:241], v15
	s_waitcnt lgkmcnt(4)
	v_mfma_f32_32x32x16_bf16 v[48:63], v[242:245], v[180:183], v[48:63]
	ds_read_b128 v[242:245], v15 offset:4096
	s_waitcnt lgkmcnt(4)
	v_mfma_f32_32x32x16_bf16 v[32:47], v[246:249], v[180:183], v[32:47]
	ds_read_b128 v[246:249], v15 offset:8192
	s_waitcnt lgkmcnt(4)
	v_mfma_f32_32x32x16_bf16 v[16:31], v[250:253], v[180:183], v[16:31]
	ds_read_b128 v[250:253], v15 offset:12288
	ds_read_b128 v[180:183], v233 offset:32768
	s_waitcnt lgkmcnt(4)
	v_mfma_f32_32x32x16_bf16 v[128:143], v[238:241], v[190:193], v[128:143]
	ds_read_b128 v[238:241], v0
	s_waitcnt lgkmcnt(4)
	v_mfma_f32_32x32x16_bf16 v[48:63], v[242:245], v[190:193], v[48:63]
	ds_read_b128 v[242:245], v0 offset:4096
	s_waitcnt lgkmcnt(4)
	v_mfma_f32_32x32x16_bf16 v[32:47], v[246:249], v[190:193], v[32:47]
	ds_read_b128 v[246:249], v0 offset:8192
	s_waitcnt lgkmcnt(4)
	v_mfma_f32_32x32x16_bf16 v[16:31], v[250:253], v[190:193], v[16:31]
	ds_read_b128 v[250:253], v0 offset:12288
	ds_read_b128 v[190:193], v234 offset:32768
	s_waitcnt lgkmcnt(4)
	v_mfma_f32_32x32x16_bf16 v[128:143], v[238:241], v[180:183], v[128:143]
	ds_read_b128 v[238:241], v184
	s_waitcnt lgkmcnt(4)
	v_mfma_f32_32x32x16_bf16 v[48:63], v[242:245], v[180:183], v[48:63]
	ds_read_b128 v[242:245], v184 offset:4096
	s_waitcnt lgkmcnt(4)
	v_mfma_f32_32x32x16_bf16 v[32:47], v[246:249], v[180:183], v[32:47]
	ds_read_b128 v[246:249], v184 offset:8192
	s_waitcnt lgkmcnt(4)
	v_mfma_f32_32x32x16_bf16 v[16:31], v[250:253], v[180:183], v[16:31]
	ds_read_b128 v[250:253], v184 offset:12288
	s_waitcnt lgkmcnt(3)
	v_mfma_f32_32x32x16_bf16 v[128:143], v[238:241], v[190:193], v[128:143]
	s_waitcnt lgkmcnt(2)
	v_mfma_f32_32x32x16_bf16 v[48:63], v[242:245], v[190:193], v[48:63]
	s_waitcnt lgkmcnt(1)
	v_mfma_f32_32x32x16_bf16 v[32:47], v[246:249], v[190:193], v[32:47]
	s_waitcnt lgkmcnt(0)
	v_mfma_f32_32x32x16_bf16 v[16:31], v[250:253], v[190:193], v[16:31]
	s_waitcnt vmcnt(6)
	s_barrier
	v_add_u32_e32 v195, 0xc000, v186
	ds_read_b128 v[180:183], v195 offset:32768
	v_add_u32_e32 v194, 0xc000, v14
	ds_read_b128 v[238:241], v194
	ds_read_b128 v[242:245], v194 offset:4096
	ds_read_b128 v[246:249], v194 offset:8192
	ds_read_b128 v[250:253], v194 offset:12288
	s_add_u32 m0, s33, 0x0
	v_lshl_add_u64 v[2:3], v[2:3], 0, s[84:85]
	global_load_lds_dwordx4 v[2:3], off
	s_add_u32 m0, s33, 0x2000
	v_lshl_add_u64 v[6:7], v[6:7], 0, s[84:85]
	global_load_lds_dwordx4 v[6:7], off
	s_add_u32 m0, s33, 0x4000
	v_lshl_add_u64 v[8:9], v[8:9], 0, s[84:85]
	global_load_lds_dwordx4 v[8:9], off
	s_add_u32 m0, s33, 0x6000
	v_lshl_add_u64 v[10:11], v[10:11], 0, s[84:85]
	global_load_lds_dwordx4 v[10:11], off
	s_add_u32 m0, s33, 0x8000
	v_lshl_add_u64 v[4:5], v[4:5], 0, s[84:85]
	global_load_lds_dwordx4 v[4:5], off
	s_add_u32 m0, s33, 0xa000
	v_lshl_add_u64 v[12:13], v[12:13], 0, s[84:85]
	global_load_lds_dwordx4 v[12:13], off
	v_add_u32_e32 v195, 0xc000, v189
	ds_read_b128 v[190:193], v195 offset:32768
	v_add_u32_e32 v194, 0xc000, v15
	s_waitcnt lgkmcnt(4)
	v_mfma_f32_32x32x16_bf16 v[128:143], v[238:241], v[180:183], v[128:143]
	ds_read_b128 v[238:241], v194
	s_waitcnt lgkmcnt(4)
	v_mfma_f32_32x32x16_bf16 v[48:63], v[242:245], v[180:183], v[48:63]
	ds_read_b128 v[242:245], v194 offset:4096
	s_waitcnt lgkmcnt(4)
	v_mfma_f32_32x32x16_bf16 v[32:47], v[246:249], v[180:183], v[32:47]
	ds_read_b128 v[246:249], v194 offset:8192
	s_waitcnt lgkmcnt(4)
	v_mfma_f32_32x32x16_bf16 v[16:31], v[250:253], v[180:183], v[16:31]
	ds_read_b128 v[250:253], v194 offset:12288
	v_add_u32_e32 v195, 0xc000, v233
	ds_read_b128 v[180:183], v195 offset:32768
	v_add_u32_e32 v194, 0xc000, v0
	s_waitcnt lgkmcnt(4)
	v_mfma_f32_32x32x16_bf16 v[128:143], v[238:241], v[190:193], v[128:143]
	ds_read_b128 v[238:241], v194
	s_waitcnt lgkmcnt(4)
	v_mfma_f32_32x32x16_bf16 v[48:63], v[242:245], v[190:193], v[48:63]
	ds_read_b128 v[242:245], v194 offset:4096
	s_waitcnt lgkmcnt(4)
	v_mfma_f32_32x32x16_bf16 v[32:47], v[246:249], v[190:193], v[32:47]
	ds_read_b128 v[246:249], v194 offset:8192
	s_waitcnt lgkmcnt(4)
	v_mfma_f32_32x32x16_bf16 v[16:31], v[250:253], v[190:193], v[16:31]
	ds_read_b128 v[250:253], v194 offset:12288
	v_add_u32_e32 v195, 0xc000, v234
	ds_read_b128 v[190:193], v195 offset:32768
	v_add_u32_e32 v194, 0xc000, v184
	s_waitcnt lgkmcnt(4)
	v_mfma_f32_32x32x16_bf16 v[128:143], v[238:241], v[180:183], v[128:143]
	ds_read_b128 v[238:241], v194
	s_waitcnt lgkmcnt(4)
	v_mfma_f32_32x32x16_bf16 v[48:63], v[242:245], v[180:183], v[48:63]
	ds_read_b128 v[242:245], v194 offset:4096
	s_waitcnt lgkmcnt(4)
	v_mfma_f32_32x32x16_bf16 v[32:47], v[246:249], v[180:183], v[32:47]
	ds_read_b128 v[246:249], v194 offset:8192
	s_waitcnt lgkmcnt(4)
	v_mfma_f32_32x32x16_bf16 v[16:31], v[250:253], v[180:183], v[16:31]
	ds_read_b128 v[250:253], v194 offset:12288
	s_waitcnt lgkmcnt(3)
	v_mfma_f32_32x32x16_bf16 v[128:143], v[238:241], v[190:193], v[128:143]
	s_waitcnt lgkmcnt(2)
	v_mfma_f32_32x32x16_bf16 v[48:63], v[242:245], v[190:193], v[48:63]
	s_waitcnt lgkmcnt(1)
	v_mfma_f32_32x32x16_bf16 v[32:47], v[246:249], v[190:193], v[32:47]
	s_waitcnt lgkmcnt(0)
	v_mfma_f32_32x32x16_bf16 v[16:31], v[250:253], v[190:193], v[16:31]
	s_waitcnt vmcnt(6)
	s_barrier
; DI f32x16 mfma(bf16x8 a, bf16x8 b, f32x16 c) { return __builtin_amdgcn_mfma_f32_32x32x16_bf16(a, b, c, 0, 0, 0); }
;     ...
;   __syncthreads();
;   DMA_ISSUE(0, 0)
;   asm volatile("s_waitcnt vmcnt(0)" ::: "memory");
;   __builtin_amdgcn_s_barrier();
;   for (int kt = 0; kt < nk; ++kt) {
;     const char* cur = lds + (kt & 1) * DBUF;
;     if (kt + 1 < nk) DMA_ISSUE((kt + 1) & 1, kt + 1)
; #pragma unroll(NTB == 1 ? 2 : 4)
;     for (int s = 0; s < 4; ++s) {
;       const int ro = ((2 * s + hh) ^ xr) * 16;
;       bf16x8 bfr[NTB];
; #pragma unroll
;       for (int tb = 0; tb < NTB; ++tb) bfr[tb] = *(const bf16x8*)(cur + bbase + tb * 32 * DROW + ro);
; #pragma unroll
;       for (int fb = 0; fb < NFB; ++fb) {
;         const bf16x8 afr = *(const bf16x8*)(cur + abase + fb * 32 * DROW + ro);
; #pragma unroll
;         for (int tb = 0; tb < NTB; ++tb) acc[tb * NFB + fb] = mfma(afr, bfr[tb], acc[tb * NFB + fb]);
;       }
;     }
;     asm volatile("s_waitcnt vmcnt(0) lgkmcnt(0)" ::: "memory");
;     __builtin_amdgcn_s_barrier();
	v_add_u32_e32 v195, 0x18000, v186
	ds_read_b128 v[180:183], v195 offset:32768
	v_add_u32_e32 v194, 0x18000, v14
	ds_read_b128 v[238:241], v194
	ds_read_b128 v[242:245], v194 offset:4096
	ds_read_b128 v[246:249], v194 offset:8192
	ds_read_b128 v[250:253], v194 offset:12288
	s_add_u32 m0, s33, 0xc000
	v_lshl_add_u64 v[2:3], v[2:3], 0, s[84:85]
	global_load_lds_dwordx4 v[2:3], off
	s_add_u32 m0, s33, 0xe000
	v_lshl_add_u64 v[6:7], v[6:7], 0, s[84:85]
	global_load_lds_dwordx4 v[6:7], off
	s_add_u32 m0, s33, 0x10000
	v_lshl_add_u64 v[8:9], v[8:9], 0, s[84:85]
	global_load_lds_dwordx4 v[8:9], off
	s_add_u32 m0, s33, 0x12000
	v_lshl_add_u64 v[10:11], v[10:11], 0, s[84:85]
	global_load_lds_dwordx4 v[10:11], off
	s_add_u32 m0, s33, 0x14000
	v_lshl_add_u64 v[4:5], v[4:5], 0, s[84:85]
	global_load_lds_dwordx4 v[4:5], off
	s_add_u32 m0, s33, 0x16000
	v_lshl_add_u64 v[12:13], v[12:13], 0, s[84:85]
	global_load_lds_dwordx4 v[12:13], off
	v_add_u32_e32 v195, 0x18000, v189
	ds_read_b128 v[190:193], v195 offset:32768
	v_add_u32_e32 v194, 0x18000, v15
	s_waitcnt lgkmcnt(4)
	v_mfma_f32_32x32x16_bf16 v[128:143], v[238:241], v[180:183], v[128:143]
	ds_read_b128 v[238:241], v194
	s_waitcnt lgkmcnt(4)
	v_mfma_f32_32x32x16_bf16 v[48:63], v[242:245], v[180:183], v[48:63]
	ds_read_b128 v[242:245], v194 offset:4096
	s_waitcnt lgkmcnt(4)
	v_mfma_f32_32x32x16_bf16 v[32:47], v[246:249], v[180:183], v[32:47]
	ds_read_b128 v[246:249], v194 offset:8192
	s_waitcnt lgkmcnt(4)
	v_mfma_f32_32x32x16_bf16 v[16:31], v[250:253], v[180:183], v[16:31]
	ds_read_b128 v[250:253], v194 offset:12288
	v_add_u32_e32 v195, 0x18000, v233
	ds_read_b128 v[180:183], v195 offset:32768
	v_add_u32_e32 v194, 0x18000, v0
	s_waitcnt lgkmcnt(4)
	v_mfma_f32_32x32x16_bf16 v[128:143], v[238:241], v[190:193], v[128:143]
	ds_read_b128 v[238:241], v194
	s_waitcnt lgkmcnt(4)
	v_mfma_f32_32x32x16_bf16 v[48:63], v[242:245], v[190:193], v[48:63]
	ds_read_b128 v[242:245], v194 offset:4096
	s_waitcnt lgkmcnt(4)
	v_mfma_f32_32x32x16_bf16 v[32:47], v[246:249], v[190:193], v[32:47]
	ds_read_b128 v[246:249], v194 offset:8192
	s_waitcnt lgkmcnt(4)
	v_mfma_f32_32x32x16_bf16 v[16:31], v[250:253], v[190:193], v[16:31]
	ds_read_b128 v[250:253], v194 offset:12288
	v_add_u32_e32 v195, 0x18000, v234
	ds_read_b128 v[190:193], v195 offset:32768
	v_add_u32_e32 v194, 0x18000, v184
	s_waitcnt lgkmcnt(4)
	v_mfma_f32_32x32x16_bf16 v[128:143], v[238:241], v[180:183], v[128:143]
	ds_read_b128 v[238:241], v194
	s_waitcnt lgkmcnt(4)
	v_mfma_f32_32x32x16_bf16 v[48:63], v[242:245], v[180:183], v[48:63]
	ds_read_b128 v[242:245], v194 offset:4096
	s_waitcnt lgkmcnt(4)
	v_mfma_f32_32x32x16_bf16 v[32:47], v[246:249], v[180:183], v[32:47]
	ds_read_b128 v[246:249], v194 offset:8192
	s_waitcnt lgkmcnt(4)
	v_mfma_f32_32x32x16_bf16 v[16:31], v[250:253], v[180:183], v[16:31]
	ds_read_b128 v[250:253], v194 offset:12288
	s_waitcnt lgkmcnt(3)
	v_mfma_f32_32x32x16_bf16 v[128:143], v[238:241], v[190:193], v[128:143]
	s_waitcnt lgkmcnt(2)
	v_mfma_f32_32x32x16_bf16 v[48:63], v[242:245], v[190:193], v[48:63]
	s_waitcnt lgkmcnt(1)
	v_mfma_f32_32x32x16_bf16 v[32:47], v[246:249], v[190:193], v[32:47]
	s_waitcnt lgkmcnt(0)
	v_mfma_f32_32x32x16_bf16 v[16:31], v[250:253], v[190:193], v[16:31]
	s_waitcnt vmcnt(6)
	s_barrier
	ds_read_b128 v[180:183], v186 offset:32768
	ds_read_b128 v[238:241], v14
	ds_read_b128 v[242:245], v14 offset:4096
	ds_read_b128 v[246:249], v14 offset:8192
	ds_read_b128 v[250:253], v14 offset:12288
	s_add_u32 m0, s33, 0x18000
	v_lshl_add_u64 v[2:3], v[2:3], 0, s[84:85]
	global_load_lds_dwordx4 v[2:3], off
	s_add_u32 m0, s33, 0x1a000
	v_lshl_add_u64 v[6:7], v[6:7], 0, s[84:85]
	global_load_lds_dwordx4 v[6:7], off
	s_add_u32 m0, s33, 0x1c000
	v_lshl_add_u64 v[8:9], v[8:9], 0, s[84:85]
	global_load_lds_dwordx4 v[8:9], off
	s_add_u32 m0, s33, 0x1e000
	v_lshl_add_u64 v[10:11], v[10:11], 0, s[84:85]
	global_load_lds_dwordx4 v[10:11], off
	s_add_u32 m0, s33, 0x20000
	v_lshl_add_u64 v[4:5], v[4:5], 0, s[84:85]
	global_load_lds_dwordx4 v[4:5], off
	s_add_u32 m0, s33, 0x22000
	v_lshl_add_u64 v[12:13], v[12:13], 0, s[84:85]
	global_load_lds_dwordx4 v[12:13], off
	ds_read_b128 v[190:193], v189 offset:32768
	s_waitcnt lgkmcnt(4)
	v_mfma_f32_32x32x16_bf16 v[128:143], v[238:241], v[180:183], v[128:143]
	ds_read_b128 v[238:241], v15
	s_waitcnt lgkmcnt(4)
	v_mfma_f32_32x32x16_bf16 v[48:63], v[242:245], v[180:183], v[48:63]
	ds_read_b128 v[242:245], v15 offset:4096
	s_waitcnt lgkmcnt(4)
	v_mfma_f32_32x32x16_bf16 v[32:47], v[246:249], v[180:183], v[32:47]
	ds_read_b128 v[246:249], v15 offset:8192
	s_waitcnt lgkmcnt(4)
	v_mfma_f32_32x32x16_bf16 v[16:31], v[250:253], v[180:183], v[16:31]
	ds_read_b128 v[250:253], v15 offset:12288
	ds_read_b128 v[180:183], v233 offset:32768
	s_waitcnt lgkmcnt(4)
	v_mfma_f32_32x32x16_bf16 v[128:143], v[238:241], v[190:193], v[128:143]
	ds_read_b128 v[238:241], v0
	s_waitcnt lgkmcnt(4)
	v_mfma_f32_32x32x16_bf16 v[48:63], v[242:245], v[190:193], v[48:63]
	ds_read_b128 v[242:245], v0 offset:4096
	s_waitcnt lgkmcnt(4)
	v_mfma_f32_32x32x16_bf16 v[32:47], v[246:249], v[190:193], v[32:47]
	ds_read_b128 v[246:249], v0 offset:8192
	s_waitcnt lgkmcnt(4)
	v_mfma_f32_32x32x16_bf16 v[16:31], v[250:253], v[190:193], v[16:31]
	ds_read_b128 v[250:253], v0 offset:12288
	ds_read_b128 v[190:193], v234 offset:32768
	s_waitcnt lgkmcnt(4)
	v_mfma_f32_32x32x16_bf16 v[128:143], v[238:241], v[180:183], v[128:143]
	ds_read_b128 v[238:241], v184
	s_waitcnt lgkmcnt(4)
	v_mfma_f32_32x32x16_bf16 v[48:63], v[242:245], v[180:183], v[48:63]
	ds_read_b128 v[242:245], v184 offset:4096
	s_waitcnt lgkmcnt(4)
	v_mfma_f32_32x32x16_bf16 v[32:47], v[246:249], v[180:183], v[32:47]
	ds_read_b128 v[246:249], v184 offset:8192
	s_waitcnt lgkmcnt(4)
	v_mfma_f32_32x32x16_bf16 v[16:31], v[250:253], v[180:183], v[16:31]
	ds_read_b128 v[250:253], v184 offset:12288
	s_waitcnt lgkmcnt(3)
	v_mfma_f32_32x32x16_bf16 v[128:143], v[238:241], v[190:193], v[128:143]
	s_waitcnt lgkmcnt(2)
	v_mfma_f32_32x32x16_bf16 v[48:63], v[242:245], v[190:193], v[48:63]
	s_waitcnt lgkmcnt(1)
	v_mfma_f32_32x32x16_bf16 v[32:47], v[246:249], v[190:193], v[32:47]
	s_waitcnt lgkmcnt(0)
	v_mfma_f32_32x32x16_bf16 v[16:31], v[250:253], v[190:193], v[16:31]
	s_waitcnt vmcnt(6)
	s_barrier
; DI f32x16 mfma(bf16x8 a, bf16x8 b, f32x16 c) { return __builtin_amdgcn_mfma_f32_32x32x16_bf16(a, b, c, 0, 0, 0); }
;     ...
;   __syncthreads();
;   DMA_ISSUE(0, 0)
;   asm volatile("s_waitcnt vmcnt(0)" ::: "memory");
;   __builtin_amdgcn_s_barrier();
;   for (int kt = 0; kt < nk; ++kt) {
;     const char* cur = lds + (kt & 1) * DBUF;
;     if (kt + 1 < nk) DMA_ISSUE((kt + 1) & 1, kt + 1)
; #pragma unroll(NTB == 1 ? 2 : 4)
;     for (int s = 0; s < 4; ++s) {
;       const int ro = ((2 * s + hh) ^ xr) * 16;
;       bf16x8 bfr[NTB];
; #pragma unroll
;       for (int tb = 0; tb < NTB; ++tb) bfr[tb] = *(const bf16x8*)(cur + bbase + tb * 32 * DROW + ro);
; #pragma unroll
;       for (int fb = 0; fb < NFB; ++fb) {
;         const bf16x8 afr = *(const bf16x8*)(cur + abase + fb * 32 * DROW + ro);
; #pragma unroll
;         for (int tb = 0; tb < NTB; ++tb) acc[tb * NFB + fb] = mfma(afr, bfr[tb], acc[tb * NFB + fb]);
;       }
;     }
;     asm volatile("s_waitcnt vmcnt(0) lgkmcnt(0)" ::: "memory");
;     __builtin_amdgcn_s_barrier();
	v_add_u32_e32 v195, 0xc000, v186
	ds_read_b128 v[180:183], v195 offset:32768
	v_add_u32_e32 v194, 0xc000, v14
	ds_read_b128 v[238:241], v194
	ds_read_b128 v[242:245], v194 offset:4096
	ds_read_b128 v[246:249], v194 offset:8192
	ds_read_b128 v[250:253], v194 offset:12288
	s_add_u32 m0, s33, 0x0
	v_lshl_add_u64 v[2:3], v[2:3], 0, s[84:85]
	global_load_lds_dwordx4 v[2:3], off
	s_add_u32 m0, s33, 0x2000
	v_lshl_add_u64 v[6:7], v[6:7], 0, s[84:85]
	global_load_lds_dwordx4 v[6:7], off
	s_add_u32 m0, s33, 0x4000
	v_lshl_add_u64 v[8:9], v[8:9], 0, s[84:85]
	global_load_lds_dwordx4 v[8:9], off
	s_add_u32 m0, s33, 0x6000
	v_lshl_add_u64 v[10:11], v[10:11], 0, s[84:85]
	global_load_lds_dwordx4 v[10:11], off
	s_add_u32 m0, s33, 0x8000
	v_lshl_add_u64 v[4:5], v[4:5], 0, s[84:85]
	global_load_lds_dwordx4 v[4:5], off
	s_add_u32 m0, s33, 0xa000
	v_lshl_add_u64 v[12:13], v[12:13], 0, s[84:85]
	global_load_lds_dwordx4 v[12:13], off
	v_add_u32_e32 v195, 0xc000, v189
	ds_read_b128 v[190:193], v195 offset:32768
	v_add_u32_e32 v194, 0xc000, v15
	s_waitcnt lgkmcnt(4)
	v_mfma_f32_32x32x16_bf16 v[128:143], v[238:241], v[180:183], v[128:143]
	ds_read_b128 v[238:241], v194
	s_waitcnt lgkmcnt(4)
	v_mfma_f32_32x32x16_bf16 v[48:63], v[242:245], v[180:183], v[48:63]
	ds_read_b128 v[242:245], v194 offset:4096
	s_waitcnt lgkmcnt(4)
	v_mfma_f32_32x32x16_bf16 v[32:47], v[246:249], v[180:183], v[32:47]
	ds_read_b128 v[246:249], v194 offset:8192
	s_waitcnt lgkmcnt(4)
	v_mfma_f32_32x32x16_bf16 v[16:31], v[250:253], v[180:183], v[16:31]
	ds_read_b128 v[250:253], v194 offset:12288
	v_add_u32_e32 v195, 0xc000, v233
	ds_read_b128 v[180:183], v195 offset:32768
	v_add_u32_e32 v194, 0xc000, v0
	s_waitcnt lgkmcnt(4)
	v_mfma_f32_32x32x16_bf16 v[128:143], v[238:241], v[190:193], v[128:143]
	ds_read_b128 v[238:241], v194
	s_waitcnt lgkmcnt(4)
	v_mfma_f32_32x32x16_bf16 v[48:63], v[242:245], v[190:193], v[48:63]
	ds_read_b128 v[242:245], v194 offset:4096
	s_waitcnt lgkmcnt(4)
	v_mfma_f32_32x32x16_bf16 v[32:47], v[246:249], v[190:193], v[32:47]
	ds_read_b128 v[246:249], v194 offset:8192
	s_waitcnt lgkmcnt(4)
	v_mfma_f32_32x32x16_bf16 v[16:31], v[250:253], v[190:193], v[16:31]
	ds_read_b128 v[250:253], v194 offset:12288
	v_add_u32_e32 v195, 0xc000, v234
	ds_read_b128 v[190:193], v195 offset:32768
	v_add_u32_e32 v194, 0xc000, v184
	s_waitcnt lgkmcnt(4)
	v_mfma_f32_32x32x16_bf16 v[128:143], v[238:241], v[180:183], v[128:143]
	ds_read_b128 v[238:241], v194
	s_waitcnt lgkmcnt(4)
	v_mfma_f32_32x32x16_bf16 v[48:63], v[242:245], v[180:183], v[48:63]
	ds_read_b128 v[242:245], v194 offset:4096
	s_waitcnt lgkmcnt(4)
	v_mfma_f32_32x32x16_bf16 v[32:47], v[246:249], v[180:183], v[32:47]
	ds_read_b128 v[246:249], v194 offset:8192
	s_waitcnt lgkmcnt(4)
	v_mfma_f32_32x32x16_bf16 v[16:31], v[250:253], v[180:183], v[16:31]
	ds_read_b128 v[250:253], v194 offset:12288
	s_waitcnt lgkmcnt(3)
	v_mfma_f32_32x32x16_bf16 v[128:143], v[238:241], v[190:193], v[128:143]
	s_waitcnt lgkmcnt(2)
	v_mfma_f32_32x32x16_bf16 v[48:63], v[242:245], v[190:193], v[48:63]
	s_waitcnt lgkmcnt(1)
	v_mfma_f32_32x32x16_bf16 v[32:47], v[246:249], v[190:193], v[32:47]
	s_waitcnt lgkmcnt(0)
	v_mfma_f32_32x32x16_bf16 v[16:31], v[250:253], v[190:193], v[16:31]
	s_waitcnt vmcnt(6)
	s_barrier
	v_add_u32_e32 v195, 0x18000, v186
	ds_read_b128 v[180:183], v195 offset:32768
	v_add_u32_e32 v194, 0x18000, v14
	ds_read_b128 v[238:241], v194
	ds_read_b128 v[242:245], v194 offset:4096
	ds_read_b128 v[246:249], v194 offset:8192
	ds_read_b128 v[250:253], v194 offset:12288
	s_add_u32 m0, s33, 0xc000
	v_lshl_add_u64 v[2:3], v[2:3], 0, s[84:85]
	global_load_lds_dwordx4 v[2:3], off
	s_add_u32 m0, s33, 0xe000
	v_lshl_add_u64 v[6:7], v[6:7], 0, s[84:85]
	global_load_lds_dwordx4 v[6:7], off
	s_add_u32 m0, s33, 0x10000
	v_lshl_add_u64 v[8:9], v[8:9], 0, s[84:85]
	global_load_lds_dwordx4 v[8:9], off
	s_add_u32 m0, s33, 0x12000
	v_lshl_add_u64 v[10:11], v[10:11], 0, s[84:85]
	global_load_lds_dwordx4 v[10:11], off
	s_add_u32 m0, s33, 0x14000
	v_lshl_add_u64 v[4:5], v[4:5], 0, s[84:85]
	global_load_lds_dwordx4 v[4:5], off
	s_add_u32 m0, s33, 0x16000
	v_lshl_add_u64 v[12:13], v[12:13], 0, s[84:85]
	global_load_lds_dwordx4 v[12:13], off
	v_add_u32_e32 v195, 0x18000, v189
	ds_read_b128 v[190:193], v195 offset:32768
	v_add_u32_e32 v194, 0x18000, v15
	s_waitcnt lgkmcnt(4)
	v_mfma_f32_32x32x16_bf16 v[128:143], v[238:241], v[180:183], v[128:143]
	ds_read_b128 v[238:241], v194
	s_waitcnt lgkmcnt(4)
	v_mfma_f32_32x32x16_bf16 v[48:63], v[242:245], v[180:183], v[48:63]
	ds_read_b128 v[242:245], v194 offset:4096
	s_waitcnt lgkmcnt(4)
	v_mfma_f32_32x32x16_bf16 v[32:47], v[246:249], v[180:183], v[32:47]
	ds_read_b128 v[246:249], v194 offset:8192
	s_waitcnt lgkmcnt(4)
	v_mfma_f32_32x32x16_bf16 v[16:31], v[250:253], v[180:183], v[16:31]
	ds_read_b128 v[250:253], v194 offset:12288
	v_add_u32_e32 v195, 0x18000, v233
	ds_read_b128 v[180:183], v195 offset:32768
	v_add_u32_e32 v194, 0x18000, v0
	s_waitcnt lgkmcnt(4)
	v_mfma_f32_32x32x16_bf16 v[128:143], v[238:241], v[190:193], v[128:143]
	ds_read_b128 v[238:241], v194
	s_waitcnt lgkmcnt(4)
	v_mfma_f32_32x32x16_bf16 v[48:63], v[242:245], v[190:193], v[48:63]
	ds_read_b128 v[242:245], v194 offset:4096
	s_waitcnt lgkmcnt(4)
	v_mfma_f32_32x32x16_bf16 v[32:47], v[246:249], v[190:193], v[32:47]
	ds_read_b128 v[246:249], v194 offset:8192
	s_waitcnt lgkmcnt(4)
	v_mfma_f32_32x32x16_bf16 v[16:31], v[250:253], v[190:193], v[16:31]
	ds_read_b128 v[250:253], v194 offset:12288
	v_add_u32_e32 v195, 0x18000, v234
	ds_read_b128 v[190:193], v195 offset:32768
	v_add_u32_e32 v194, 0x18000, v184
	s_waitcnt lgkmcnt(4)
	v_mfma_f32_32x32x16_bf16 v[128:143], v[238:241], v[180:183], v[128:143]
	ds_read_b128 v[238:241], v194
	s_waitcnt lgkmcnt(4)
	v_mfma_f32_32x32x16_bf16 v[48:63], v[242:245], v[180:183], v[48:63]
	ds_read_b128 v[242:245], v194 offset:4096
	s_waitcnt lgkmcnt(4)
	v_mfma_f32_32x32x16_bf16 v[32:47], v[246:249], v[180:183], v[32:47]
	ds_read_b128 v[246:249], v194 offset:8192
	s_waitcnt lgkmcnt(4)
	v_mfma_f32_32x32x16_bf16 v[16:31], v[250:253], v[180:183], v[16:31]
	ds_read_b128 v[250:253], v194 offset:12288
	s_waitcnt lgkmcnt(3)
	v_mfma_f32_32x32x16_bf16 v[128:143], v[238:241], v[190:193], v[128:143]
	s_waitcnt lgkmcnt(2)
	v_mfma_f32_32x32x16_bf16 v[48:63], v[242:245], v[190:193], v[48:63]
	s_waitcnt lgkmcnt(1)
	v_mfma_f32_32x32x16_bf16 v[32:47], v[246:249], v[190:193], v[32:47]
	s_waitcnt lgkmcnt(0)
	v_mfma_f32_32x32x16_bf16 v[16:31], v[250:253], v[190:193], v[16:31]
	s_waitcnt vmcnt(6)
	s_barrier
; DI f32x16 mfma(bf16x8 a, bf16x8 b, f32x16 c) { return __builtin_amdgcn_mfma_f32_32x32x16_bf16(a, b, c, 0, 0, 0); }
;     ...
;   __syncthreads();
;   DMA_ISSUE(0, 0)
;   asm volatile("s_waitcnt vmcnt(0)" ::: "memory");
;   __builtin_amdgcn_s_barrier();
;   for (int kt = 0; kt < nk; ++kt) {
;     const char* cur = lds + (kt & 1) * DBUF;
;     if (kt + 1 < nk) DMA_ISSUE((kt + 1) & 1, kt + 1)
; #pragma unroll(NTB == 1 ? 2 : 4)
;     for (int s = 0; s < 4; ++s) {
;       const int ro = ((2 * s + hh) ^ xr) * 16;
;       bf16x8 bfr[NTB];
; #pragma unroll
;       for (int tb = 0; tb < NTB; ++tb) bfr[tb] = *(const bf16x8*)(cur + bbase + tb * 32 * DROW + ro);
; #pragma unroll
;       for (int fb = 0; fb < NFB; ++fb) {
;         const bf16x8 afr = *(const bf16x8*)(cur + abase + fb * 32 * DROW + ro);
; #pragma unroll
;         for (int tb = 0; tb < NTB; ++tb) acc[tb * NFB + fb] = mfma(afr, bfr[tb], acc[tb * NFB + fb]);
;       }
;     }
;     asm volatile("s_waitcnt vmcnt(0) lgkmcnt(0)" ::: "memory");
;     __builtin_amdgcn_s_barrier();
	ds_read_b128 v[180:183], v186 offset:32768
	ds_read_b128 v[238:241], v14
	ds_read_b128 v[242:245], v14 offset:4096
	ds_read_b128 v[246:249], v14 offset:8192
	ds_read_b128 v[250:253], v14 offset:12288
	s_add_u32 m0, s33, 0x18000
	v_lshl_add_u64 v[2:3], v[2:3], 0, s[84:85]
	global_load_lds_dwordx4 v[2:3], off
	s_add_u32 m0, s33, 0x1a000
	v_lshl_add_u64 v[6:7], v[6:7], 0, s[84:85]
	global_load_lds_dwordx4 v[6:7], off
	s_add_u32 m0, s33, 0x1c000
	v_lshl_add_u64 v[8:9], v[8:9], 0, s[84:85]
	global_load_lds_dwordx4 v[8:9], off
	s_add_u32 m0, s33, 0x1e000
	v_lshl_add_u64 v[10:11], v[10:11], 0, s[84:85]
	global_load_lds_dwordx4 v[10:11], off
	s_add_u32 m0, s33, 0x20000
	v_lshl_add_u64 v[4:5], v[4:5], 0, s[84:85]
	global_load_lds_dwordx4 v[4:5], off
	s_add_u32 m0, s33, 0x22000
	v_lshl_add_u64 v[12:13], v[12:13], 0, s[84:85]
	global_load_lds_dwordx4 v[12:13], off
	ds_read_b128 v[190:193], v189 offset:32768
	s_waitcnt lgkmcnt(4)
	v_mfma_f32_32x32x16_bf16 v[128:143], v[238:241], v[180:183], v[128:143]
	ds_read_b128 v[238:241], v15
	s_waitcnt lgkmcnt(4)
	v_mfma_f32_32x32x16_bf16 v[48:63], v[242:245], v[180:183], v[48:63]
	ds_read_b128 v[242:245], v15 offset:4096
	s_waitcnt lgkmcnt(4)
	v_mfma_f32_32x32x16_bf16 v[32:47], v[246:249], v[180:183], v[32:47]
	ds_read_b128 v[246:249], v15 offset:8192
	s_waitcnt lgkmcnt(4)
	v_mfma_f32_32x32x16_bf16 v[16:31], v[250:253], v[180:183], v[16:31]
	ds_read_b128 v[250:253], v15 offset:12288
	ds_read_b128 v[180:183], v233 offset:32768
	s_waitcnt lgkmcnt(4)
	v_mfma_f32_32x32x16_bf16 v[128:143], v[238:241], v[190:193], v[128:143]
	ds_read_b128 v[238:241], v0
	s_waitcnt lgkmcnt(4)
	v_mfma_f32_32x32x16_bf16 v[48:63], v[242:245], v[190:193], v[48:63]
	ds_read_b128 v[242:245], v0 offset:4096
	s_waitcnt lgkmcnt(4)
	v_mfma_f32_32x32x16_bf16 v[32:47], v[246:249], v[190:193], v[32:47]
	ds_read_b128 v[246:249], v0 offset:8192
	s_waitcnt lgkmcnt(4)
	v_mfma_f32_32x32x16_bf16 v[16:31], v[250:253], v[190:193], v[16:31]
	ds_read_b128 v[250:253], v0 offset:12288
	ds_read_b128 v[190:193], v234 offset:32768
	s_waitcnt lgkmcnt(4)
	v_mfma_f32_32x32x16_bf16 v[128:143], v[238:241], v[180:183], v[128:143]
	ds_read_b128 v[238:241], v184
	s_waitcnt lgkmcnt(4)
	v_mfma_f32_32x32x16_bf16 v[48:63], v[242:245], v[180:183], v[48:63]
	ds_read_b128 v[242:245], v184 offset:4096
	s_waitcnt lgkmcnt(4)
	v_mfma_f32_32x32x16_bf16 v[32:47], v[246:249], v[180:183], v[32:47]
	ds_read_b128 v[246:249], v184 offset:8192
	s_waitcnt lgkmcnt(4)
	v_mfma_f32_32x32x16_bf16 v[16:31], v[250:253], v[180:183], v[16:31]
	ds_read_b128 v[250:253], v184 offset:12288
	s_waitcnt lgkmcnt(3)
	v_mfma_f32_32x32x16_bf16 v[128:143], v[238:241], v[190:193], v[128:143]
	s_waitcnt lgkmcnt(2)
	v_mfma_f32_32x32x16_bf16 v[48:63], v[242:245], v[190:193], v[48:63]
	s_waitcnt lgkmcnt(1)
	v_mfma_f32_32x32x16_bf16 v[32:47], v[246:249], v[190:193], v[32:47]
	s_waitcnt lgkmcnt(0)
	v_mfma_f32_32x32x16_bf16 v[16:31], v[250:253], v[190:193], v[16:31]
	s_waitcnt vmcnt(6)
	s_barrier
	v_add_u32_e32 v195, 0xc000, v186
	ds_read_b128 v[180:183], v195 offset:32768
	v_add_u32_e32 v194, 0xc000, v14
	ds_read_b128 v[238:241], v194
	ds_read_b128 v[242:245], v194 offset:4096
	ds_read_b128 v[246:249], v194 offset:8192
	ds_read_b128 v[250:253], v194 offset:12288
	s_add_u32 m0, s33, 0x0
	v_lshl_add_u64 v[2:3], v[2:3], 0, s[84:85]
	global_load_lds_dwordx4 v[2:3], off
	s_add_u32 m0, s33, 0x2000
	v_lshl_add_u64 v[6:7], v[6:7], 0, s[84:85]
	global_load_lds_dwordx4 v[6:7], off
	s_add_u32 m0, s33, 0x4000
	v_lshl_add_u64 v[8:9], v[8:9], 0, s[84:85]
	global_load_lds_dwordx4 v[8:9], off
	s_add_u32 m0, s33, 0x6000
	v_lshl_add_u64 v[10:11], v[10:11], 0, s[84:85]
	global_load_lds_dwordx4 v[10:11], off
	s_add_u32 m0, s33, 0x8000
	v_lshl_add_u64 v[4:5], v[4:5], 0, s[84:85]
	global_load_lds_dwordx4 v[4:5], off
	s_add_u32 m0, s33, 0xa000
	v_lshl_add_u64 v[12:13], v[12:13], 0, s[84:85]
	global_load_lds_dwordx4 v[12:13], off
	v_add_u32_e32 v195, 0xc000, v189
	ds_read_b128 v[190:193], v195 offset:32768
	v_add_u32_e32 v194, 0xc000, v15
	s_waitcnt lgkmcnt(4)
	v_mfma_f32_32x32x16_bf16 v[128:143], v[238:241], v[180:183], v[128:143]
	ds_read_b128 v[238:241], v194
	s_waitcnt lgkmcnt(4)
	v_mfma_f32_32x32x16_bf16 v[48:63], v[242:245], v[180:183], v[48:63]
	ds_read_b128 v[242:245], v194 offset:4096
	s_waitcnt lgkmcnt(4)
	v_mfma_f32_32x32x16_bf16 v[32:47], v[246:249], v[180:183], v[32:47]
	ds_read_b128 v[246:249], v194 offset:8192
	s_waitcnt lgkmcnt(4)
	v_mfma_f32_32x32x16_bf16 v[16:31], v[250:253], v[180:183], v[16:31]
	ds_read_b128 v[250:253], v194 offset:12288
	v_add_u32_e32 v195, 0xc000, v233
	ds_read_b128 v[180:183], v195 offset:32768
	v_add_u32_e32 v194, 0xc000, v0
	s_waitcnt lgkmcnt(4)
	v_mfma_f32_32x32x16_bf16 v[128:143], v[238:241], v[190:193], v[128:143]
	ds_read_b128 v[238:241], v194
	s_waitcnt lgkmcnt(4)
	v_mfma_f32_32x32x16_bf16 v[48:63], v[242:245], v[190:193], v[48:63]
	ds_read_b128 v[242:245], v194 offset:4096
	s_waitcnt lgkmcnt(4)
	v_mfma_f32_32x32x16_bf16 v[32:47], v[246:249], v[190:193], v[32:47]
	ds_read_b128 v[246:249], v194 offset:8192
	s_waitcnt lgkmcnt(4)
	v_mfma_f32_32x32x16_bf16 v[16:31], v[250:253], v[190:193], v[16:31]
	ds_read_b128 v[250:253], v194 offset:12288
	v_add_u32_e32 v195, 0xc000, v234
	ds_read_b128 v[190:193], v195 offset:32768
	v_add_u32_e32 v194, 0xc000, v184
	s_waitcnt lgkmcnt(4)
	v_mfma_f32_32x32x16_bf16 v[128:143], v[238:241], v[180:183], v[128:143]
	ds_read_b128 v[238:241], v194
	s_waitcnt lgkmcnt(4)
	v_mfma_f32_32x32x16_bf16 v[48:63], v[242:245], v[180:183], v[48:63]
	ds_read_b128 v[242:245], v194 offset:4096
	s_waitcnt lgkmcnt(4)
	v_mfma_f32_32x32x16_bf16 v[32:47], v[246:249], v[180:183], v[32:47]
	ds_read_b128 v[246:249], v194 offset:8192
	s_waitcnt lgkmcnt(4)
	v_mfma_f32_32x32x16_bf16 v[16:31], v[250:253], v[180:183], v[16:31]
	ds_read_b128 v[250:253], v194 offset:12288
	s_waitcnt lgkmcnt(3)
	v_mfma_f32_32x32x16_bf16 v[128:143], v[238:241], v[190:193], v[128:143]
	s_waitcnt lgkmcnt(2)
	v_mfma_f32_32x32x16_bf16 v[48:63], v[242:245], v[190:193], v[48:63]
	s_waitcnt lgkmcnt(1)
	v_mfma_f32_32x32x16_bf16 v[32:47], v[246:249], v[190:193], v[32:47]
	s_waitcnt lgkmcnt(0)
	v_mfma_f32_32x32x16_bf16 v[16:31], v[250:253], v[190:193], v[16:31]
	s_waitcnt vmcnt(6)
	s_barrier
; DI f32x16 mfma(bf16x8 a, bf16x8 b, f32x16 c) { return __builtin_amdgcn_mfma_f32_32x32x16_bf16(a, b, c, 0, 0, 0); }
;     ...
;   __syncthreads();
;   DMA_ISSUE(0, 0)
;   asm volatile("s_waitcnt vmcnt(0)" ::: "memory");
;   __builtin_amdgcn_s_barrier();
;   for (int kt = 0; kt < nk; ++kt) {
;     const char* cur = lds + (kt & 1) * DBUF;
;     if (kt + 1 < nk) DMA_ISSUE((kt + 1) & 1, kt + 1)
; #pragma unroll(NTB == 1 ? 2 : 4)
;     for (int s = 0; s < 4; ++s) {
;       const int ro = ((2 * s + hh) ^ xr) * 16;
;       bf16x8 bfr[NTB];
; #pragma unroll
;       for (int tb = 0; tb < NTB; ++tb) bfr[tb] = *(const bf16x8*)(cur + bbase + tb * 32 * DROW + ro);
; #pragma unroll
;       for (int fb = 0; fb < NFB; ++fb) {
;         const bf16x8 afr = *(const bf16x8*)(cur + abase + fb * 32 * DROW + ro);
; #pragma unroll
;         for (int tb = 0; tb < NTB; ++tb) acc[tb * NFB + fb] = mfma(afr, bfr[tb], acc[tb * NFB + fb]);
;       }
;     }
;     asm volatile("s_waitcnt vmcnt(0) lgkmcnt(0)" ::: "memory");
;     __builtin_amdgcn_s_barrier();
	v_add_u32_e32 v195, 0x18000, v186
	ds_read_b128 v[180:183], v195 offset:32768
	v_add_u32_e32 v194, 0x18000, v14
	ds_read_b128 v[238:241], v194
	ds_read_b128 v[242:245], v194 offset:4096
	ds_read_b128 v[246:249], v194 offset:8192
	ds_read_b128 v[250:253], v194 offset:12288
	s_add_u32 m0, s33, 0xc000
	v_lshl_add_u64 v[2:3], v[2:3], 0, s[84:85]
	global_load_lds_dwordx4 v[2:3], off
	s_add_u32 m0, s33, 0xe000
	v_lshl_add_u64 v[6:7], v[6:7], 0, s[84:85]
	global_load_lds_dwordx4 v[6:7], off
	s_add_u32 m0, s33, 0x10000
	v_lshl_add_u64 v[8:9], v[8:9], 0, s[84:85]
	global_load_lds_dwordx4 v[8:9], off
	s_add_u32 m0, s33, 0x12000
	v_lshl_add_u64 v[10:11], v[10:11], 0, s[84:85]
	global_load_lds_dwordx4 v[10:11], off
	s_add_u32 m0, s33, 0x14000
	v_lshl_add_u64 v[4:5], v[4:5], 0, s[84:85]
	global_load_lds_dwordx4 v[4:5], off
	s_add_u32 m0, s33, 0x16000
	v_lshl_add_u64 v[12:13], v[12:13], 0, s[84:85]
	global_load_lds_dwordx4 v[12:13], off
	v_add_u32_e32 v195, 0x18000, v189
	ds_read_b128 v[190:193], v195 offset:32768
	v_add_u32_e32 v194, 0x18000, v15
	s_waitcnt lgkmcnt(4)
	v_mfma_f32_32x32x16_bf16 v[128:143], v[238:241], v[180:183], v[128:143]
	ds_read_b128 v[238:241], v194
	s_waitcnt lgkmcnt(4)
	v_mfma_f32_32x32x16_bf16 v[48:63], v[242:245], v[180:183], v[48:63]
	ds_read_b128 v[242:245], v194 offset:4096
	s_waitcnt lgkmcnt(4)
	v_mfma_f32_32x32x16_bf16 v[32:47], v[246:249], v[180:183], v[32:47]
	ds_read_b128 v[246:249], v194 offset:8192
	s_waitcnt lgkmcnt(4)
	v_mfma_f32_32x32x16_bf16 v[16:31], v[250:253], v[180:183], v[16:31]
	ds_read_b128 v[250:253], v194 offset:12288
	v_add_u32_e32 v195, 0x18000, v233
	ds_read_b128 v[180:183], v195 offset:32768
	v_add_u32_e32 v194, 0x18000, v0
	s_waitcnt lgkmcnt(4)
	v_mfma_f32_32x32x16_bf16 v[128:143], v[238:241], v[190:193], v[128:143]
	ds_read_b128 v[238:241], v194
	s_waitcnt lgkmcnt(4)
	v_mfma_f32_32x32x16_bf16 v[48:63], v[242:245], v[190:193], v[48:63]
	ds_read_b128 v[242:245], v194 offset:4096
	s_waitcnt lgkmcnt(4)
	v_mfma_f32_32x32x16_bf16 v[32:47], v[246:249], v[190:193], v[32:47]
	ds_read_b128 v[246:249], v194 offset:8192
	s_waitcnt lgkmcnt(4)
	v_mfma_f32_32x32x16_bf16 v[16:31], v[250:253], v[190:193], v[16:31]
	ds_read_b128 v[250:253], v194 offset:12288
	v_add_u32_e32 v195, 0x18000, v234
	ds_read_b128 v[190:193], v195 offset:32768
	v_add_u32_e32 v194, 0x18000, v184
	s_waitcnt lgkmcnt(4)
	v_mfma_f32_32x32x16_bf16 v[128:143], v[238:241], v[180:183], v[128:143]
	ds_read_b128 v[238:241], v194
	s_waitcnt lgkmcnt(4)
	v_mfma_f32_32x32x16_bf16 v[48:63], v[242:245], v[180:183], v[48:63]
	ds_read_b128 v[242:245], v194 offset:4096
	s_waitcnt lgkmcnt(4)
	v_mfma_f32_32x32x16_bf16 v[32:47], v[246:249], v[180:183], v[32:47]
	ds_read_b128 v[246:249], v194 offset:8192
	s_waitcnt lgkmcnt(4)
	v_mfma_f32_32x32x16_bf16 v[16:31], v[250:253], v[180:183], v[16:31]
	ds_read_b128 v[250:253], v194 offset:12288
	s_waitcnt lgkmcnt(3)
	v_mfma_f32_32x32x16_bf16 v[128:143], v[238:241], v[190:193], v[128:143]
	s_waitcnt lgkmcnt(2)
	v_mfma_f32_32x32x16_bf16 v[48:63], v[242:245], v[190:193], v[48:63]
	s_waitcnt lgkmcnt(1)
	v_mfma_f32_32x32x16_bf16 v[32:47], v[246:249], v[190:193], v[32:47]
	s_waitcnt lgkmcnt(0)
	v_mfma_f32_32x32x16_bf16 v[16:31], v[250:253], v[190:193], v[16:31]
	s_waitcnt vmcnt(6)
	s_barrier
	ds_read_b128 v[180:183], v186 offset:32768
	ds_read_b128 v[238:241], v14
	ds_read_b128 v[242:245], v14 offset:4096
	ds_read_b128 v[246:249], v14 offset:8192
	ds_read_b128 v[250:253], v14 offset:12288
	s_add_u32 m0, s33, 0x18000
	v_lshl_add_u64 v[2:3], v[2:3], 0, s[84:85]
	global_load_lds_dwordx4 v[2:3], off
	s_add_u32 m0, s33, 0x1a000
	v_lshl_add_u64 v[6:7], v[6:7], 0, s[84:85]
	global_load_lds_dwordx4 v[6:7], off
	s_add_u32 m0, s33, 0x1c000
	v_lshl_add_u64 v[8:9], v[8:9], 0, s[84:85]
	global_load_lds_dwordx4 v[8:9], off
	s_add_u32 m0, s33, 0x1e000
	v_lshl_add_u64 v[10:11], v[10:11], 0, s[84:85]
	global_load_lds_dwordx4 v[10:11], off
	s_add_u32 m0, s33, 0x20000
	v_lshl_add_u64 v[4:5], v[4:5], 0, s[84:85]
	global_load_lds_dwordx4 v[4:5], off
	s_add_u32 m0, s33, 0x22000
	v_lshl_add_u64 v[12:13], v[12:13], 0, s[84:85]
	global_load_lds_dwordx4 v[12:13], off
	ds_read_b128 v[190:193], v189 offset:32768
	s_waitcnt lgkmcnt(4)
	v_mfma_f32_32x32x16_bf16 v[128:143], v[238:241], v[180:183], v[128:143]
	ds_read_b128 v[238:241], v15
	s_waitcnt lgkmcnt(4)
	v_mfma_f32_32x32x16_bf16 v[48:63], v[242:245], v[180:183], v[48:63]
	ds_read_b128 v[242:245], v15 offset:4096
	s_waitcnt lgkmcnt(4)
	v_mfma_f32_32x32x16_bf16 v[32:47], v[246:249], v[180:183], v[32:47]
	ds_read_b128 v[246:249], v15 offset:8192
	s_waitcnt lgkmcnt(4)
	v_mfma_f32_32x32x16_bf16 v[16:31], v[250:253], v[180:183], v[16:31]
	ds_read_b128 v[250:253], v15 offset:12288
	ds_read_b128 v[180:183], v233 offset:32768
	s_waitcnt lgkmcnt(4)
	v_mfma_f32_32x32x16_bf16 v[128:143], v[238:241], v[190:193], v[128:143]
	ds_read_b128 v[238:241], v0
	s_waitcnt lgkmcnt(4)
	v_mfma_f32_32x32x16_bf16 v[48:63], v[242:245], v[190:193], v[48:63]
	ds_read_b128 v[242:245], v0 offset:4096
	s_waitcnt lgkmcnt(4)
	v_mfma_f32_32x32x16_bf16 v[32:47], v[246:249], v[190:193], v[32:47]
	ds_read_b128 v[246:249], v0 offset:8192
	s_waitcnt lgkmcnt(4)
	v_mfma_f32_32x32x16_bf16 v[16:31], v[250:253], v[190:193], v[16:31]
	ds_read_b128 v[250:253], v0 offset:12288
	ds_read_b128 v[190:193], v234 offset:32768
	s_waitcnt lgkmcnt(4)
	v_mfma_f32_32x32x16_bf16 v[128:143], v[238:241], v[180:183], v[128:143]
	ds_read_b128 v[238:241], v184
	s_waitcnt lgkmcnt(4)
	v_mfma_f32_32x32x16_bf16 v[48:63], v[242:245], v[180:183], v[48:63]
	ds_read_b128 v[242:245], v184 offset:4096
	s_waitcnt lgkmcnt(4)
	v_mfma_f32_32x32x16_bf16 v[32:47], v[246:249], v[180:183], v[32:47]
	ds_read_b128 v[246:249], v184 offset:8192
	s_waitcnt lgkmcnt(4)
	v_mfma_f32_32x32x16_bf16 v[16:31], v[250:253], v[180:183], v[16:31]
	ds_read_b128 v[250:253], v184 offset:12288
	s_waitcnt lgkmcnt(3)
	v_mfma_f32_32x32x16_bf16 v[128:143], v[238:241], v[190:193], v[128:143]
	s_waitcnt lgkmcnt(2)
	v_mfma_f32_32x32x16_bf16 v[48:63], v[242:245], v[190:193], v[48:63]
	s_waitcnt lgkmcnt(1)
	v_mfma_f32_32x32x16_bf16 v[32:47], v[246:249], v[190:193], v[32:47]
	s_waitcnt lgkmcnt(0)
	v_mfma_f32_32x32x16_bf16 v[16:31], v[250:253], v[190:193], v[16:31]
	s_waitcnt vmcnt(6)
	s_barrier
; DI f32x16 mfma(bf16x8 a, bf16x8 b, f32x16 c) { return __builtin_amdgcn_mfma_f32_32x32x16_bf16(a, b, c, 0, 0, 0); }
;     ...
;   __syncthreads();
;   DMA_ISSUE(0, 0)
;   asm volatile("s_waitcnt vmcnt(0)" ::: "memory");
;   __builtin_amdgcn_s_barrier();
;   for (int kt = 0; kt < nk; ++kt) {
;     const char* cur = lds + (kt & 1) * DBUF;
;     if (kt + 1 < nk) DMA_ISSUE((kt + 1) & 1, kt + 1)
; #pragma unroll(NTB == 1 ? 2 : 4)
;     for (int s = 0; s < 4; ++s) {
;       const int ro = ((2 * s + hh) ^ xr) * 16;
;       bf16x8 bfr[NTB];
; #pragma unroll
;       for (int tb = 0; tb < NTB; ++tb) bfr[tb] = *(const bf16x8*)(cur + bbase + tb * 32 * DROW + ro);
; #pragma unroll
;       for (int fb = 0; fb < NFB; ++fb) {
;         const bf16x8 afr = *(const bf16x8*)(cur + abase + fb * 32 * DROW + ro);
; #pragma unroll
;         for (int tb = 0; tb < NTB; ++tb) acc[tb * NFB + fb] = mfma(afr, bfr[tb], acc[tb * NFB + fb]);
;       }
;     }
;     asm volatile("s_waitcnt vmcnt(0) lgkmcnt(0)" ::: "memory");
;     __builtin_amdgcn_s_barrier();
	v_add_u32_e32 v195, 0xc000, v186
	ds_read_b128 v[180:183], v195 offset:32768
	v_add_u32_e32 v194, 0xc000, v14
	ds_read_b128 v[238:241], v194
	ds_read_b128 v[242:245], v194 offset:4096
	ds_read_b128 v[246:249], v194 offset:8192
	ds_read_b128 v[250:253], v194 offset:12288
	s_add_u32 m0, s33, 0x0
	v_lshl_add_u64 v[2:3], v[2:3], 0, s[84:85]
	global_load_lds_dwordx4 v[2:3], off
	s_add_u32 m0, s33, 0x2000
	v_lshl_add_u64 v[6:7], v[6:7], 0, s[84:85]
	global_load_lds_dwordx4 v[6:7], off
	s_add_u32 m0, s33, 0x4000
	v_lshl_add_u64 v[8:9], v[8:9], 0, s[84:85]
	global_load_lds_dwordx4 v[8:9], off
	s_add_u32 m0, s33, 0x6000
	v_lshl_add_u64 v[10:11], v[10:11], 0, s[84:85]
	global_load_lds_dwordx4 v[10:11], off
	s_add_u32 m0, s33, 0x8000
	v_lshl_add_u64 v[4:5], v[4:5], 0, s[84:85]
	global_load_lds_dwordx4 v[4:5], off
	s_add_u32 m0, s33, 0xa000
	v_lshl_add_u64 v[12:13], v[12:13], 0, s[84:85]
	global_load_lds_dwordx4 v[12:13], off
	v_add_u32_e32 v195, 0xc000, v189
	ds_read_b128 v[190:193], v195 offset:32768
	v_add_u32_e32 v194, 0xc000, v15
	s_waitcnt lgkmcnt(4)
	v_mfma_f32_32x32x16_bf16 v[128:143], v[238:241], v[180:183], v[128:143]
	ds_read_b128 v[238:241], v194
	s_waitcnt lgkmcnt(4)
	v_mfma_f32_32x32x16_bf16 v[48:63], v[242:245], v[180:183], v[48:63]
	ds_read_b128 v[242:245], v194 offset:4096
	s_waitcnt lgkmcnt(4)
	v_mfma_f32_32x32x16_bf16 v[32:47], v[246:249], v[180:183], v[32:47]
	ds_read_b128 v[246:249], v194 offset:8192
	s_waitcnt lgkmcnt(4)
	v_mfma_f32_32x32x16_bf16 v[16:31], v[250:253], v[180:183], v[16:31]
	ds_read_b128 v[250:253], v194 offset:12288
	v_add_u32_e32 v195, 0xc000, v233
	ds_read_b128 v[180:183], v195 offset:32768
	v_add_u32_e32 v194, 0xc000, v0
	s_waitcnt lgkmcnt(4)
	v_mfma_f32_32x32x16_bf16 v[128:143], v[238:241], v[190:193], v[128:143]
	ds_read_b128 v[238:241], v194
	s_waitcnt lgkmcnt(4)
	v_mfma_f32_32x32x16_bf16 v[48:63], v[242:245], v[190:193], v[48:63]
	ds_read_b128 v[242:245], v194 offset:4096
	s_waitcnt lgkmcnt(4)
	v_mfma_f32_32x32x16_bf16 v[32:47], v[246:249], v[190:193], v[32:47]
	ds_read_b128 v[246:249], v194 offset:8192
	s_waitcnt lgkmcnt(4)
	v_mfma_f32_32x32x16_bf16 v[16:31], v[250:253], v[190:193], v[16:31]
	ds_read_b128 v[250:253], v194 offset:12288
	v_add_u32_e32 v195, 0xc000, v234
	ds_read_b128 v[190:193], v195 offset:32768
	v_add_u32_e32 v194, 0xc000, v184
	s_waitcnt lgkmcnt(4)
	v_mfma_f32_32x32x16_bf16 v[128:143], v[238:241], v[180:183], v[128:143]
	ds_read_b128 v[238:241], v194
	s_waitcnt lgkmcnt(4)
	v_mfma_f32_32x32x16_bf16 v[48:63], v[242:245], v[180:183], v[48:63]
	ds_read_b128 v[242:245], v194 offset:4096
	s_waitcnt lgkmcnt(4)
	v_mfma_f32_32x32x16_bf16 v[32:47], v[246:249], v[180:183], v[32:47]
	ds_read_b128 v[246:249], v194 offset:8192
	s_waitcnt lgkmcnt(4)
	v_mfma_f32_32x32x16_bf16 v[16:31], v[250:253], v[180:183], v[16:31]
	ds_read_b128 v[250:253], v194 offset:12288
	s_waitcnt lgkmcnt(3)
	v_mfma_f32_32x32x16_bf16 v[128:143], v[238:241], v[190:193], v[128:143]
	s_waitcnt lgkmcnt(2)
	v_mfma_f32_32x32x16_bf16 v[48:63], v[242:245], v[190:193], v[48:63]
	s_waitcnt lgkmcnt(1)
	v_mfma_f32_32x32x16_bf16 v[32:47], v[246:249], v[190:193], v[32:47]
	s_waitcnt lgkmcnt(0)
	v_mfma_f32_32x32x16_bf16 v[16:31], v[250:253], v[190:193], v[16:31]
	s_waitcnt vmcnt(6)
	s_barrier
	v_add_u32_e32 v195, 0x18000, v186
	ds_read_b128 v[180:183], v195 offset:32768
	v_add_u32_e32 v194, 0x18000, v14
	ds_read_b128 v[238:241], v194
	ds_read_b128 v[242:245], v194 offset:4096
	ds_read_b128 v[246:249], v194 offset:8192
	ds_read_b128 v[250:253], v194 offset:12288
	s_add_u32 m0, s33, 0xc000
	v_lshl_add_u64 v[2:3], v[2:3], 0, s[84:85]
	global_load_lds_dwordx4 v[2:3], off
	s_add_u32 m0, s33, 0xe000
	v_lshl_add_u64 v[6:7], v[6:7], 0, s[84:85]
	global_load_lds_dwordx4 v[6:7], off
	s_add_u32 m0, s33, 0x10000
	v_lshl_add_u64 v[8:9], v[8:9], 0, s[84:85]
	global_load_lds_dwordx4 v[8:9], off
	s_add_u32 m0, s33, 0x12000
	v_lshl_add_u64 v[10:11], v[10:11], 0, s[84:85]
	global_load_lds_dwordx4 v[10:11], off
	s_add_u32 m0, s33, 0x14000
	v_lshl_add_u64 v[4:5], v[4:5], 0, s[84:85]
	global_load_lds_dwordx4 v[4:5], off
	s_add_u32 m0, s33, 0x16000
	v_lshl_add_u64 v[12:13], v[12:13], 0, s[84:85]
	global_load_lds_dwordx4 v[12:13], off
	v_add_u32_e32 v195, 0x18000, v189
	ds_read_b128 v[190:193], v195 offset:32768
	v_add_u32_e32 v194, 0x18000, v15
	s_waitcnt lgkmcnt(4)
	v_mfma_f32_32x32x16_bf16 v[128:143], v[238:241], v[180:183], v[128:143]
	ds_read_b128 v[238:241], v194
	s_waitcnt lgkmcnt(4)
	v_mfma_f32_32x32x16_bf16 v[48:63], v[242:245], v[180:183], v[48:63]
	ds_read_b128 v[242:245], v194 offset:4096
	s_waitcnt lgkmcnt(4)
	v_mfma_f32_32x32x16_bf16 v[32:47], v[246:249], v[180:183], v[32:47]
	ds_read_b128 v[246:249], v194 offset:8192
	s_waitcnt lgkmcnt(4)
	v_mfma_f32_32x32x16_bf16 v[16:31], v[250:253], v[180:183], v[16:31]
	ds_read_b128 v[250:253], v194 offset:12288
	v_add_u32_e32 v195, 0x18000, v233
	ds_read_b128 v[180:183], v195 offset:32768
	v_add_u32_e32 v194, 0x18000, v0
	s_waitcnt lgkmcnt(4)
	v_mfma_f32_32x32x16_bf16 v[128:143], v[238:241], v[190:193], v[128:143]
	ds_read_b128 v[238:241], v194
	s_waitcnt lgkmcnt(4)
	v_mfma_f32_32x32x16_bf16 v[48:63], v[242:245], v[190:193], v[48:63]
	ds_read_b128 v[242:245], v194 offset:4096
	s_waitcnt lgkmcnt(4)
	v_mfma_f32_32x32x16_bf16 v[32:47], v[246:249], v[190:193], v[32:47]
	ds_read_b128 v[246:249], v194 offset:8192
	s_waitcnt lgkmcnt(4)
	v_mfma_f32_32x32x16_bf16 v[16:31], v[250:253], v[190:193], v[16:31]
	ds_read_b128 v[250:253], v194 offset:12288
	v_add_u32_e32 v195, 0x18000, v234
	ds_read_b128 v[190:193], v195 offset:32768
	v_add_u32_e32 v194, 0x18000, v184
	s_waitcnt lgkmcnt(4)
	v_mfma_f32_32x32x16_bf16 v[128:143], v[238:241], v[180:183], v[128:143]
	ds_read_b128 v[238:241], v194
	s_waitcnt lgkmcnt(4)
	v_mfma_f32_32x32x16_bf16 v[48:63], v[242:245], v[180:183], v[48:63]
	ds_read_b128 v[242:245], v194 offset:4096
	s_waitcnt lgkmcnt(4)
	v_mfma_f32_32x32x16_bf16 v[32:47], v[246:249], v[180:183], v[32:47]
	ds_read_b128 v[246:249], v194 offset:8192
	s_waitcnt lgkmcnt(4)
	v_mfma_f32_32x32x16_bf16 v[16:31], v[250:253], v[180:183], v[16:31]
	ds_read_b128 v[250:253], v194 offset:12288
	s_waitcnt lgkmcnt(3)
	v_mfma_f32_32x32x16_bf16 v[128:143], v[238:241], v[190:193], v[128:143]
	s_waitcnt lgkmcnt(2)
	v_mfma_f32_32x32x16_bf16 v[48:63], v[242:245], v[190:193], v[48:63]
	s_waitcnt lgkmcnt(1)
	v_mfma_f32_32x32x16_bf16 v[32:47], v[246:249], v[190:193], v[32:47]
	s_waitcnt lgkmcnt(0)
	v_mfma_f32_32x32x16_bf16 v[16:31], v[250:253], v[190:193], v[16:31]
	s_waitcnt vmcnt(6)
	s_barrier
; DI f32x16 mfma(bf16x8 a, bf16x8 b, f32x16 c) { return __builtin_amdgcn_mfma_f32_32x32x16_bf16(a, b, c, 0, 0, 0); }
;     ...
;   __syncthreads();
;   DMA_ISSUE(0, 0)
;   asm volatile("s_waitcnt vmcnt(0)" ::: "memory");
;   __builtin_amdgcn_s_barrier();
;   for (int kt = 0; kt < nk; ++kt) {
;     const char* cur = lds + (kt & 1) * DBUF;
;     if (kt + 1 < nk) DMA_ISSUE((kt + 1) & 1, kt + 1)
; #pragma unroll(NTB == 1 ? 2 : 4)
;     for (int s = 0; s < 4; ++s) {
;       const int ro = ((2 * s + hh) ^ xr) * 16;
;       bf16x8 bfr[NTB];
; #pragma unroll
;       for (int tb = 0; tb < NTB; ++tb) bfr[tb] = *(const bf16x8*)(cur + bbase + tb * 32 * DROW + ro);
; #pragma unroll
;       for (int fb = 0; fb < NFB; ++fb) {
;         const bf16x8 afr = *(const bf16x8*)(cur + abase + fb * 32 * DROW + ro);
; #pragma unroll
;         for (int tb = 0; tb < NTB; ++tb) acc[tb * NFB + fb] = mfma(afr, bfr[tb], acc[tb * NFB + fb]);
;       }
;     }
;     asm volatile("s_waitcnt vmcnt(0) lgkmcnt(0)" ::: "memory");
;     __builtin_amdgcn_s_barrier();
	ds_read_b128 v[180:183], v186 offset:32768
	ds_read_b128 v[238:241], v14
	ds_read_b128 v[242:245], v14 offset:4096
	ds_read_b128 v[246:249], v14 offset:8192
	ds_read_b128 v[250:253], v14 offset:12288
	s_add_u32 m0, s33, 0x18000
	v_lshl_add_u64 v[2:3], v[2:3], 0, s[84:85]
	global_load_lds_dwordx4 v[2:3], off
	s_add_u32 m0, s33, 0x1a000
	v_lshl_add_u64 v[6:7], v[6:7], 0, s[84:85]
	global_load_lds_dwordx4 v[6:7], off
	s_add_u32 m0, s33, 0x1c000
	v_lshl_add_u64 v[8:9], v[8:9], 0, s[84:85]
	global_load_lds_dwordx4 v[8:9], off
	s_add_u32 m0, s33, 0x1e000
	v_lshl_add_u64 v[10:11], v[10:11], 0, s[84:85]
	global_load_lds_dwordx4 v[10:11], off
	s_add_u32 m0, s33, 0x20000
	v_lshl_add_u64 v[4:5], v[4:5], 0, s[84:85]
	global_load_lds_dwordx4 v[4:5], off
	s_add_u32 m0, s33, 0x22000
	v_lshl_add_u64 v[12:13], v[12:13], 0, s[84:85]
	global_load_lds_dwordx4 v[12:13], off
	ds_read_b128 v[190:193], v189 offset:32768
	s_waitcnt lgkmcnt(4)
	v_mfma_f32_32x32x16_bf16 v[128:143], v[238:241], v[180:183], v[128:143]
	ds_read_b128 v[238:241], v15
	s_waitcnt lgkmcnt(4)
	v_mfma_f32_32x32x16_bf16 v[48:63], v[242:245], v[180:183], v[48:63]
	ds_read_b128 v[242:245], v15 offset:4096
	s_waitcnt lgkmcnt(4)
	v_mfma_f32_32x32x16_bf16 v[32:47], v[246:249], v[180:183], v[32:47]
	ds_read_b128 v[246:249], v15 offset:8192
	s_waitcnt lgkmcnt(4)
	v_mfma_f32_32x32x16_bf16 v[16:31], v[250:253], v[180:183], v[16:31]
	ds_read_b128 v[250:253], v15 offset:12288
	ds_read_b128 v[180:183], v233 offset:32768
	s_waitcnt lgkmcnt(4)
	v_mfma_f32_32x32x16_bf16 v[128:143], v[238:241], v[190:193], v[128:143]
	ds_read_b128 v[238:241], v0
	s_waitcnt lgkmcnt(4)
	v_mfma_f32_32x32x16_bf16 v[48:63], v[242:245], v[190:193], v[48:63]
	ds_read_b128 v[242:245], v0 offset:4096
	s_waitcnt lgkmcnt(4)
	v_mfma_f32_32x32x16_bf16 v[32:47], v[246:249], v[190:193], v[32:47]
	ds_read_b128 v[246:249], v0 offset:8192
	s_waitcnt lgkmcnt(4)
	v_mfma_f32_32x32x16_bf16 v[16:31], v[250:253], v[190:193], v[16:31]
	ds_read_b128 v[250:253], v0 offset:12288
	ds_read_b128 v[190:193], v234 offset:32768
	s_waitcnt lgkmcnt(4)
	v_mfma_f32_32x32x16_bf16 v[128:143], v[238:241], v[180:183], v[128:143]
	ds_read_b128 v[238:241], v184
	s_waitcnt lgkmcnt(4)
	v_mfma_f32_32x32x16_bf16 v[48:63], v[242:245], v[180:183], v[48:63]
	ds_read_b128 v[242:245], v184 offset:4096
	s_waitcnt lgkmcnt(4)
	v_mfma_f32_32x32x16_bf16 v[32:47], v[246:249], v[180:183], v[32:47]
	ds_read_b128 v[246:249], v184 offset:8192
	s_waitcnt lgkmcnt(4)
	v_mfma_f32_32x32x16_bf16 v[16:31], v[250:253], v[180:183], v[16:31]
	ds_read_b128 v[250:253], v184 offset:12288
	s_waitcnt lgkmcnt(3)
	v_mfma_f32_32x32x16_bf16 v[128:143], v[238:241], v[190:193], v[128:143]
	s_waitcnt lgkmcnt(2)
	v_mfma_f32_32x32x16_bf16 v[48:63], v[242:245], v[190:193], v[48:63]
	s_waitcnt lgkmcnt(1)
	v_mfma_f32_32x32x16_bf16 v[32:47], v[246:249], v[190:193], v[32:47]
	s_waitcnt lgkmcnt(0)
	v_mfma_f32_32x32x16_bf16 v[16:31], v[250:253], v[190:193], v[16:31]
	s_waitcnt vmcnt(6)
	s_barrier
	v_add_u32_e32 v195, 0xc000, v186
	ds_read_b128 v[180:183], v195 offset:32768
	v_add_u32_e32 v194, 0xc000, v14
	ds_read_b128 v[238:241], v194
	ds_read_b128 v[242:245], v194 offset:4096
	ds_read_b128 v[246:249], v194 offset:8192
	ds_read_b128 v[250:253], v194 offset:12288
	v_add_u32_e32 v195, 0xc000, v189
	ds_read_b128 v[190:193], v195 offset:32768
	v_add_u32_e32 v194, 0xc000, v15
	s_waitcnt lgkmcnt(4)
	v_mfma_f32_32x32x16_bf16 v[128:143], v[238:241], v[180:183], v[128:143]
	ds_read_b128 v[238:241], v194
	s_waitcnt lgkmcnt(4)
	v_mfma_f32_32x32x16_bf16 v[48:63], v[242:245], v[180:183], v[48:63]
	ds_read_b128 v[242:245], v194 offset:4096
	s_waitcnt lgkmcnt(4)
	v_mfma_f32_32x32x16_bf16 v[32:47], v[246:249], v[180:183], v[32:47]
	ds_read_b128 v[246:249], v194 offset:8192
	s_waitcnt lgkmcnt(4)
	v_mfma_f32_32x32x16_bf16 v[16:31], v[250:253], v[180:183], v[16:31]
	ds_read_b128 v[250:253], v194 offset:12288
	v_add_u32_e32 v195, 0xc000, v233
	ds_read_b128 v[180:183], v195 offset:32768
	v_add_u32_e32 v194, 0xc000, v0
	s_waitcnt lgkmcnt(4)
	v_mfma_f32_32x32x16_bf16 v[128:143], v[238:241], v[190:193], v[128:143]
	ds_read_b128 v[238:241], v194
	s_waitcnt lgkmcnt(4)
	v_mfma_f32_32x32x16_bf16 v[48:63], v[242:245], v[190:193], v[48:63]
	ds_read_b128 v[242:245], v194 offset:4096
	s_waitcnt lgkmcnt(4)
	v_mfma_f32_32x32x16_bf16 v[32:47], v[246:249], v[190:193], v[32:47]
	ds_read_b128 v[246:249], v194 offset:8192
	s_waitcnt lgkmcnt(4)
	v_mfma_f32_32x32x16_bf16 v[16:31], v[250:253], v[190:193], v[16:31]
	ds_read_b128 v[250:253], v194 offset:12288
	v_add_u32_e32 v195, 0xc000, v234
	ds_read_b128 v[190:193], v195 offset:32768
	v_add_u32_e32 v194, 0xc000, v184
	s_waitcnt lgkmcnt(4)
	v_mfma_f32_32x32x16_bf16 v[128:143], v[238:241], v[180:183], v[128:143]
	ds_read_b128 v[238:241], v194
	s_waitcnt lgkmcnt(4)
	v_mfma_f32_32x32x16_bf16 v[48:63], v[242:245], v[180:183], v[48:63]
	ds_read_b128 v[242:245], v194 offset:4096
	s_waitcnt lgkmcnt(4)
	v_mfma_f32_32x32x16_bf16 v[32:47], v[246:249], v[180:183], v[32:47]
	ds_read_b128 v[246:249], v194 offset:8192
	s_waitcnt lgkmcnt(4)
	v_mfma_f32_32x32x16_bf16 v[16:31], v[250:253], v[180:183], v[16:31]
	ds_read_b128 v[250:253], v194 offset:12288
	s_waitcnt lgkmcnt(3)
	v_mfma_f32_32x32x16_bf16 v[128:143], v[238:241], v[190:193], v[128:143]
	s_waitcnt lgkmcnt(2)
	v_mfma_f32_32x32x16_bf16 v[48:63], v[242:245], v[190:193], v[48:63]
	s_waitcnt lgkmcnt(1)
	v_mfma_f32_32x32x16_bf16 v[32:47], v[246:249], v[190:193], v[32:47]
	s_waitcnt lgkmcnt(0)
	v_mfma_f32_32x32x16_bf16 v[16:31], v[250:253], v[190:193], v[16:31]
	s_waitcnt vmcnt(0)
	s_barrier
; DI unsigned pack2(float a, float b) { f2_t v = {a, b}; bf2_t r = __builtin_convertvector(v, bf2_t); return __builtin_bit_cast(unsigned, r); }
; DI f32x16 mfma(bf16x8 a, bf16x8 b, f32x16 c) { return __builtin_amdgcn_mfma_f32_32x32x16_bf16(a, b, c, 0, 0, 0); }
;     ...
;   __syncthreads();
;   DMA_ISSUE(0, 0)
;   asm volatile("s_waitcnt vmcnt(0)" ::: "memory");
;   __builtin_amdgcn_s_barrier();
;   for (int kt = 0; kt < nk; ++kt) {
;     const char* cur = lds + (kt & 1) * DBUF;
;     if (kt + 1 < nk) DMA_ISSUE((kt + 1) & 1, kt + 1)
; #pragma unroll(NTB == 1 ? 2 : 4)
;     for (int s = 0; s < 4; ++s) {
;       const int ro = ((2 * s + hh) ^ xr) * 16;
;       bf16x8 bfr[NTB];
; #pragma unroll
;       for (int tb = 0; tb < NTB; ++tb) bfr[tb] = *(const bf16x8*)(cur + bbase + tb * 32 * DROW + ro);
; #pragma unroll
;       for (int fb = 0; fb < NFB; ++fb) {
;         const bf16x8 afr = *(const bf16x8*)(cur + abase + fb * 32 * DROW + ro);
; #pragma unroll
;         for (int tb = 0; tb < NTB; ++tb) acc[tb * NFB + fb] = mfma(afr, bfr[tb], acc[tb * NFB + fb]);
;       }
;     }
;     asm volatile("s_waitcnt vmcnt(0) lgkmcnt(0)" ::: "memory");
;     __builtin_amdgcn_s_barrier();
; __global__ void __launch_bounds__(512) mega(Params p) {
;     ...
; #pragma unroll
;           for (int fb = 0; fb < 4; ++fb)
; #pragma unroll
;             for (int i = 0; i < 8; ++i) {
;               const float b0 = __uint_as_float(bp[fb][i] << 16), b1 = __uint_as_float(bp[fb][i] & 0xffff0000u);
;               const float g0 = 1.f / (1.f + __builtin_amdgcn_exp2f(nr1 * acc[fb][2 * i]));
;               const float g1 = 1.f / (1.f + __builtin_amdgcn_exp2f(nr1 * acc[fb][2 * i + 1]));
;               float y0 = g0 * b0, y1 = g1 * b1;
;               if (n > 0) { y0 += __uint_as_float(yp[fb][i] << 16); y1 += __uint_as_float(yp[fb][i] & 0xffff0000u); }
;               yp[fb][i] = pack2(y0, y1);
	v_add_u32_e32 v195, 0x18000, v186
	ds_read_b128 v[180:183], v195 offset:32768
	v_add_u32_e32 v194, 0x18000, v14
	ds_read_b128 v[238:241], v194
	ds_read_b128 v[242:245], v194 offset:4096
	ds_read_b128 v[246:249], v194 offset:8192
	ds_read_b128 v[250:253], v194 offset:12288
	v_add_u32_e32 v195, 0x18000, v189
	ds_read_b128 v[190:193], v195 offset:32768
	v_add_u32_e32 v194, 0x18000, v15
	s_waitcnt lgkmcnt(4)
	v_mfma_f32_32x32x16_bf16 v[128:143], v[238:241], v[180:183], v[128:143]
	ds_read_b128 v[238:241], v194
	s_waitcnt lgkmcnt(4)
	v_mfma_f32_32x32x16_bf16 v[48:63], v[242:245], v[180:183], v[48:63]
	ds_read_b128 v[242:245], v194 offset:4096
	s_waitcnt lgkmcnt(4)
	v_mfma_f32_32x32x16_bf16 v[32:47], v[246:249], v[180:183], v[32:47]
	ds_read_b128 v[246:249], v194 offset:8192
	s_waitcnt lgkmcnt(4)
	v_mfma_f32_32x32x16_bf16 v[16:31], v[250:253], v[180:183], v[16:31]
	ds_read_b128 v[250:253], v194 offset:12288
	v_add_u32_e32 v195, 0x18000, v233
	ds_read_b128 v[180:183], v195 offset:32768
	v_add_u32_e32 v194, 0x18000, v0
	s_waitcnt lgkmcnt(4)
	v_mfma_f32_32x32x16_bf16 v[128:143], v[238:241], v[190:193], v[128:143]
	ds_read_b128 v[238:241], v194
	s_waitcnt lgkmcnt(4)
	v_mfma_f32_32x32x16_bf16 v[48:63], v[242:245], v[190:193], v[48:63]
	ds_read_b128 v[242:245], v194 offset:4096
	s_waitcnt lgkmcnt(4)
	v_mfma_f32_32x32x16_bf16 v[32:47], v[246:249], v[190:193], v[32:47]
	ds_read_b128 v[246:249], v194 offset:8192
	s_waitcnt lgkmcnt(4)
	v_mfma_f32_32x32x16_bf16 v[16:31], v[250:253], v[190:193], v[16:31]
	ds_read_b128 v[250:253], v194 offset:12288
	v_add_u32_e32 v195, 0x18000, v234
	ds_read_b128 v[190:193], v195 offset:32768
	v_add_u32_e32 v194, 0x18000, v184
	s_waitcnt lgkmcnt(4)
	v_mfma_f32_32x32x16_bf16 v[128:143], v[238:241], v[180:183], v[128:143]
	ds_read_b128 v[238:241], v194
	s_waitcnt lgkmcnt(4)
	v_mfma_f32_32x32x16_bf16 v[48:63], v[242:245], v[180:183], v[48:63]
	ds_read_b128 v[242:245], v194 offset:4096
	s_waitcnt lgkmcnt(4)
	v_mfma_f32_32x32x16_bf16 v[32:47], v[246:249], v[180:183], v[32:47]
	ds_read_b128 v[246:249], v194 offset:8192
	s_waitcnt lgkmcnt(4)
	v_mfma_f32_32x32x16_bf16 v[16:31], v[250:253], v[180:183], v[16:31]
	ds_read_b128 v[250:253], v194 offset:12288
	s_waitcnt lgkmcnt(3)
	v_mfma_f32_32x32x16_bf16 v[128:143], v[238:241], v[190:193], v[128:143]
	s_waitcnt lgkmcnt(2)
	v_mfma_f32_32x32x16_bf16 v[48:63], v[242:245], v[190:193], v[48:63]
	s_waitcnt lgkmcnt(1)
	v_mfma_f32_32x32x16_bf16 v[32:47], v[246:249], v[190:193], v[32:47]
	s_waitcnt lgkmcnt(0)
	v_mfma_f32_32x32x16_bf16 v[16:31], v[250:253], v[190:193], v[16:31]
	s_nop 7
	s_nop 7
	s_waitcnt vmcnt(0) lgkmcnt(0)
	s_barrier
	v_cvt_pk_bf16_f32 v7, v66, v67
	v_mul_f32_e32 v66, v236, v128
	v_mul_f32_e32 v67, v236, v129
	v_exp_f32_e32 v66, v66
	v_exp_f32_e32 v67, v67
	v_cvt_pk_bf16_f32 v6, v68, v69
	v_cvt_pk_bf16_f32 v5, v70, v71
	v_cvt_pk_bf16_f32 v4, v72, v73
	v_pk_add_f32 v[66:67], v[66:67], 1.0 op_sel_hi:[1,0]
	v_cvt_pk_bf16_f32 v180, v112, v113
	v_div_scale_f32 v68, s[34:35], v67, v67, 1.0
	v_rcp_f32_e32 v69, v68
	v_cvt_pk_bf16_f32 v8, v64, v65
	v_lshlrev_b32_e32 v64, 16, v180
	v_and_b32_e32 v65, 0xffff0000, v180
	v_fma_f32 v70, -v68, v69, 1.0
	v_fmac_f32_e32 v69, v70, v69
	v_div_scale_f32 v70, vcc, 1.0, v67, 1.0
	v_mul_f32_e32 v71, v70, v69
	v_fma_f32 v72, -v68, v71, v70
	v_fmac_f32_e32 v71, v72, v69
	v_fma_f32 v68, -v68, v71, v70
	v_div_fmas_f32 v68, v68, v69, v71
	v_div_fixup_f32 v67, v68, v67, 1.0
	v_div_scale_f32 v68, s[34:35], v66, v66, 1.0
	v_rcp_f32_e32 v69, v68
	v_cvt_pk_bf16_f32 v181, v114, v115
	v_cvt_pk_bf16_f32 v182, v116, v117
	v_cvt_pk_bf16_f32 v118, v118, v119
	v_fma_f32 v70, -v68, v69, 1.0
	v_fmac_f32_e32 v69, v70, v69
	v_div_scale_f32 v70, vcc, 1.0, v66, 1.0
	v_mul_f32_e32 v71, v70, v69
	v_fma_f32 v72, -v68, v71, v70
	v_fmac_f32_e32 v71, v72, v69
	v_fma_f32 v68, -v68, v71, v70
	v_div_fmas_f32 v68, v68, v69, v71
	v_div_fixup_f32 v66, v68, v66, 1.0
	v_lshlrev_b32_e32 v70, 16, v166
	v_and_b32_e32 v71, 0xffff0000, v166
	v_pk_mul_f32 v[68:69], v[66:67], v[64:65]
	v_pk_fma_f32 v[64:65], v[66:67], v[64:65], v[70:71]
	v_mul_f32_e32 v66, v236, v130
	v_mul_f32_e32 v67, v236, v131
	v_exp_f32_e32 v66, v66
	v_exp_f32_e32 v67, v67
	v_cndmask_b32_e64 v64, v64, v68, s[0:1]
	v_cndmask_b32_e64 v65, v65, v69, s[0:1]
	v_cvt_pk_bf16_f32 v166, v64, v65
	v_pk_add_f32 v[66:67], v[66:67], 1.0 op_sel_hi:[1,0]
	v_lshlrev_b32_e32 v64, 16, v181
	v_div_scale_f32 v68, s[34:35], v67, v67, 1.0
	v_rcp_f32_e32 v69, v68
	v_and_b32_e32 v65, 0xffff0000, v181
	v_cvt_pk_bf16_f32 v117, v120, v121
	v_cvt_pk_bf16_f32 v116, v122, v123
	v_fma_f32 v70, -v68, v69, 1.0
	v_fmac_f32_e32 v69, v70, v69
	v_div_scale_f32 v70, vcc, 1.0, v67, 1.0
	v_mul_f32_e32 v71, v70, v69
	v_fma_f32 v72, -v68, v71, v70
	v_fmac_f32_e32 v71, v72, v69
	v_fma_f32 v68, -v68, v71, v70
	v_div_fmas_f32 v68, v68, v69, v71
	v_div_fixup_f32 v67, v68, v67, 1.0
	v_div_scale_f32 v68, s[34:35], v66, v66, 1.0
	v_rcp_f32_e32 v69, v68
	v_cvt_pk_bf16_f32 v115, v124, v125
	v_mul_f32_e32 v48, v236, v48
	v_mul_f32_e32 v49, v236, v49
	v_fma_f32 v70, -v68, v69, 1.0
	v_fmac_f32_e32 v69, v70, v69
	v_div_scale_f32 v70, vcc, 1.0, v66, 1.0
	v_mul_f32_e32 v71, v70, v69
	v_fma_f32 v72, -v68, v71, v70
	v_fmac_f32_e32 v71, v72, v69
	v_fma_f32 v68, -v68, v71, v70
	v_div_fmas_f32 v68, v68, v69, v71
	v_div_fixup_f32 v66, v68, v66, 1.0
	v_lshlrev_b32_e32 v70, 16, v167
	v_and_b32_e32 v71, 0xffff0000, v167
	v_pk_mul_f32 v[68:69], v[66:67], v[64:65]
	v_pk_fma_f32 v[64:65], v[66:67], v[64:65], v[70:71]
	v_mul_f32_e32 v66, v236, v132
	v_mul_f32_e32 v67, v236, v133
	v_exp_f32_e32 v66, v66
	v_exp_f32_e32 v67, v67
	v_cndmask_b32_e64 v64, v64, v68, s[0:1]
; DI unsigned pack2(float a, float b) { f2_t v = {a, b}; bf2_t r = __builtin_convertvector(v, bf2_t); return __builtin_bit_cast(unsigned, r); }
; __global__ void __launch_bounds__(512) mega(Params p) {
;     ...
; #pragma unroll
;           for (int fb = 0; fb < 4; ++fb)
; #pragma unroll
;             for (int i = 0; i < 8; ++i) {
;               const float b0 = __uint_as_float(bp[fb][i] << 16), b1 = __uint_as_float(bp[fb][i] & 0xffff0000u);
;               const float g0 = 1.f / (1.f + __builtin_amdgcn_exp2f(nr1 * acc[fb][2 * i]));
;               const float g1 = 1.f / (1.f + __builtin_amdgcn_exp2f(nr1 * acc[fb][2 * i + 1]));
;               float y0 = g0 * b0, y1 = g1 * b1;
;               if (n > 0) { y0 += __uint_as_float(yp[fb][i] << 16); y1 += __uint_as_float(yp[fb][i] & 0xffff0000u); }
;               yp[fb][i] = pack2(y0, y1);
	v_cndmask_b32_e64 v65, v65, v69, s[0:1]
	v_cvt_pk_bf16_f32 v167, v64, v65
	v_pk_add_f32 v[66:67], v[66:67], 1.0 op_sel_hi:[1,0]
	v_lshlrev_b32_e32 v64, 16, v182
	v_div_scale_f32 v68, s[34:35], v67, v67, 1.0
	v_rcp_f32_e32 v69, v68
	v_and_b32_e32 v65, 0xffff0000, v182
	v_exp_f32_e32 v48, v48
	v_exp_f32_e32 v49, v49
	v_fma_f32 v70, -v68, v69, 1.0
	v_fmac_f32_e32 v69, v70, v69
	v_div_scale_f32 v70, vcc, 1.0, v67, 1.0
	v_mul_f32_e32 v71, v70, v69
	v_fma_f32 v72, -v68, v71, v70
	v_fmac_f32_e32 v71, v72, v69
	v_fma_f32 v68, -v68, v71, v70
	v_div_fmas_f32 v68, v68, v69, v71
	v_div_fixup_f32 v67, v68, v67, 1.0
	v_div_scale_f32 v68, s[34:35], v66, v66, 1.0
	v_rcp_f32_e32 v69, v68
	v_cvt_pk_bf16_f32 v114, v126, v127
	v_pk_add_f32 v[48:49], v[48:49], 1.0 op_sel_hi:[1,0]
	v_mul_f32_e32 v50, v236, v50
	v_fma_f32 v70, -v68, v69, 1.0
	v_fmac_f32_e32 v69, v70, v69
	v_div_scale_f32 v70, vcc, 1.0, v66, 1.0
	v_mul_f32_e32 v71, v70, v69
	v_fma_f32 v72, -v68, v71, v70
	v_fmac_f32_e32 v71, v72, v69
	v_fma_f32 v68, -v68, v71, v70
	v_div_fmas_f32 v68, v68, v69, v71
	v_div_fixup_f32 v66, v68, v66, 1.0
	v_lshlrev_b32_e32 v70, 16, v168
	v_and_b32_e32 v71, 0xffff0000, v168
	v_pk_mul_f32 v[68:69], v[66:67], v[64:65]
	v_pk_fma_f32 v[64:65], v[66:67], v[64:65], v[70:71]
	v_mul_f32_e32 v66, v236, v134
	v_mul_f32_e32 v67, v236, v135
	v_exp_f32_e32 v66, v66
	v_exp_f32_e32 v67, v67
	v_cndmask_b32_e64 v64, v64, v68, s[0:1]
	v_cndmask_b32_e64 v65, v65, v69, s[0:1]
	v_cvt_pk_bf16_f32 v168, v64, v65
	v_pk_add_f32 v[66:67], v[66:67], 1.0 op_sel_hi:[1,0]
	v_lshlrev_b32_e32 v64, 16, v118
	v_div_scale_f32 v68, s[34:35], v67, v67, 1.0
	v_rcp_f32_e32 v69, v68
	v_and_b32_e32 v65, 0xffff0000, v118
	v_mul_f32_e32 v51, v236, v51
	v_exp_f32_e32 v50, v50
	v_fma_f32 v70, -v68, v69, 1.0
	v_fmac_f32_e32 v69, v70, v69
	v_div_scale_f32 v70, vcc, 1.0, v67, 1.0
	v_mul_f32_e32 v71, v70, v69
	v_fma_f32 v72, -v68, v71, v70
	v_fmac_f32_e32 v71, v72, v69
	v_fma_f32 v68, -v68, v71, v70
	v_div_fmas_f32 v68, v68, v69, v71
	v_div_fixup_f32 v67, v68, v67, 1.0
	v_div_scale_f32 v68, s[34:35], v66, v66, 1.0
	v_rcp_f32_e32 v69, v68
	v_exp_f32_e32 v51, v51
	v_cvt_pk_bf16_f32 v113, v96, v97
	v_cvt_pk_bf16_f32 v112, v98, v99
	v_fma_f32 v70, -v68, v69, 1.0
	v_fmac_f32_e32 v69, v70, v69
	v_div_scale_f32 v70, vcc, 1.0, v66, 1.0
	v_mul_f32_e32 v71, v70, v69
	v_fma_f32 v72, -v68, v71, v70
	v_fmac_f32_e32 v71, v72, v69
	v_fma_f32 v68, -v68, v71, v70
	v_div_fmas_f32 v68, v68, v69, v71
	v_div_fixup_f32 v66, v68, v66, 1.0
	v_lshlrev_b32_e32 v70, 16, v169
	v_and_b32_e32 v71, 0xffff0000, v169
	v_pk_mul_f32 v[68:69], v[66:67], v[64:65]
	v_pk_fma_f32 v[64:65], v[66:67], v[64:65], v[70:71]
	v_mul_f32_e32 v66, v236, v136
	v_mul_f32_e32 v67, v236, v137
	v_exp_f32_e32 v66, v66
	v_exp_f32_e32 v67, v67
	v_cndmask_b32_e64 v64, v64, v68, s[0:1]
	v_cndmask_b32_e64 v65, v65, v69, s[0:1]
	v_cvt_pk_bf16_f32 v169, v64, v65
	v_pk_add_f32 v[66:67], v[66:67], 1.0 op_sel_hi:[1,0]
	v_lshlrev_b32_e32 v64, 16, v117
	v_div_scale_f32 v68, s[34:35], v67, v67, 1.0
	v_rcp_f32_e32 v69, v68
	v_and_b32_e32 v65, 0xffff0000, v117
	v_pk_add_f32 v[50:51], v[50:51], 1.0 op_sel_hi:[1,0]
	v_cvt_pk_bf16_f32 v101, v100, v101
	v_fma_f32 v70, -v68, v69, 1.0
	v_fmac_f32_e32 v69, v70, v69
	v_div_scale_f32 v70, vcc, 1.0, v67, 1.0
	v_mul_f32_e32 v71, v70, v69
	v_fma_f32 v72, -v68, v71, v70
	v_fmac_f32_e32 v71, v72, v69
	v_fma_f32 v68, -v68, v71, v70
	v_div_fmas_f32 v68, v68, v69, v71
	v_div_fixup_f32 v67, v68, v67, 1.0
	v_div_scale_f32 v68, s[34:35], v66, v66, 1.0
	v_rcp_f32_e32 v69, v68
	v_cvt_pk_bf16_f32 v100, v102, v103
	v_cvt_pk_bf16_f32 v99, v104, v105
	v_cvt_pk_bf16_f32 v98, v106, v107
	v_fma_f32 v70, -v68, v69, 1.0
	v_fmac_f32_e32 v69, v70, v69
	v_div_scale_f32 v70, vcc, 1.0, v66, 1.0
	v_mul_f32_e32 v71, v70, v69
	v_fma_f32 v72, -v68, v71, v70
	v_fmac_f32_e32 v71, v72, v69
	v_fma_f32 v68, -v68, v71, v70
	v_div_fmas_f32 v68, v68, v69, v71
	v_div_fixup_f32 v66, v68, v66, 1.0
	v_lshlrev_b32_e32 v70, 16, v170
	v_and_b32_e32 v71, 0xffff0000, v170
	v_pk_mul_f32 v[68:69], v[66:67], v[64:65]
	v_pk_fma_f32 v[64:65], v[66:67], v[64:65], v[70:71]
	v_mul_f32_e32 v66, v236, v138
	v_mul_f32_e32 v67, v236, v139
	v_exp_f32_e32 v66, v66
	v_exp_f32_e32 v67, v67
	v_cndmask_b32_e64 v64, v64, v68, s[0:1]
	v_cndmask_b32_e64 v65, v65, v69, s[0:1]
	v_cvt_pk_bf16_f32 v170, v64, v65
	v_pk_add_f32 v[66:67], v[66:67], 1.0 op_sel_hi:[1,0]
	v_lshlrev_b32_e32 v64, 16, v116
	v_div_scale_f32 v68, s[34:35], v67, v67, 1.0
	v_rcp_f32_e32 v69, v68
	v_and_b32_e32 v65, 0xffff0000, v116
	v_cvt_pk_bf16_f32 v97, v108, v109
	v_mul_f32_e32 v32, v236, v32
	v_fma_f32 v70, -v68, v69, 1.0
	v_fmac_f32_e32 v69, v70, v69
	v_div_scale_f32 v70, vcc, 1.0, v67, 1.0
	v_mul_f32_e32 v71, v70, v69
	v_fma_f32 v72, -v68, v71, v70
	v_fmac_f32_e32 v71, v72, v69
	v_fma_f32 v68, -v68, v71, v70
	v_div_fmas_f32 v68, v68, v69, v71
	v_div_fixup_f32 v67, v68, v67, 1.0
	v_div_scale_f32 v68, s[34:35], v66, v66, 1.0
	v_rcp_f32_e32 v69, v68
	v_mul_f32_e32 v33, v236, v33
	v_exp_f32_e32 v32, v32
	v_exp_f32_e32 v33, v33
	v_fma_f32 v70, -v68, v69, 1.0
	v_fmac_f32_e32 v69, v70, v69
	v_div_scale_f32 v70, vcc, 1.0, v66, 1.0
	v_mul_f32_e32 v71, v70, v69
	v_fma_f32 v72, -v68, v71, v70
	v_fmac_f32_e32 v71, v72, v69
	v_fma_f32 v68, -v68, v71, v70
	v_div_fmas_f32 v68, v68, v69, v71
	v_div_fixup_f32 v66, v68, v66, 1.0
	v_lshlrev_b32_e32 v70, 16, v171
	v_and_b32_e32 v71, 0xffff0000, v171
	v_pk_mul_f32 v[68:69], v[66:67], v[64:65]
	v_pk_fma_f32 v[64:65], v[66:67], v[64:65], v[70:71]
	v_mul_f32_e32 v66, v236, v140
	v_mul_f32_e32 v67, v236, v141
	v_exp_f32_e32 v66, v66
	v_exp_f32_e32 v67, v67
	v_cndmask_b32_e64 v64, v64, v68, s[0:1]
; DI unsigned pack2(float a, float b) { f2_t v = {a, b}; bf2_t r = __builtin_convertvector(v, bf2_t); return __builtin_bit_cast(unsigned, r); }
; __global__ void __launch_bounds__(512) mega(Params p) {
;     ...
; #pragma unroll
;           for (int fb = 0; fb < 4; ++fb)
; #pragma unroll
;             for (int i = 0; i < 8; ++i) {
;               const float b0 = __uint_as_float(bp[fb][i] << 16), b1 = __uint_as_float(bp[fb][i] & 0xffff0000u);
;               const float g0 = 1.f / (1.f + __builtin_amdgcn_exp2f(nr1 * acc[fb][2 * i]));
;               const float g1 = 1.f / (1.f + __builtin_amdgcn_exp2f(nr1 * acc[fb][2 * i + 1]));
;               float y0 = g0 * b0, y1 = g1 * b1;
;               if (n > 0) { y0 += __uint_as_float(yp[fb][i] << 16); y1 += __uint_as_float(yp[fb][i] & 0xffff0000u); }
;               yp[fb][i] = pack2(y0, y1);
	v_cndmask_b32_e64 v65, v65, v69, s[0:1]
	v_cvt_pk_bf16_f32 v171, v64, v65
	v_pk_add_f32 v[66:67], v[66:67], 1.0 op_sel_hi:[1,0]
	v_lshlrev_b32_e32 v64, 16, v115
	v_div_scale_f32 v68, s[34:35], v67, v67, 1.0
	v_rcp_f32_e32 v69, v68
	v_and_b32_e32 v65, 0xffff0000, v115
	v_cvt_pk_bf16_f32 v96, v110, v111
	v_pk_add_f32 v[32:33], v[32:33], 1.0 op_sel_hi:[1,0]
	v_fma_f32 v70, -v68, v69, 1.0
	v_fmac_f32_e32 v69, v70, v69
	v_div_scale_f32 v70, vcc, 1.0, v67, 1.0
	v_mul_f32_e32 v71, v70, v69
	v_fma_f32 v72, -v68, v71, v70
	v_fmac_f32_e32 v71, v72, v69
	v_fma_f32 v68, -v68, v71, v70
	v_div_fmas_f32 v68, v68, v69, v71
	v_div_fixup_f32 v67, v68, v67, 1.0
	v_div_scale_f32 v68, s[34:35], v66, v66, 1.0
	v_rcp_f32_e32 v69, v68
	v_cvt_pk_bf16_f32 v80, v80, v81
	v_cvt_pk_bf16_f32 v15, v82, v83
	v_cvt_pk_bf16_f32 v14, v84, v85
	v_fma_f32 v70, -v68, v69, 1.0
	v_fmac_f32_e32 v69, v70, v69
	v_div_scale_f32 v70, vcc, 1.0, v66, 1.0
	v_mul_f32_e32 v71, v70, v69
	v_fma_f32 v72, -v68, v71, v70
	v_fmac_f32_e32 v71, v72, v69
	v_fma_f32 v68, -v68, v71, v70
	v_div_fmas_f32 v68, v68, v69, v71
	v_div_fixup_f32 v66, v68, v66, 1.0
	v_lshlrev_b32_e32 v70, 16, v172
	v_and_b32_e32 v71, 0xffff0000, v172
	v_pk_mul_f32 v[68:69], v[66:67], v[64:65]
	v_pk_fma_f32 v[64:65], v[66:67], v[64:65], v[70:71]
	v_mul_f32_e32 v66, v236, v142
	v_mul_f32_e32 v67, v236, v143
	v_exp_f32_e32 v66, v66
	v_exp_f32_e32 v67, v67
	v_cndmask_b32_e64 v64, v64, v68, s[0:1]
	v_cndmask_b32_e64 v65, v65, v69, s[0:1]
	v_cvt_pk_bf16_f32 v172, v64, v65
	v_pk_add_f32 v[66:67], v[66:67], 1.0 op_sel_hi:[1,0]
	v_lshlrev_b32_e32 v64, 16, v114
	v_div_scale_f32 v68, s[34:35], v67, v67, 1.0
	v_rcp_f32_e32 v69, v68
	v_and_b32_e32 v65, 0xffff0000, v114
	v_cvt_pk_bf16_f32 v13, v86, v87
	v_cvt_pk_bf16_f32 v12, v88, v89
	v_fma_f32 v70, -v68, v69, 1.0
	v_fmac_f32_e32 v69, v70, v69
	v_div_scale_f32 v70, vcc, 1.0, v67, 1.0
	v_mul_f32_e32 v71, v70, v69
	v_fma_f32 v72, -v68, v71, v70
	v_fmac_f32_e32 v71, v72, v69
	v_fma_f32 v68, -v68, v71, v70
	v_div_fmas_f32 v68, v68, v69, v71
	v_div_fixup_f32 v67, v68, v67, 1.0
	v_div_scale_f32 v68, s[34:35], v66, v66, 1.0
	v_rcp_f32_e32 v69, v68
	v_cvt_pk_bf16_f32 v11, v90, v91
	v_cvt_pk_bf16_f32 v10, v92, v93
	v_cvt_pk_bf16_f32 v9, v94, v95
	v_fma_f32 v70, -v68, v69, 1.0
	v_fmac_f32_e32 v69, v70, v69
	v_div_scale_f32 v70, vcc, 1.0, v66, 1.0
	v_mul_f32_e32 v71, v70, v69
	v_fma_f32 v72, -v68, v71, v70
	v_fmac_f32_e32 v71, v72, v69
	v_fma_f32 v68, -v68, v71, v70
	v_div_fmas_f32 v68, v68, v69, v71
	v_div_fixup_f32 v66, v68, v66, 1.0
	v_lshlrev_b32_e32 v70, 16, v173
	v_and_b32_e32 v71, 0xffff0000, v173
	v_pk_mul_f32 v[68:69], v[66:67], v[64:65]
	v_pk_fma_f32 v[64:65], v[66:67], v[64:65], v[70:71]
	v_div_scale_f32 v66, s[34:35], v49, v49, 1.0
	v_rcp_f32_e32 v67, v66
	v_cndmask_b32_e64 v64, v64, v68, s[0:1]
	v_cndmask_b32_e64 v65, v65, v69, s[0:1]
	v_cvt_pk_bf16_f32 v173, v64, v65
	v_fma_f32 v68, -v66, v67, 1.0
	v_fmac_f32_e32 v67, v68, v67
	v_div_scale_f32 v68, vcc, 1.0, v49, 1.0
	v_mul_f32_e32 v69, v68, v67
	v_fma_f32 v70, -v66, v69, v68
	v_fmac_f32_e32 v69, v70, v67
	v_fma_f32 v66, -v66, v69, v68
	v_div_fmas_f32 v66, v66, v67, v69
	v_div_fixup_f32 v49, v66, v49, 1.0
	v_div_scale_f32 v66, s[34:35], v48, v48, 1.0
	v_rcp_f32_e32 v67, v66
	v_lshlrev_b32_e32 v64, 16, v113
	v_and_b32_e32 v65, 0xffff0000, v113
	v_cvt_pk_bf16_f32 v3, v74, v75
	v_fma_f32 v68, -v66, v67, 1.0
	v_fmac_f32_e32 v67, v68, v67
	v_div_scale_f32 v68, vcc, 1.0, v48, 1.0
	v_mul_f32_e32 v69, v68, v67
	v_fma_f32 v70, -v66, v69, v68
	v_fmac_f32_e32 v69, v70, v67
	v_fma_f32 v66, -v66, v69, v68
	v_div_fmas_f32 v66, v66, v67, v69
	v_div_fixup_f32 v48, v66, v48, 1.0
	v_lshlrev_b32_e32 v68, 16, v174
	v_and_b32_e32 v69, 0xffff0000, v174
	v_pk_mul_f32 v[66:67], v[48:49], v[64:65]
	v_pk_fma_f32 v[48:49], v[48:49], v[64:65], v[68:69]
	v_div_scale_f32 v64, s[34:35], v51, v51, 1.0
	v_rcp_f32_e32 v65, v64
	v_cndmask_b32_e64 v48, v48, v66, s[0:1]
	v_cndmask_b32_e64 v49, v49, v67, s[0:1]
	v_cvt_pk_bf16_f32 v174, v48, v49
	v_fma_f32 v66, -v64, v65, 1.0
	v_fmac_f32_e32 v65, v66, v65
	v_div_scale_f32 v66, vcc, 1.0, v51, 1.0
	v_mul_f32_e32 v67, v66, v65
	v_fma_f32 v68, -v64, v67, v66
	v_fmac_f32_e32 v67, v68, v65
	v_fma_f32 v64, -v64, v67, v66
	v_div_fmas_f32 v64, v64, v65, v67
	v_div_fixup_f32 v51, v64, v51, 1.0
	v_div_scale_f32 v64, s[34:35], v50, v50, 1.0
	v_rcp_f32_e32 v65, v64
	v_lshlrev_b32_e32 v48, 16, v112
	v_and_b32_e32 v49, 0xffff0000, v112
	v_cvt_pk_bf16_f32 v2, v76, v77
	v_fma_f32 v66, -v64, v65, 1.0
	v_fmac_f32_e32 v65, v66, v65
	v_div_scale_f32 v66, vcc, 1.0, v50, 1.0
	v_mul_f32_e32 v67, v66, v65
	v_fma_f32 v68, -v64, v67, v66
	v_fmac_f32_e32 v67, v68, v65
	v_fma_f32 v64, -v64, v67, v66
	v_div_fmas_f32 v64, v64, v65, v67
	v_div_fixup_f32 v50, v64, v50, 1.0
	v_lshlrev_b32_e32 v66, 16, v175
	v_and_b32_e32 v67, 0xffff0000, v175
	v_pk_mul_f32 v[64:65], v[50:51], v[48:49]
	v_pk_fma_f32 v[48:49], v[50:51], v[48:49], v[66:67]
	v_mul_f32_e32 v50, v236, v52
	v_mul_f32_e32 v51, v236, v53
	v_exp_f32_e32 v50, v50
	v_exp_f32_e32 v51, v51
	v_cndmask_b32_e64 v48, v48, v64, s[0:1]
	v_cndmask_b32_e64 v49, v49, v65, s[0:1]
	v_cvt_pk_bf16_f32 v175, v48, v49
	v_pk_add_f32 v[50:51], v[50:51], 1.0 op_sel_hi:[1,0]
	v_lshlrev_b32_e32 v48, 16, v101
	v_div_scale_f32 v52, s[34:35], v51, v51, 1.0
	v_rcp_f32_e32 v53, v52
	v_and_b32_e32 v49, 0xffff0000, v101
	v_cvt_pk_bf16_f32 v0, v78, v79
	s_add_i32 s8, s8, 1
	v_fma_f32 v64, -v52, v53, 1.0
	v_fmac_f32_e32 v53, v64, v53
	v_div_scale_f32 v64, vcc, 1.0, v51, 1.0
	v_mul_f32_e32 v65, v64, v53
	v_fma_f32 v66, -v52, v65, v64
	v_fmac_f32_e32 v65, v66, v53
	v_fma_f32 v52, -v52, v65, v64
	v_div_fmas_f32 v52, v52, v53, v65
; DI unsigned pack2(float a, float b) { f2_t v = {a, b}; bf2_t r = __builtin_convertvector(v, bf2_t); return __builtin_bit_cast(unsigned, r); }
; __global__ void __launch_bounds__(512) mega(Params p) {
;     ...
; #pragma unroll
;           for (int fb = 0; fb < 4; ++fb)
; #pragma unroll
;             for (int i = 0; i < 8; ++i) {
;               const float b0 = __uint_as_float(bp[fb][i] << 16), b1 = __uint_as_float(bp[fb][i] & 0xffff0000u);
;               const float g0 = 1.f / (1.f + __builtin_amdgcn_exp2f(nr1 * acc[fb][2 * i]));
;               const float g1 = 1.f / (1.f + __builtin_amdgcn_exp2f(nr1 * acc[fb][2 * i + 1]));
;               float y0 = g0 * b0, y1 = g1 * b1;
;               if (n > 0) { y0 += __uint_as_float(yp[fb][i] << 16); y1 += __uint_as_float(yp[fb][i] & 0xffff0000u); }
;               yp[fb][i] = pack2(y0, y1);
	v_div_fixup_f32 v51, v52, v51, 1.0
	v_div_scale_f32 v52, s[34:35], v50, v50, 1.0
	v_rcp_f32_e32 v53, v52
	s_cmp_eq_u32 s8, 3
	v_fma_f32 v64, -v52, v53, 1.0
	v_fmac_f32_e32 v53, v64, v53
	v_div_scale_f32 v64, vcc, 1.0, v50, 1.0
	v_mul_f32_e32 v65, v64, v53
	v_fma_f32 v66, -v52, v65, v64
	v_fmac_f32_e32 v65, v66, v53
	v_fma_f32 v52, -v52, v65, v64
	v_div_fmas_f32 v52, v52, v53, v65
	v_div_fixup_f32 v50, v52, v50, 1.0
	v_lshlrev_b32_e32 v64, 16, v176
	v_and_b32_e32 v65, 0xffff0000, v176
	v_pk_mul_f32 v[52:53], v[50:51], v[48:49]
	v_pk_fma_f32 v[48:49], v[50:51], v[48:49], v[64:65]
	v_mul_f32_e32 v50, v236, v54
	v_mul_f32_e32 v51, v236, v55
	v_exp_f32_e32 v50, v50
	v_exp_f32_e32 v51, v51
	v_cndmask_b32_e64 v48, v48, v52, s[0:1]
	v_cndmask_b32_e64 v49, v49, v53, s[0:1]
	v_cvt_pk_bf16_f32 v176, v48, v49
	v_pk_add_f32 v[50:51], v[50:51], 1.0 op_sel_hi:[1,0]
	v_lshlrev_b32_e32 v48, 16, v100
	v_div_scale_f32 v52, s[34:35], v51, v51, 1.0
	v_rcp_f32_e32 v53, v52
	v_and_b32_e32 v49, 0xffff0000, v100
	v_fma_f32 v54, -v52, v53, 1.0
	v_fmac_f32_e32 v53, v54, v53
	v_div_scale_f32 v54, vcc, 1.0, v51, 1.0
	v_mul_f32_e32 v55, v54, v53
	v_fma_f32 v64, -v52, v55, v54
	v_fmac_f32_e32 v55, v64, v53
	v_fma_f32 v52, -v52, v55, v54
	v_div_fmas_f32 v52, v52, v53, v55
	v_div_fixup_f32 v51, v52, v51, 1.0
	v_div_scale_f32 v52, s[34:35], v50, v50, 1.0
	v_rcp_f32_e32 v53, v52
	s_nop 0
	v_fma_f32 v54, -v52, v53, 1.0
	v_fmac_f32_e32 v53, v54, v53
	v_div_scale_f32 v54, vcc, 1.0, v50, 1.0
	v_mul_f32_e32 v55, v54, v53
	v_fma_f32 v64, -v52, v55, v54
	v_fmac_f32_e32 v55, v64, v53
	v_fma_f32 v52, -v52, v55, v54
	v_div_fmas_f32 v52, v52, v53, v55
	v_div_fixup_f32 v50, v52, v50, 1.0
	v_lshlrev_b32_e32 v54, 16, v177
	v_and_b32_e32 v55, 0xffff0000, v177
	v_pk_mul_f32 v[52:53], v[50:51], v[48:49]
	v_pk_fma_f32 v[48:49], v[50:51], v[48:49], v[54:55]
	v_mul_f32_e32 v50, v236, v56
	v_mul_f32_e32 v51, v236, v57
	v_exp_f32_e32 v50, v50
	v_exp_f32_e32 v51, v51
	v_cndmask_b32_e64 v48, v48, v52, s[0:1]
	v_cndmask_b32_e64 v49, v49, v53, s[0:1]
	v_cvt_pk_bf16_f32 v177, v48, v49
	v_pk_add_f32 v[50:51], v[50:51], 1.0 op_sel_hi:[1,0]
	v_lshlrev_b32_e32 v48, 16, v99
	v_div_scale_f32 v52, s[34:35], v51, v51, 1.0
	v_rcp_f32_e32 v53, v52
	v_and_b32_e32 v49, 0xffff0000, v99
	v_fma_f32 v54, -v52, v53, 1.0
	v_fmac_f32_e32 v53, v54, v53
	v_div_scale_f32 v54, vcc, 1.0, v51, 1.0
	v_mul_f32_e32 v55, v54, v53
	v_fma_f32 v56, -v52, v55, v54
	v_fmac_f32_e32 v55, v56, v53
	v_fma_f32 v52, -v52, v55, v54
	v_div_fmas_f32 v52, v52, v53, v55
	v_div_fixup_f32 v51, v52, v51, 1.0
	v_div_scale_f32 v52, s[34:35], v50, v50, 1.0
	v_rcp_f32_e32 v53, v52
	s_nop 0
	v_fma_f32 v54, -v52, v53, 1.0
	v_fmac_f32_e32 v53, v54, v53
	v_div_scale_f32 v54, vcc, 1.0, v50, 1.0
	v_mul_f32_e32 v55, v54, v53
	v_fma_f32 v56, -v52, v55, v54
	v_fmac_f32_e32 v55, v56, v53
	v_fma_f32 v52, -v52, v55, v54
	v_div_fmas_f32 v52, v52, v53, v55
	v_div_fixup_f32 v50, v52, v50, 1.0
	v_lshlrev_b32_e32 v54, 16, v178
	v_and_b32_e32 v55, 0xffff0000, v178
	v_pk_mul_f32 v[52:53], v[50:51], v[48:49]
	v_pk_fma_f32 v[48:49], v[50:51], v[48:49], v[54:55]
	v_mul_f32_e32 v50, v236, v58
	v_mul_f32_e32 v51, v236, v59
	v_exp_f32_e32 v50, v50
	v_exp_f32_e32 v51, v51
	v_cndmask_b32_e64 v48, v48, v52, s[0:1]
	v_cndmask_b32_e64 v49, v49, v53, s[0:1]
	v_cvt_pk_bf16_f32 v178, v48, v49
	v_pk_add_f32 v[50:51], v[50:51], 1.0 op_sel_hi:[1,0]
	v_lshlrev_b32_e32 v48, 16, v98
	v_div_scale_f32 v52, s[34:35], v51, v51, 1.0
	v_rcp_f32_e32 v53, v52
	v_and_b32_e32 v49, 0xffff0000, v98
	v_fma_f32 v54, -v52, v53, 1.0
	v_fmac_f32_e32 v53, v54, v53
	v_div_scale_f32 v54, vcc, 1.0, v51, 1.0
	v_mul_f32_e32 v55, v54, v53
	v_fma_f32 v56, -v52, v55, v54
	v_fmac_f32_e32 v55, v56, v53
	v_fma_f32 v52, -v52, v55, v54
	v_div_fmas_f32 v52, v52, v53, v55
	v_div_fixup_f32 v51, v52, v51, 1.0
	v_div_scale_f32 v52, s[34:35], v50, v50, 1.0
	v_rcp_f32_e32 v53, v52
	s_nop 0
	v_fma_f32 v54, -v52, v53, 1.0
	v_fmac_f32_e32 v53, v54, v53
	v_div_scale_f32 v54, vcc, 1.0, v50, 1.0
	v_mul_f32_e32 v55, v54, v53
	v_fma_f32 v56, -v52, v55, v54
	v_fmac_f32_e32 v55, v56, v53
	v_fma_f32 v52, -v52, v55, v54
	v_div_fmas_f32 v52, v52, v53, v55
	v_div_fixup_f32 v50, v52, v50, 1.0
	v_lshlrev_b32_e32 v54, 16, v179
	v_and_b32_e32 v55, 0xffff0000, v179
	v_pk_mul_f32 v[52:53], v[50:51], v[48:49]
	v_pk_fma_f32 v[48:49], v[50:51], v[48:49], v[54:55]
	v_mul_f32_e32 v50, v236, v60
	v_mul_f32_e32 v51, v236, v61
	v_exp_f32_e32 v50, v50
	v_exp_f32_e32 v51, v51
	v_cndmask_b32_e64 v48, v48, v52, s[0:1]
	v_cndmask_b32_e64 v49, v49, v53, s[0:1]
	v_cvt_pk_bf16_f32 v179, v48, v49
	v_pk_add_f32 v[50:51], v[50:51], 1.0 op_sel_hi:[1,0]
	v_lshlrev_b32_e32 v48, 16, v97
	v_div_scale_f32 v52, s[34:35], v51, v51, 1.0
	v_rcp_f32_e32 v53, v52
	v_and_b32_e32 v49, 0xffff0000, v97
	v_fma_f32 v54, -v52, v53, 1.0
	v_fmac_f32_e32 v53, v54, v53
	v_div_scale_f32 v54, vcc, 1.0, v51, 1.0
	v_mul_f32_e32 v55, v54, v53
	v_fma_f32 v56, -v52, v55, v54
	v_fmac_f32_e32 v55, v56, v53
	v_fma_f32 v52, -v52, v55, v54
	v_div_fmas_f32 v52, v52, v53, v55
	v_div_fixup_f32 v51, v52, v51, 1.0
	v_div_scale_f32 v52, s[34:35], v50, v50, 1.0
	v_rcp_f32_e32 v53, v52
	s_nop 0
	v_fma_f32 v54, -v52, v53, 1.0
	v_fmac_f32_e32 v53, v54, v53
	v_div_scale_f32 v54, vcc, 1.0, v50, 1.0
	v_mul_f32_e32 v55, v54, v53
	v_fma_f32 v56, -v52, v55, v54
	v_fmac_f32_e32 v55, v56, v53
	v_fma_f32 v52, -v52, v55, v54
	v_div_fmas_f32 v52, v52, v53, v55
	v_div_fixup_f32 v50, v52, v50, 1.0
	v_lshlrev_b32_e32 v54, 16, v164
	v_and_b32_e32 v55, 0xffff0000, v164
	v_pk_mul_f32 v[52:53], v[50:51], v[48:49]
	v_pk_fma_f32 v[48:49], v[50:51], v[48:49], v[54:55]
	v_mul_f32_e32 v50, v236, v62
	v_mul_f32_e32 v51, v236, v63
; DI unsigned pack2(float a, float b) { f2_t v = {a, b}; bf2_t r = __builtin_convertvector(v, bf2_t); return __builtin_bit_cast(unsigned, r); }
; __global__ void __launch_bounds__(512) mega(Params p) {
;     ...
; #pragma unroll
;           for (int fb = 0; fb < 4; ++fb)
; #pragma unroll
;             for (int i = 0; i < 8; ++i) {
;               const float b0 = __uint_as_float(bp[fb][i] << 16), b1 = __uint_as_float(bp[fb][i] & 0xffff0000u);
;               const float g0 = 1.f / (1.f + __builtin_amdgcn_exp2f(nr1 * acc[fb][2 * i]));
;               const float g1 = 1.f / (1.f + __builtin_amdgcn_exp2f(nr1 * acc[fb][2 * i + 1]));
;               float y0 = g0 * b0, y1 = g1 * b1;
;               if (n > 0) { y0 += __uint_as_float(yp[fb][i] << 16); y1 += __uint_as_float(yp[fb][i] & 0xffff0000u); }
;               yp[fb][i] = pack2(y0, y1);
	v_exp_f32_e32 v50, v50
	v_exp_f32_e32 v51, v51
	v_cndmask_b32_e64 v48, v48, v52, s[0:1]
	v_cndmask_b32_e64 v49, v49, v53, s[0:1]
	v_cvt_pk_bf16_f32 v164, v48, v49
	v_pk_add_f32 v[50:51], v[50:51], 1.0 op_sel_hi:[1,0]
	v_lshlrev_b32_e32 v48, 16, v96
	v_div_scale_f32 v52, s[34:35], v51, v51, 1.0
	v_rcp_f32_e32 v53, v52
	v_and_b32_e32 v49, 0xffff0000, v96
	v_fma_f32 v54, -v52, v53, 1.0
	v_fmac_f32_e32 v53, v54, v53
	v_div_scale_f32 v54, vcc, 1.0, v51, 1.0
	v_mul_f32_e32 v55, v54, v53
	v_fma_f32 v56, -v52, v55, v54
	v_fmac_f32_e32 v55, v56, v53
	v_fma_f32 v52, -v52, v55, v54
	v_div_fmas_f32 v52, v52, v53, v55
	v_div_fixup_f32 v51, v52, v51, 1.0
	v_div_scale_f32 v52, s[34:35], v50, v50, 1.0
	v_rcp_f32_e32 v53, v52
	s_nop 0
	v_fma_f32 v54, -v52, v53, 1.0
	v_fmac_f32_e32 v53, v54, v53
	v_div_scale_f32 v54, vcc, 1.0, v50, 1.0
	v_mul_f32_e32 v55, v54, v53
	v_fma_f32 v56, -v52, v55, v54
	v_fmac_f32_e32 v55, v56, v53
	v_fma_f32 v52, -v52, v55, v54
	v_div_fmas_f32 v52, v52, v53, v55
	v_div_fixup_f32 v50, v52, v50, 1.0
	v_lshlrev_b32_e32 v54, 16, v165
	v_and_b32_e32 v55, 0xffff0000, v165
	v_pk_mul_f32 v[52:53], v[50:51], v[48:49]
	v_pk_fma_f32 v[48:49], v[50:51], v[48:49], v[54:55]
	v_div_scale_f32 v50, s[34:35], v33, v33, 1.0
	v_rcp_f32_e32 v51, v50
	v_cndmask_b32_e64 v48, v48, v52, s[0:1]
	v_cndmask_b32_e64 v49, v49, v53, s[0:1]
	v_cvt_pk_bf16_f32 v165, v48, v49
	v_fma_f32 v52, -v50, v51, 1.0
	v_fmac_f32_e32 v51, v52, v51
	v_div_scale_f32 v52, vcc, 1.0, v33, 1.0
	v_mul_f32_e32 v53, v52, v51
	v_fma_f32 v54, -v50, v53, v52
	v_fmac_f32_e32 v53, v54, v51
	v_fma_f32 v50, -v50, v53, v52
	v_div_fmas_f32 v50, v50, v51, v53
	v_div_fixup_f32 v33, v50, v33, 1.0
	v_div_scale_f32 v50, s[34:35], v32, v32, 1.0
	v_rcp_f32_e32 v51, v50
	v_lshlrev_b32_e32 v48, 16, v80
	v_and_b32_e32 v49, 0xffff0000, v80
	v_fma_f32 v52, -v50, v51, 1.0
	v_fmac_f32_e32 v51, v52, v51
	v_div_scale_f32 v52, vcc, 1.0, v32, 1.0
	v_mul_f32_e32 v53, v52, v51
	v_fma_f32 v54, -v50, v53, v52
	v_fmac_f32_e32 v53, v54, v51
	v_fma_f32 v50, -v50, v53, v52
	v_div_fmas_f32 v50, v50, v51, v53
	v_div_fixup_f32 v32, v50, v32, 1.0
	v_lshlrev_b32_e32 v52, 16, v162
	v_and_b32_e32 v53, 0xffff0000, v162
	v_pk_mul_f32 v[50:51], v[32:33], v[48:49]
	v_pk_fma_f32 v[32:33], v[32:33], v[48:49], v[52:53]
	s_nop 0
	v_cndmask_b32_e64 v33, v33, v51, s[0:1]
	v_cndmask_b32_e64 v32, v32, v50, s[0:1]
	v_cvt_pk_bf16_f32 v162, v32, v33
	v_lshlrev_b32_e32 v32, 16, v15
	v_and_b32_e32 v33, 0xffff0000, v15
	v_mul_f32_e32 v15, v236, v34
	v_exp_f32_e32 v34, v15
	v_mul_f32_e32 v15, v236, v35
	v_exp_f32_e32 v35, v15
	s_nop 0
	v_pk_add_f32 v[34:35], v[34:35], 1.0 op_sel_hi:[1,0]
	s_nop 0
	v_div_scale_f32 v15, s[34:35], v35, v35, 1.0
	v_rcp_f32_e32 v48, v15
	s_nop 0
	v_fma_f32 v49, -v15, v48, 1.0
	v_fmac_f32_e32 v48, v49, v48
	v_div_scale_f32 v49, vcc, 1.0, v35, 1.0
	v_mul_f32_e32 v50, v49, v48
	v_fma_f32 v51, -v15, v50, v49
	v_fmac_f32_e32 v50, v51, v48
	v_fma_f32 v15, -v15, v50, v49
	v_div_fmas_f32 v15, v15, v48, v50
	v_div_fixup_f32 v35, v15, v35, 1.0
	v_div_scale_f32 v15, s[34:35], v34, v34, 1.0
	v_rcp_f32_e32 v48, v15
	s_nop 0
	v_fma_f32 v49, -v15, v48, 1.0
	v_fmac_f32_e32 v48, v49, v48
	v_div_scale_f32 v49, vcc, 1.0, v34, 1.0
	v_mul_f32_e32 v50, v49, v48
	v_fma_f32 v51, -v15, v50, v49
	v_fmac_f32_e32 v50, v51, v48
	v_fma_f32 v15, -v15, v50, v49
	v_div_fmas_f32 v15, v15, v48, v50
	v_div_fixup_f32 v34, v15, v34, 1.0
	v_lshlrev_b32_e32 v50, 16, v163
	v_and_b32_e32 v51, 0xffff0000, v163
	v_pk_mul_f32 v[48:49], v[34:35], v[32:33]
	v_pk_fma_f32 v[32:33], v[34:35], v[32:33], v[50:51]
	s_nop 0
	v_cndmask_b32_e64 v15, v33, v49, s[0:1]
	v_cndmask_b32_e64 v32, v32, v48, s[0:1]
	v_cvt_pk_bf16_f32 v163, v32, v15
	v_lshlrev_b32_e32 v32, 16, v14
	v_and_b32_e32 v33, 0xffff0000, v14
	v_mul_f32_e32 v14, v236, v36
	v_mul_f32_e32 v15, v236, v37
	v_exp_f32_e32 v14, v14
	v_exp_f32_e32 v15, v15
	s_nop 0
	v_pk_add_f32 v[14:15], v[14:15], 1.0 op_sel_hi:[1,0]
	s_nop 0
	v_div_scale_f32 v34, s[34:35], v15, v15, 1.0
	v_rcp_f32_e32 v35, v34
	s_nop 0
	v_fma_f32 v36, -v34, v35, 1.0
	v_fmac_f32_e32 v35, v36, v35
	v_div_scale_f32 v36, vcc, 1.0, v15, 1.0
	v_mul_f32_e32 v37, v36, v35
	v_fma_f32 v48, -v34, v37, v36
	v_fmac_f32_e32 v37, v48, v35
	v_fma_f32 v34, -v34, v37, v36
	v_div_fmas_f32 v34, v34, v35, v37
	v_div_fixup_f32 v15, v34, v15, 1.0
	v_div_scale_f32 v34, s[34:35], v14, v14, 1.0
	v_rcp_f32_e32 v35, v34
	s_nop 0
	v_fma_f32 v36, -v34, v35, 1.0
	v_fmac_f32_e32 v35, v36, v35
	v_div_scale_f32 v36, vcc, 1.0, v14, 1.0
	v_mul_f32_e32 v37, v36, v35
	v_fma_f32 v48, -v34, v37, v36
	v_fmac_f32_e32 v37, v48, v35
	v_fma_f32 v34, -v34, v37, v36
	v_div_fmas_f32 v34, v34, v35, v37
	v_div_fixup_f32 v14, v34, v14, 1.0
	v_lshlrev_b32_e32 v36, 16, v160
	v_and_b32_e32 v37, 0xffff0000, v160
	v_pk_mul_f32 v[34:35], v[14:15], v[32:33]
	v_pk_fma_f32 v[14:15], v[14:15], v[32:33], v[36:37]
	s_nop 0
	v_cndmask_b32_e64 v15, v15, v35, s[0:1]
	v_cndmask_b32_e64 v14, v14, v34, s[0:1]
	v_cvt_pk_bf16_f32 v160, v14, v15
	v_lshlrev_b32_e32 v14, 16, v13
	v_and_b32_e32 v15, 0xffff0000, v13
	v_mul_f32_e32 v13, v236, v38
	v_exp_f32_e32 v32, v13
	v_mul_f32_e32 v13, v236, v39
	v_exp_f32_e32 v33, v13
	s_nop 0
	v_pk_add_f32 v[32:33], v[32:33], 1.0 op_sel_hi:[1,0]
	s_nop 0
	v_div_scale_f32 v13, s[34:35], v33, v33, 1.0
	v_rcp_f32_e32 v34, v13
	s_nop 0
	v_fma_f32 v35, -v13, v34, 1.0
	v_fmac_f32_e32 v34, v35, v34
	v_div_scale_f32 v35, vcc, 1.0, v33, 1.0
	v_mul_f32_e32 v36, v35, v34
	v_fma_f32 v37, -v13, v36, v35
	v_fmac_f32_e32 v36, v37, v34
	v_fma_f32 v13, -v13, v36, v35
	v_div_fmas_f32 v13, v13, v34, v36
	v_div_fixup_f32 v33, v13, v33, 1.0
	v_div_scale_f32 v13, s[34:35], v32, v32, 1.0
; DI unsigned pack2(float a, float b) { f2_t v = {a, b}; bf2_t r = __builtin_convertvector(v, bf2_t); return __builtin_bit_cast(unsigned, r); }
; __global__ void __launch_bounds__(512) mega(Params p) {
;     ...
;           for (int fb = 0; fb < 4; ++fb)
; #pragma unroll
;             for (int i = 0; i < 8; ++i) {
;               const float b0 = __uint_as_float(bp[fb][i] << 16), b1 = __uint_as_float(bp[fb][i] & 0xffff0000u);
;               const float g0 = 1.f / (1.f + __builtin_amdgcn_exp2f(nr1 * acc[fb][2 * i]));
;               const float g1 = 1.f / (1.f + __builtin_amdgcn_exp2f(nr1 * acc[fb][2 * i + 1]));
;               float y0 = g0 * b0, y1 = g1 * b1;
;               if (n > 0) { y0 += __uint_as_float(yp[fb][i] << 16); y1 += __uint_as_float(yp[fb][i] & 0xffff0000u); }
;               yp[fb][i] = pack2(y0, y1);
;             }
	v_rcp_f32_e32 v34, v13
	s_nop 0
	v_fma_f32 v35, -v13, v34, 1.0
	v_fmac_f32_e32 v34, v35, v34
	v_div_scale_f32 v35, vcc, 1.0, v32, 1.0
	v_mul_f32_e32 v36, v35, v34
	v_fma_f32 v37, -v13, v36, v35
	v_fmac_f32_e32 v36, v37, v34
	v_fma_f32 v13, -v13, v36, v35
	v_div_fmas_f32 v13, v13, v34, v36
	v_div_fixup_f32 v32, v13, v32, 1.0
	v_lshlrev_b32_e32 v36, 16, v161
	v_and_b32_e32 v37, 0xffff0000, v161
	v_pk_mul_f32 v[34:35], v[32:33], v[14:15]
	v_pk_fma_f32 v[14:15], v[32:33], v[14:15], v[36:37]
	s_nop 0
	v_cndmask_b32_e64 v13, v15, v35, s[0:1]
	v_cndmask_b32_e64 v14, v14, v34, s[0:1]
	v_cvt_pk_bf16_f32 v161, v14, v13
	v_lshlrev_b32_e32 v14, 16, v12
	v_and_b32_e32 v15, 0xffff0000, v12
	v_mul_f32_e32 v12, v236, v40
	v_mul_f32_e32 v13, v236, v41
	v_exp_f32_e32 v12, v12
	v_exp_f32_e32 v13, v13
	s_nop 0
	v_pk_add_f32 v[12:13], v[12:13], 1.0 op_sel_hi:[1,0]
	s_nop 0
	v_div_scale_f32 v32, s[34:35], v13, v13, 1.0
	v_rcp_f32_e32 v33, v32
	s_nop 0
	v_fma_f32 v34, -v32, v33, 1.0
	v_fmac_f32_e32 v33, v34, v33
	v_div_scale_f32 v34, vcc, 1.0, v13, 1.0
	v_mul_f32_e32 v35, v34, v33
	v_fma_f32 v36, -v32, v35, v34
	v_fmac_f32_e32 v35, v36, v33
	v_fma_f32 v32, -v32, v35, v34
	v_div_fmas_f32 v32, v32, v33, v35
	v_div_fixup_f32 v13, v32, v13, 1.0
	v_div_scale_f32 v32, s[34:35], v12, v12, 1.0
	v_rcp_f32_e32 v33, v32
	s_nop 0
	v_fma_f32 v34, -v32, v33, 1.0
	v_fmac_f32_e32 v33, v34, v33
	v_div_scale_f32 v34, vcc, 1.0, v12, 1.0
	v_mul_f32_e32 v35, v34, v33
	v_fma_f32 v36, -v32, v35, v34
	v_fmac_f32_e32 v35, v36, v33
	v_fma_f32 v32, -v32, v35, v34
	v_div_fmas_f32 v32, v32, v33, v35
	v_div_fixup_f32 v12, v32, v12, 1.0
	v_lshlrev_b32_e32 v34, 16, v158
	v_and_b32_e32 v35, 0xffff0000, v158
	v_pk_mul_f32 v[32:33], v[12:13], v[14:15]
	v_pk_fma_f32 v[12:13], v[12:13], v[14:15], v[34:35]
	s_nop 0
	v_cndmask_b32_e64 v13, v13, v33, s[0:1]
	v_cndmask_b32_e64 v12, v12, v32, s[0:1]
	v_cvt_pk_bf16_f32 v158, v12, v13
	v_lshlrev_b32_e32 v12, 16, v11
	v_and_b32_e32 v13, 0xffff0000, v11
	v_mul_f32_e32 v11, v236, v42
	v_exp_f32_e32 v14, v11
	v_mul_f32_e32 v11, v236, v43
	v_exp_f32_e32 v15, v11
	s_nop 0
	v_pk_add_f32 v[14:15], v[14:15], 1.0 op_sel_hi:[1,0]
	s_nop 0
	v_div_scale_f32 v11, s[34:35], v15, v15, 1.0
	v_rcp_f32_e32 v32, v11
	s_nop 0
	v_fma_f32 v33, -v11, v32, 1.0
	v_fmac_f32_e32 v32, v33, v32
	v_div_scale_f32 v33, vcc, 1.0, v15, 1.0
	v_mul_f32_e32 v34, v33, v32
	v_fma_f32 v35, -v11, v34, v33
	v_fmac_f32_e32 v34, v35, v32
	v_fma_f32 v11, -v11, v34, v33
	v_div_fmas_f32 v11, v11, v32, v34
	v_div_fixup_f32 v15, v11, v15, 1.0
	v_div_scale_f32 v11, s[34:35], v14, v14, 1.0
	v_rcp_f32_e32 v32, v11
	s_nop 0
	v_fma_f32 v33, -v11, v32, 1.0
	v_fmac_f32_e32 v32, v33, v32
	v_div_scale_f32 v33, vcc, 1.0, v14, 1.0
	v_mul_f32_e32 v34, v33, v32
	v_fma_f32 v35, -v11, v34, v33
	v_fmac_f32_e32 v34, v35, v32
	v_fma_f32 v11, -v11, v34, v33
	v_div_fmas_f32 v11, v11, v32, v34
	v_div_fixup_f32 v14, v11, v14, 1.0
	v_lshlrev_b32_e32 v34, 16, v159
	v_and_b32_e32 v35, 0xffff0000, v159
	v_pk_mul_f32 v[32:33], v[14:15], v[12:13]
	v_pk_fma_f32 v[12:13], v[14:15], v[12:13], v[34:35]
	s_nop 0
	v_cndmask_b32_e64 v11, v13, v33, s[0:1]
	v_cndmask_b32_e64 v12, v12, v32, s[0:1]
	v_cvt_pk_bf16_f32 v159, v12, v11
	v_lshlrev_b32_e32 v12, 16, v10
	v_and_b32_e32 v13, 0xffff0000, v10
	v_mul_f32_e32 v10, v236, v44
	v_mul_f32_e32 v11, v236, v45
	v_exp_f32_e32 v10, v10
	v_exp_f32_e32 v11, v11
	s_nop 0
	v_pk_add_f32 v[10:11], v[10:11], 1.0 op_sel_hi:[1,0]
	s_nop 0
	v_div_scale_f32 v14, s[34:35], v11, v11, 1.0
	v_rcp_f32_e32 v15, v14
	s_nop 0
	v_fma_f32 v32, -v14, v15, 1.0
	v_fmac_f32_e32 v15, v32, v15
	v_div_scale_f32 v32, vcc, 1.0, v11, 1.0
	v_mul_f32_e32 v33, v32, v15
	v_fma_f32 v34, -v14, v33, v32
	v_fmac_f32_e32 v33, v34, v15
	v_fma_f32 v14, -v14, v33, v32
	v_div_fmas_f32 v14, v14, v15, v33
	v_div_fixup_f32 v11, v14, v11, 1.0
	v_div_scale_f32 v14, s[34:35], v10, v10, 1.0
	v_rcp_f32_e32 v15, v14
	s_nop 0
	v_fma_f32 v32, -v14, v15, 1.0
	v_fmac_f32_e32 v15, v32, v15
	v_div_scale_f32 v32, vcc, 1.0, v10, 1.0
	v_mul_f32_e32 v33, v32, v15
	v_fma_f32 v34, -v14, v33, v32
	v_fmac_f32_e32 v33, v34, v15
	v_fma_f32 v14, -v14, v33, v32
	v_div_fmas_f32 v14, v14, v15, v33
	v_div_fixup_f32 v10, v14, v10, 1.0
	v_lshlrev_b32_e32 v32, 16, v156
	v_and_b32_e32 v33, 0xffff0000, v156
	v_pk_mul_f32 v[14:15], v[10:11], v[12:13]
	v_pk_fma_f32 v[10:11], v[10:11], v[12:13], v[32:33]
	s_nop 0
	v_cndmask_b32_e64 v11, v11, v15, s[0:1]
	v_cndmask_b32_e64 v10, v10, v14, s[0:1]
	v_cvt_pk_bf16_f32 v156, v10, v11
	v_lshlrev_b32_e32 v10, 16, v9
	v_and_b32_e32 v11, 0xffff0000, v9
	v_mul_f32_e32 v9, v236, v46
	v_exp_f32_e32 v12, v9
	v_mul_f32_e32 v9, v236, v47
	v_exp_f32_e32 v13, v9
	s_nop 0
	v_pk_add_f32 v[12:13], v[12:13], 1.0 op_sel_hi:[1,0]
	s_nop 0
	v_div_scale_f32 v9, s[34:35], v13, v13, 1.0
	v_rcp_f32_e32 v14, v9
	s_nop 0
	v_fma_f32 v15, -v9, v14, 1.0
	v_fmac_f32_e32 v14, v15, v14
	v_div_scale_f32 v15, vcc, 1.0, v13, 1.0
	v_mul_f32_e32 v32, v15, v14
	v_fma_f32 v33, -v9, v32, v15
	v_fmac_f32_e32 v32, v33, v14
	v_fma_f32 v9, -v9, v32, v15
	v_div_fmas_f32 v9, v9, v14, v32
	v_div_fixup_f32 v13, v9, v13, 1.0
	v_div_scale_f32 v9, s[34:35], v12, v12, 1.0
	v_rcp_f32_e32 v14, v9
	s_nop 0
	v_fma_f32 v15, -v9, v14, 1.0
	v_fmac_f32_e32 v14, v15, v14
	v_div_scale_f32 v15, vcc, 1.0, v12, 1.0
	v_mul_f32_e32 v32, v15, v14
	v_fma_f32 v33, -v9, v32, v15
	v_fmac_f32_e32 v32, v33, v14
	v_fma_f32 v9, -v9, v32, v15
	v_div_fmas_f32 v9, v9, v14, v32
	v_div_fixup_f32 v12, v9, v12, 1.0
	v_lshlrev_b32_e32 v32, 16, v157
	v_and_b32_e32 v33, 0xffff0000, v157
	v_pk_mul_f32 v[14:15], v[12:13], v[10:11]
	v_pk_fma_f32 v[10:11], v[12:13], v[10:11], v[32:33]
	s_nop 0
	v_cndmask_b32_e64 v9, v11, v15, s[0:1]
; DI unsigned pack2(float a, float b) { f2_t v = {a, b}; bf2_t r = __builtin_convertvector(v, bf2_t); return __builtin_bit_cast(unsigned, r); }
; __global__ void __launch_bounds__(512) mega(Params p) {
;     ...
;           for (int fb = 0; fb < 4; ++fb)
; #pragma unroll
;             for (int i = 0; i < 8; ++i) {
;               const float b0 = __uint_as_float(bp[fb][i] << 16), b1 = __uint_as_float(bp[fb][i] & 0xffff0000u);
;               const float g0 = 1.f / (1.f + __builtin_amdgcn_exp2f(nr1 * acc[fb][2 * i]));
;               const float g1 = 1.f / (1.f + __builtin_amdgcn_exp2f(nr1 * acc[fb][2 * i + 1]));
;               float y0 = g0 * b0, y1 = g1 * b1;
;               if (n > 0) { y0 += __uint_as_float(yp[fb][i] << 16); y1 += __uint_as_float(yp[fb][i] & 0xffff0000u); }
;               yp[fb][i] = pack2(y0, y1);
;             }
	v_cndmask_b32_e64 v10, v10, v14, s[0:1]
	v_cvt_pk_bf16_f32 v157, v10, v9
	v_lshlrev_b32_e32 v10, 16, v8
	v_and_b32_e32 v11, 0xffff0000, v8
	v_mul_f32_e32 v8, v236, v16
	v_mul_f32_e32 v9, v236, v17
	v_exp_f32_e32 v8, v8
	v_exp_f32_e32 v9, v9
	s_nop 0
	v_pk_add_f32 v[8:9], v[8:9], 1.0 op_sel_hi:[1,0]
	s_nop 0
	v_div_scale_f32 v12, s[34:35], v9, v9, 1.0
	v_rcp_f32_e32 v13, v12
	s_nop 0
	v_fma_f32 v14, -v12, v13, 1.0
	v_fmac_f32_e32 v13, v14, v13
	v_div_scale_f32 v14, vcc, 1.0, v9, 1.0
	v_mul_f32_e32 v15, v14, v13
	v_fma_f32 v16, -v12, v15, v14
	v_fmac_f32_e32 v15, v16, v13
	v_fma_f32 v12, -v12, v15, v14
	v_div_fmas_f32 v12, v12, v13, v15
	v_div_fixup_f32 v9, v12, v9, 1.0
	v_div_scale_f32 v12, s[34:35], v8, v8, 1.0
	v_rcp_f32_e32 v13, v12
	s_nop 0
	v_fma_f32 v14, -v12, v13, 1.0
	v_fmac_f32_e32 v13, v14, v13
	v_div_scale_f32 v14, vcc, 1.0, v8, 1.0
	v_mul_f32_e32 v15, v14, v13
	v_fma_f32 v16, -v12, v15, v14
	v_fmac_f32_e32 v15, v16, v13
	v_fma_f32 v12, -v12, v15, v14
	v_div_fmas_f32 v12, v12, v13, v15
	v_div_fixup_f32 v8, v12, v8, 1.0
	v_lshlrev_b32_e32 v14, 16, v154
	v_and_b32_e32 v15, 0xffff0000, v154
	v_pk_mul_f32 v[12:13], v[8:9], v[10:11]
	v_pk_fma_f32 v[8:9], v[8:9], v[10:11], v[14:15]
	s_nop 0
	v_cndmask_b32_e64 v9, v9, v13, s[0:1]
	v_cndmask_b32_e64 v8, v8, v12, s[0:1]
	v_cvt_pk_bf16_f32 v154, v8, v9
	v_lshlrev_b32_e32 v8, 16, v7
	v_and_b32_e32 v9, 0xffff0000, v7
	v_mul_f32_e32 v7, v236, v18
	v_exp_f32_e32 v10, v7
	v_mul_f32_e32 v7, v236, v19
	v_exp_f32_e32 v11, v7
	s_nop 0
	v_pk_add_f32 v[10:11], v[10:11], 1.0 op_sel_hi:[1,0]
	s_nop 0
	v_div_scale_f32 v7, s[34:35], v11, v11, 1.0
	v_rcp_f32_e32 v12, v7
	s_nop 0
	v_fma_f32 v13, -v7, v12, 1.0
	v_fmac_f32_e32 v12, v13, v12
	v_div_scale_f32 v13, vcc, 1.0, v11, 1.0
	v_mul_f32_e32 v14, v13, v12
	v_fma_f32 v15, -v7, v14, v13
	v_fmac_f32_e32 v14, v15, v12
	v_fma_f32 v7, -v7, v14, v13
	v_div_fmas_f32 v7, v7, v12, v14
	v_div_fixup_f32 v11, v7, v11, 1.0
	v_div_scale_f32 v7, s[34:35], v10, v10, 1.0
	v_rcp_f32_e32 v12, v7
	s_nop 0
	v_fma_f32 v13, -v7, v12, 1.0
	v_fmac_f32_e32 v12, v13, v12
	v_div_scale_f32 v13, vcc, 1.0, v10, 1.0
	v_mul_f32_e32 v14, v13, v12
	v_fma_f32 v15, -v7, v14, v13
	v_fmac_f32_e32 v14, v15, v12
	v_fma_f32 v7, -v7, v14, v13
	v_div_fmas_f32 v7, v7, v12, v14
	v_div_fixup_f32 v10, v7, v10, 1.0
	v_lshlrev_b32_e32 v14, 16, v155
	v_and_b32_e32 v15, 0xffff0000, v155
	v_pk_mul_f32 v[12:13], v[10:11], v[8:9]
	v_pk_fma_f32 v[8:9], v[10:11], v[8:9], v[14:15]
	s_nop 0
	v_cndmask_b32_e64 v7, v9, v13, s[0:1]
	v_cndmask_b32_e64 v8, v8, v12, s[0:1]
	v_cvt_pk_bf16_f32 v155, v8, v7
	v_lshlrev_b32_e32 v8, 16, v6
	v_and_b32_e32 v9, 0xffff0000, v6
	v_mul_f32_e32 v6, v236, v20
	v_mul_f32_e32 v7, v236, v21
	v_exp_f32_e32 v6, v6
	v_exp_f32_e32 v7, v7
	s_nop 0
	v_pk_add_f32 v[6:7], v[6:7], 1.0 op_sel_hi:[1,0]
	s_nop 0
	v_div_scale_f32 v10, s[34:35], v7, v7, 1.0
	v_rcp_f32_e32 v11, v10
	s_nop 0
	v_fma_f32 v12, -v10, v11, 1.0
	v_fmac_f32_e32 v11, v12, v11
	v_div_scale_f32 v12, vcc, 1.0, v7, 1.0
	v_mul_f32_e32 v13, v12, v11
	v_fma_f32 v14, -v10, v13, v12
	v_fmac_f32_e32 v13, v14, v11
	v_fma_f32 v10, -v10, v13, v12
	v_div_fmas_f32 v10, v10, v11, v13
	v_div_fixup_f32 v7, v10, v7, 1.0
	v_div_scale_f32 v10, s[34:35], v6, v6, 1.0
	v_rcp_f32_e32 v11, v10
	s_nop 0
	v_fma_f32 v12, -v10, v11, 1.0
	v_fmac_f32_e32 v11, v12, v11
	v_div_scale_f32 v12, vcc, 1.0, v6, 1.0
	v_mul_f32_e32 v13, v12, v11
	v_fma_f32 v14, -v10, v13, v12
	v_fmac_f32_e32 v13, v14, v11
	v_fma_f32 v10, -v10, v13, v12
	v_div_fmas_f32 v10, v10, v11, v13
	v_div_fixup_f32 v6, v10, v6, 1.0
	v_lshlrev_b32_e32 v12, 16, v152
	v_and_b32_e32 v13, 0xffff0000, v152
	v_pk_mul_f32 v[10:11], v[6:7], v[8:9]
	v_pk_fma_f32 v[6:7], v[6:7], v[8:9], v[12:13]
	s_nop 0
	v_cndmask_b32_e64 v7, v7, v11, s[0:1]
	v_cndmask_b32_e64 v6, v6, v10, s[0:1]
	v_cvt_pk_bf16_f32 v152, v6, v7
	v_lshlrev_b32_e32 v6, 16, v5
	v_and_b32_e32 v7, 0xffff0000, v5
	v_mul_f32_e32 v5, v236, v22
	v_exp_f32_e32 v8, v5
	v_mul_f32_e32 v5, v236, v23
	v_exp_f32_e32 v9, v5
	s_nop 0
	v_pk_add_f32 v[8:9], v[8:9], 1.0 op_sel_hi:[1,0]
	s_nop 0
	v_div_scale_f32 v5, s[34:35], v9, v9, 1.0
	v_rcp_f32_e32 v10, v5
	s_nop 0
	v_fma_f32 v11, -v5, v10, 1.0
	v_fmac_f32_e32 v10, v11, v10
	v_div_scale_f32 v11, vcc, 1.0, v9, 1.0
	v_mul_f32_e32 v12, v11, v10
	v_fma_f32 v13, -v5, v12, v11
	v_fmac_f32_e32 v12, v13, v10
	v_fma_f32 v5, -v5, v12, v11
	v_div_fmas_f32 v5, v5, v10, v12
	v_div_fixup_f32 v9, v5, v9, 1.0
	v_div_scale_f32 v5, s[34:35], v8, v8, 1.0
	v_rcp_f32_e32 v10, v5
	s_nop 0
	v_fma_f32 v11, -v5, v10, 1.0
	v_fmac_f32_e32 v10, v11, v10
	v_div_scale_f32 v11, vcc, 1.0, v8, 1.0
	v_mul_f32_e32 v12, v11, v10
	v_fma_f32 v13, -v5, v12, v11
	v_fmac_f32_e32 v12, v13, v10
	v_fma_f32 v5, -v5, v12, v11
	v_div_fmas_f32 v5, v5, v10, v12
	v_div_fixup_f32 v8, v5, v8, 1.0
	v_lshlrev_b32_e32 v12, 16, v153
	v_and_b32_e32 v13, 0xffff0000, v153
	v_pk_mul_f32 v[10:11], v[8:9], v[6:7]
	v_pk_fma_f32 v[6:7], v[8:9], v[6:7], v[12:13]
	s_nop 0
	v_cndmask_b32_e64 v5, v7, v11, s[0:1]
	v_cndmask_b32_e64 v6, v6, v10, s[0:1]
	v_cvt_pk_bf16_f32 v153, v6, v5
	v_lshlrev_b32_e32 v6, 16, v4
	v_and_b32_e32 v7, 0xffff0000, v4
	v_mul_f32_e32 v4, v236, v24
	v_mul_f32_e32 v5, v236, v25
	v_exp_f32_e32 v4, v4
	v_exp_f32_e32 v5, v5
	s_nop 0
	v_pk_add_f32 v[4:5], v[4:5], 1.0 op_sel_hi:[1,0]
	s_nop 0
	v_div_scale_f32 v8, s[34:35], v5, v5, 1.0
	v_rcp_f32_e32 v9, v8
	s_nop 0
	v_fma_f32 v10, -v8, v9, 1.0
	v_fmac_f32_e32 v9, v10, v9
	v_div_scale_f32 v10, vcc, 1.0, v5, 1.0
	v_mul_f32_e32 v11, v10, v9
	v_fma_f32 v12, -v8, v11, v10
	v_fmac_f32_e32 v11, v12, v9
	v_fma_f32 v8, -v8, v11, v10
	v_div_fmas_f32 v8, v8, v9, v11
	v_div_fixup_f32 v5, v8, v5, 1.0
; DI int get_tid() { int t = threadIdx.x; asm volatile("" : "+v"(t)); return t; }
; template <int ROWS>
; DI void epi_flush(char* lds, u16* __restrict__ dst, size_t ld) {
;   const int tid = get_tid();
;   const int r0 = tid >> 5, ch = tid & 31;
;   __syncthreads();
; #pragma unroll 4
;   for (int r = r0; r < ROWS; r += 16) {
;     const u32x4 v = *(const u32x4*)(lds + r * EROW + ch * 16);
;     *(u32x4*)(dst + (size_t)r * ld + ch * 8) = v;
; __global__ void __launch_bounds__(512) mega(Params p) {
;     ...
;         __syncthreads();
; #pragma unroll
;         for (int fb = 0; fb < 4; ++fb)
; #pragma unroll
;           for (int jq = 0; jq < 4; ++jq)
;             *(uint2*)(lds + (wt * 32 + l32) * EROW + (wf * 128 + fb * 32 + 8 * jq + 4 * hh) * 2) = make_uint2(yp[fb][2 * jq], yp[fb][2 * jq + 1]);
;         epi_flush<128>(lds, (u16*)(ws + R_Y) + (size_t)tt * 128 * 1024 + ft * 256, 1024);
	v_div_scale_f32 v8, s[34:35], v4, v4, 1.0
	v_rcp_f32_e32 v9, v8
	s_nop 0
	v_fma_f32 v10, -v8, v9, 1.0
	v_fmac_f32_e32 v9, v10, v9
	v_div_scale_f32 v10, vcc, 1.0, v4, 1.0
	v_mul_f32_e32 v11, v10, v9
	v_fma_f32 v12, -v8, v11, v10
	v_fmac_f32_e32 v11, v12, v9
	v_fma_f32 v8, -v8, v11, v10
	v_div_fmas_f32 v8, v8, v9, v11
	v_div_fixup_f32 v4, v8, v4, 1.0
	v_lshlrev_b32_e32 v10, 16, v150
	v_and_b32_e32 v11, 0xffff0000, v150
	v_pk_mul_f32 v[8:9], v[4:5], v[6:7]
	v_pk_fma_f32 v[4:5], v[4:5], v[6:7], v[10:11]
	s_nop 0
	v_cndmask_b32_e64 v5, v5, v9, s[0:1]
	v_cndmask_b32_e64 v4, v4, v8, s[0:1]
	v_cvt_pk_bf16_f32 v150, v4, v5
	v_lshlrev_b32_e32 v4, 16, v3
	v_and_b32_e32 v5, 0xffff0000, v3
	v_mul_f32_e32 v3, v236, v26
	v_exp_f32_e32 v6, v3
	v_mul_f32_e32 v3, v236, v27
	v_exp_f32_e32 v7, v3
	s_nop 0
	v_pk_add_f32 v[6:7], v[6:7], 1.0 op_sel_hi:[1,0]
	s_nop 0
	v_div_scale_f32 v3, s[34:35], v7, v7, 1.0
	v_rcp_f32_e32 v8, v3
	s_nop 0
	v_fma_f32 v9, -v3, v8, 1.0
	v_fmac_f32_e32 v8, v9, v8
	v_div_scale_f32 v9, vcc, 1.0, v7, 1.0
	v_mul_f32_e32 v10, v9, v8
	v_fma_f32 v11, -v3, v10, v9
	v_fmac_f32_e32 v10, v11, v8
	v_fma_f32 v3, -v3, v10, v9
	v_div_fmas_f32 v3, v3, v8, v10
	v_div_fixup_f32 v7, v3, v7, 1.0
	v_div_scale_f32 v3, s[34:35], v6, v6, 1.0
	v_rcp_f32_e32 v8, v3
	s_nop 0
	v_fma_f32 v9, -v3, v8, 1.0
	v_fmac_f32_e32 v8, v9, v8
	v_div_scale_f32 v9, vcc, 1.0, v6, 1.0
	v_mul_f32_e32 v10, v9, v8
	v_fma_f32 v11, -v3, v10, v9
	v_fmac_f32_e32 v10, v11, v8
	v_fma_f32 v3, -v3, v10, v9
	v_div_fmas_f32 v3, v3, v8, v10
	v_div_fixup_f32 v6, v3, v6, 1.0
	v_lshlrev_b32_e32 v10, 16, v151
	v_and_b32_e32 v11, 0xffff0000, v151
	v_pk_mul_f32 v[8:9], v[6:7], v[4:5]
	v_pk_fma_f32 v[4:5], v[6:7], v[4:5], v[10:11]
	s_nop 0
	v_cndmask_b32_e64 v3, v5, v9, s[0:1]
	v_cndmask_b32_e64 v4, v4, v8, s[0:1]
	v_cvt_pk_bf16_f32 v151, v4, v3
	v_lshlrev_b32_e32 v4, 16, v2
	v_and_b32_e32 v5, 0xffff0000, v2
	v_mul_f32_e32 v2, v236, v28
	v_mul_f32_e32 v3, v236, v29
	v_exp_f32_e32 v2, v2
	v_exp_f32_e32 v3, v3
	s_nop 0
	v_pk_add_f32 v[2:3], v[2:3], 1.0 op_sel_hi:[1,0]
	s_nop 0
	v_div_scale_f32 v6, s[34:35], v3, v3, 1.0
	v_rcp_f32_e32 v7, v6
	s_nop 0
	v_fma_f32 v8, -v6, v7, 1.0
	v_fmac_f32_e32 v7, v8, v7
	v_div_scale_f32 v8, vcc, 1.0, v3, 1.0
	v_mul_f32_e32 v9, v8, v7
	v_fma_f32 v10, -v6, v9, v8
	v_fmac_f32_e32 v9, v10, v7
	v_fma_f32 v6, -v6, v9, v8
	v_div_fmas_f32 v6, v6, v7, v9
	v_div_fixup_f32 v3, v6, v3, 1.0
	v_div_scale_f32 v6, s[34:35], v2, v2, 1.0
	v_rcp_f32_e32 v7, v6
	s_nop 0
	v_fma_f32 v8, -v6, v7, 1.0
	v_fmac_f32_e32 v7, v8, v7
	v_div_scale_f32 v8, vcc, 1.0, v2, 1.0
	v_mul_f32_e32 v9, v8, v7
	v_fma_f32 v10, -v6, v9, v8
	v_fmac_f32_e32 v9, v10, v7
	v_fma_f32 v6, -v6, v9, v8
	v_div_fmas_f32 v6, v6, v7, v9
	v_div_fixup_f32 v2, v6, v2, 1.0
	v_lshlrev_b32_e32 v8, 16, v148
	v_and_b32_e32 v9, 0xffff0000, v148
	v_pk_mul_f32 v[6:7], v[2:3], v[4:5]
	v_pk_fma_f32 v[2:3], v[2:3], v[4:5], v[8:9]
	s_nop 0
	v_cndmask_b32_e64 v3, v3, v7, s[0:1]
	v_cndmask_b32_e64 v2, v2, v6, s[0:1]
	v_cvt_pk_bf16_f32 v148, v2, v3
	v_lshlrev_b32_e32 v2, 16, v0
	v_and_b32_e32 v3, 0xffff0000, v0
	v_mul_f32_e32 v0, v236, v30
	v_exp_f32_e32 v4, v0
	v_mul_f32_e32 v0, v236, v31
	v_exp_f32_e32 v5, v0
	s_nop 0
	v_pk_add_f32 v[4:5], v[4:5], 1.0 op_sel_hi:[1,0]
	s_nop 0
	v_div_scale_f32 v0, s[34:35], v5, v5, 1.0
	v_rcp_f32_e32 v6, v0
	s_nop 0
	v_fma_f32 v7, -v0, v6, 1.0
	v_fmac_f32_e32 v6, v7, v6
	v_div_scale_f32 v7, vcc, 1.0, v5, 1.0
	v_mul_f32_e32 v8, v7, v6
	v_fma_f32 v9, -v0, v8, v7
	v_fmac_f32_e32 v8, v9, v6
	v_fma_f32 v0, -v0, v8, v7
	v_div_fmas_f32 v0, v0, v6, v8
	v_div_fixup_f32 v5, v0, v5, 1.0
	v_div_scale_f32 v0, s[34:35], v4, v4, 1.0
	v_rcp_f32_e32 v6, v0
	s_nop 0
	v_fma_f32 v7, -v0, v6, 1.0
	v_fmac_f32_e32 v6, v7, v6
	v_div_scale_f32 v7, vcc, 1.0, v4, 1.0
	v_mul_f32_e32 v8, v7, v6
	v_fma_f32 v9, -v0, v8, v7
	v_fmac_f32_e32 v8, v9, v6
	v_fma_f32 v0, -v0, v8, v7
	v_div_fmas_f32 v0, v0, v6, v8
	v_div_fixup_f32 v4, v0, v4, 1.0
	v_lshlrev_b32_e32 v8, 16, v149
	v_and_b32_e32 v9, 0xffff0000, v149
	v_pk_mul_f32 v[6:7], v[4:5], v[2:3]
	v_pk_fma_f32 v[2:3], v[4:5], v[2:3], v[8:9]
	s_nop 0
	v_cndmask_b32_e64 v0, v3, v7, s[0:1]
	v_cndmask_b32_e64 v2, v2, v6, s[0:1]
	v_cvt_pk_bf16_f32 v149, v2, v0
	s_cbranch_scc0 .LBB0_25
	v_mov_b32_e32 v6, v145
	s_waitcnt vmcnt(0)
	s_barrier
	ds_write2_b64 v235, v[166:167], v[168:169] offset1:2
	ds_write2_b64 v235, v[170:171], v[172:173] offset0:4 offset1:6
	ds_write2_b64 v235, v[174:175], v[176:177] offset0:8 offset1:10
	ds_write2_b64 v235, v[178:179], v[164:165] offset0:12 offset1:14
	ds_write2_b64 v235, v[162:163], v[160:161] offset0:16 offset1:18
	ds_write2_b64 v235, v[158:159], v[156:157] offset0:20 offset1:22
	ds_write2_b64 v235, v[154:155], v[152:153] offset0:24 offset1:26
	ds_write2_b64 v235, v[150:151], v[148:149] offset0:28 offset1:30
	s_waitcnt lgkmcnt(0)
	v_ashrrev_i32_e32 v2, 5, v6
	v_cmp_gt_i32_e32 vcc, s70, v2
	s_barrier
	s_and_saveexec_b64 s[0:1], vcc
	s_cbranch_execz .LBB0_23
	v_max_i32_e32 v0, 0x70, v2
	v_sub_u32_e32 v0, v0, v2
	v_add_u32_e32 v0, 15, v0
	v_and_b32_e32 v4, 31, v6
	v_and_b32_e32 v3, 48, v0
	s_and_b32 s33, s52, 0xe0
	v_lshlrev_b32_e32 v12, 4, v4
	v_cmp_ne_u32_e32 vcc, 48, v3
	s_and_saveexec_b64 s[8:9], vcc
	s_cbranch_execz .LBB0_55
	v_lshrrev_b32_e32 v3, 4, v0
	s_add_i32 s34, s33, s57
	v_add_u32_e32 v3, 1, v3
	s_add_i32 s34, s34, s58
	v_and_b32_e32 v7, 3, v3
	s_ashr_i32 s35, s34, 31
	v_ashrrev_i32_e32 v3, 31, v2
	s_lshl_b64 s[34:35], s[34:35], 18
	v_lshlrev_b64 v[8:9], 11, v[2:3]
	v_lshl_add_u64 v[8:9], s[34:35], 0, v[8:9]
	s_lshl_b64 s[34:35], s[54:55], 1
	s_add_u32 s34, s10, s34
	v_lshl_or_b32 v8, v4, 4, v8
	s_addc_u32 s35, s11, s35
	v_lshl_add_u64 v[4:5], s[34:35], 0, v[8:9]
	s_movk_i32 s34, 0x210
	v_mul_lo_u32 v3, v2, s34
	v_add3_u32 v3, v3, v12, 0
	v_sub_u32_e32 v7, 0, v7
	s_mov_b64 s[34:35], 0
	s_mov_b64 s[64:65], 0x8000
